# LDS-DMA mainloop also for the merge K=1024 gate GEMM (dropped tail MFMAs replaced by s_nop to keep trans spacing)
# speedup vs baseline: 1.0495x; 1.0194x over previous
.LBB0_463:
	s_ashr_i32 s0, s12, 3
	s_mul_hi_i32 s1, s0, 0x66666667
	s_lshr_b32 s13, s1, 31
	s_ashr_i32 s1, s1, 4
	s_add_i32 s1, s1, s13
	s_mul_i32 s13, s1, 40
	s_sub_i32 s0, s0, s13
	s_and_b32 s22, s0, 7
	s_mul_i32 s1, s1, 5
	s_ashr_i32 s0, s0, 3
	s_lshl_b32 s13, s12, 3
	s_add_i32 s1, s1, s0
	s_and_b32 s13, s13, 56
	s_lshl_b32 s0, s1, 7
	s_or_b32 s13, s22, s13
	s_add_i32 s22, s0, 0x100
	s_cmp_lt_i32 s1, 6
	s_cselect_b32 s0, s0, s22
	s_lshl_b32 s1, s13, 18
	v_readlane_b32 s22, v251, 31
	v_mov_b32_e32 v36, v178
	v_readlane_b32 s23, v251, 32
	s_add_u32 s22, s22, s1
	s_addc_u32 s23, s23, 0
	v_ashrrev_i32_e32 v34, 3, v36
	s_ashr_i32 s1, s0, 31
	v_lshlrev_b32_e32 v0, 3, v36
	v_ashrrev_i32_e32 v35, 31, v34
	s_lshl_b64 s[24:25], s[0:1], 11
	v_and_b32_e32 v37, 56, v0
	v_lshlrev_b64 v[2:3], 11, v[34:35]
	s_add_u32 s24, s92, s24
	v_lshl_add_u64 v[4:5], s[22:23], 0, v[2:3]
	v_lshlrev_b32_e32 v0, 1, v37
	s_addc_u32 s25, s93, s25
	v_lshl_add_u64 v[68:69], v[4:5], 0, v[0:1]
	v_lshl_add_u64 v[2:3], s[24:25], 0, v[2:3]
	v_lshl_add_u64 v[70:71], v[2:3], 0, v[0:1]
	v_and_b32_e32 v0, 7, v36
	v_bfe_u32 v66, v36, 4, 3
	v_xor_b32_e32 v66, v66, v0
	v_sub_u32_e32 v66, v66, v0
	v_lshlrev_b32_e32 v66, 4, v66
	v_ashrrev_i32_e32 v67, 31, v66
	v_lshl_add_u64 v[68:69], v[68:69], 0, v[66:67]
	v_lshl_add_u64 v[70:71], v[70:71], 0, v[66:67]
	v_add_co_u32_e32 v72, vcc, s73, v68
	s_nop 1
	v_addc_co_u32_e32 v73, vcc, 0, v69, vcc
	v_add_co_u32_e32 v74, vcc, s73, v70
	s_nop 1
	v_addc_co_u32_e32 v75, vcc, 0, v71, vcc
	v_add_co_u32_e32 v76, vcc, s52, v68
	s_nop 1
	v_addc_co_u32_e32 v77, vcc, 0, v69, vcc
	v_add_co_u32_e32 v78, vcc, s52, v70
	s_nop 1
	v_addc_co_u32_e32 v79, vcc, 0, v71, vcc
	v_add_co_u32_e32 v80, vcc, s53, v68
	s_nop 1
	v_addc_co_u32_e32 v81, vcc, 0, v69, vcc
	v_add_co_u32_e32 v82, vcc, s53, v70
	s_nop 1
	v_addc_co_u32_e32 v83, vcc, 0, v71, vcc
	v_and_b32_e32 v0, 31, v36
	v_bfe_u32 v66, v36, 5, 1
	v_bfe_u32 v67, v36, 1, 3
	v_xor_b32_e32 v66, v66, v67
	v_lshlrev_b32_e32 v66, 4, v66
	v_lshl_add_u32 v66, v0, 7, v66
	v_bfe_u32 v67, v36, 7, 1
	v_lshl_add_u32 v86, v67, 13, v66
	v_bfe_u32 v67, v36, 6, 1
	v_lshl_add_u32 v90, v67, 13, v66
	v_add_u32_e32 v90, 0x4000, v90
	v_xor_b32_e32 v87, 32, v86
	v_xor_b32_e32 v91, 32, v90
	v_xor_b32_e32 v88, 64, v86
	v_xor_b32_e32 v92, 64, v90
	v_xor_b32_e32 v89, 96, v86
	v_xor_b32_e32 v93, 96, v90
	v_lshrrev_b32_e32 v66, 6, v36
	v_lshlrev_b32_e32 v66, 10, v66
	s_nop 1
	v_readfirstlane_b32 s14, v66
	s_movk_i32 s1, 0x14c0
	s_mov_b32 s27, 0
	s_lshl_b32 s13, s13, 7
	s_add_u32 m0, s14, 0x800
	s_nop 0
	global_load_lds_dwordx4 v[68:69], off
	s_add_u32 m0, s14, 0x1800
	s_nop 0
	global_load_lds_dwordx4 v[72:73], off
	s_add_u32 m0, s14, 0x2800
	s_nop 0
	global_load_lds_dwordx4 v[76:77], off
	s_add_u32 m0, s14, 0x3800
	s_nop 0
	global_load_lds_dwordx4 v[80:81], off
	s_add_u32 m0, s14, 0x4800
	s_nop 0
	global_load_lds_dwordx4 v[70:71], off
	s_add_u32 m0, s14, 0x5800
	s_nop 0
	global_load_lds_dwordx4 v[74:75], off
	s_add_u32 m0, s14, 0x6800
	s_nop 0
	global_load_lds_dwordx4 v[78:79], off
	s_add_u32 m0, s14, 0x7800
	s_nop 0
	global_load_lds_dwordx4 v[82:83], off
	s_add_u32 m0, s14, 0x8780
	s_nop 0
	global_load_lds_dwordx4 v[68:69], off offset:128
	s_add_u32 m0, s14, 0x9780
	s_nop 0
	global_load_lds_dwordx4 v[72:73], off offset:128
	s_add_u32 m0, s14, 0xa780
	s_nop 0
	global_load_lds_dwordx4 v[76:77], off offset:128
	s_add_u32 m0, s14, 0xb780
	s_nop 0
	global_load_lds_dwordx4 v[80:81], off offset:128
	s_add_u32 m0, s14, 0xc780
	s_nop 0
	global_load_lds_dwordx4 v[70:71], off offset:128
	s_add_u32 m0, s14, 0xd780
	s_nop 0
	global_load_lds_dwordx4 v[74:75], off offset:128
	s_add_u32 m0, s14, 0xe780
	s_nop 0
	global_load_lds_dwordx4 v[78:79], off offset:128
	s_add_u32 m0, s14, 0xf780
	s_nop 0
	global_load_lds_dwordx4 v[82:83], off offset:128
	s_waitcnt vmcnt(8)
	s_barrier
	ds_read_b128 v[94:97], v86 offset:2048
	ds_read_b128 v[98:101], v86 offset:6144
	ds_read_b128 v[102:105], v90 offset:2048
	ds_read_b128 v[106:109], v90 offset:6144
	ds_read_b128 v[110:113], v87 offset:2048
	ds_read_b128 v[114:117], v87 offset:6144
	ds_read_b128 v[118:121], v91 offset:2048
	ds_read_b128 v[122:125], v91 offset:6144
	ds_read_b128 v[126:129], v88 offset:2048
	ds_read_b128 v[130:133], v88 offset:6144
	ds_read_b128 v[134:137], v92 offset:2048
	ds_read_b128 v[138:141], v92 offset:6144
	ds_read_b128 v[142:145], v89 offset:2048
	ds_read_b128 v[146:149], v89 offset:6144
	ds_read_b128 v[150:153], v93 offset:2048
	ds_read_b128 v[154:157], v93 offset:6144
	s_waitcnt lgkmcnt(0)
	s_barrier
	s_add_u32 m0, s14, 0x700
	s_nop 0
	global_load_lds_dwordx4 v[68:69], off offset:256
	s_add_u32 m0, s14, 0x1700
	s_nop 0
	global_load_lds_dwordx4 v[72:73], off offset:256
	s_add_u32 m0, s14, 0x2700
	s_nop 0
	global_load_lds_dwordx4 v[76:77], off offset:256
	s_add_u32 m0, s14, 0x3700
	s_nop 0
	global_load_lds_dwordx4 v[80:81], off offset:256
	s_add_u32 m0, s14, 0x4700
	s_nop 0
	global_load_lds_dwordx4 v[70:71], off offset:256
	s_add_u32 m0, s14, 0x5700
	s_nop 0
	global_load_lds_dwordx4 v[74:75], off offset:256
	s_add_u32 m0, s14, 0x6700
	s_nop 0
	global_load_lds_dwordx4 v[78:79], off offset:256
	s_add_u32 m0, s14, 0x7700
	s_nop 0
	global_load_lds_dwordx4 v[82:83], off offset:256
	v_mfma_f32_32x32x16_bf16 v[34:49], v[94:97], v[102:105], 0
	v_mfma_f32_32x32x16_bf16 v[50:65], v[94:97], v[106:109], 0
	v_mfma_f32_32x32x16_bf16 v[2:17], v[98:101], v[102:105], 0
	v_mfma_f32_32x32x16_bf16 v[18:33], v[98:101], v[106:109], 0
	s_waitcnt vmcnt(8)
	s_barrier
	ds_read_b128 v[94:97], v86 offset:34816
	ds_read_b128 v[98:101], v86 offset:38912
	ds_read_b128 v[102:105], v90 offset:34816
	ds_read_b128 v[106:109], v90 offset:38912
	v_mfma_f32_32x32x16_bf16 v[34:49], v[110:113], v[118:121], v[34:49]
	v_mfma_f32_32x32x16_bf16 v[50:65], v[110:113], v[122:125], v[50:65]
	v_mfma_f32_32x32x16_bf16 v[2:17], v[114:117], v[118:121], v[2:17]
	v_mfma_f32_32x32x16_bf16 v[18:33], v[114:117], v[122:125], v[18:33]
	ds_read_b128 v[110:113], v87 offset:34816
	ds_read_b128 v[114:117], v87 offset:38912
	ds_read_b128 v[118:121], v91 offset:34816
	ds_read_b128 v[122:125], v91 offset:38912
	v_mfma_f32_32x32x16_bf16 v[34:49], v[126:129], v[134:137], v[34:49]
	v_mfma_f32_32x32x16_bf16 v[50:65], v[126:129], v[138:141], v[50:65]
	v_mfma_f32_32x32x16_bf16 v[2:17], v[130:133], v[134:137], v[2:17]
	v_mfma_f32_32x32x16_bf16 v[18:33], v[130:133], v[138:141], v[18:33]
	ds_read_b128 v[126:129], v88 offset:34816
	ds_read_b128 v[130:133], v88 offset:38912
	ds_read_b128 v[134:137], v92 offset:34816
	ds_read_b128 v[138:141], v92 offset:38912
	v_mfma_f32_32x32x16_bf16 v[34:49], v[142:145], v[150:153], v[34:49]
	v_mfma_f32_32x32x16_bf16 v[50:65], v[142:145], v[154:157], v[50:65]
	v_mfma_f32_32x32x16_bf16 v[2:17], v[146:149], v[150:153], v[2:17]
	v_mfma_f32_32x32x16_bf16 v[18:33], v[146:149], v[154:157], v[18:33]
	ds_read_b128 v[142:145], v89 offset:34816
	ds_read_b128 v[146:149], v89 offset:38912
	ds_read_b128 v[150:153], v93 offset:34816
	ds_read_b128 v[154:157], v93 offset:38912
	s_waitcnt lgkmcnt(0)
	s_barrier
	s_add_u32 m0, s14, 0x8680
	s_nop 0
	global_load_lds_dwordx4 v[68:69], off offset:384
	s_add_u32 m0, s14, 0x9680
	s_nop 0
	global_load_lds_dwordx4 v[72:73], off offset:384
	s_add_u32 m0, s14, 0xa680
	s_nop 0
	global_load_lds_dwordx4 v[76:77], off offset:384
	s_add_u32 m0, s14, 0xb680
	s_nop 0
	global_load_lds_dwordx4 v[80:81], off offset:384
	s_add_u32 m0, s14, 0xc680
	s_nop 0
	global_load_lds_dwordx4 v[70:71], off offset:384
	s_add_u32 m0, s14, 0xd680
	s_nop 0
	global_load_lds_dwordx4 v[74:75], off offset:384
	s_add_u32 m0, s14, 0xe680
	s_nop 0
	global_load_lds_dwordx4 v[78:79], off offset:384
	s_add_u32 m0, s14, 0xf680
	s_nop 0
	global_load_lds_dwordx4 v[82:83], off offset:384
	v_mfma_f32_32x32x16_bf16 v[34:49], v[94:97], v[102:105], v[34:49]
	v_mfma_f32_32x32x16_bf16 v[50:65], v[94:97], v[106:109], v[50:65]
	v_mfma_f32_32x32x16_bf16 v[2:17], v[98:101], v[102:105], v[2:17]
	v_mfma_f32_32x32x16_bf16 v[18:33], v[98:101], v[106:109], v[18:33]
	s_waitcnt vmcnt(8)
	s_barrier
	ds_read_b128 v[94:97], v86 offset:2048
	ds_read_b128 v[98:101], v86 offset:6144
	ds_read_b128 v[102:105], v90 offset:2048
	ds_read_b128 v[106:109], v90 offset:6144
	v_mfma_f32_32x32x16_bf16 v[34:49], v[110:113], v[118:121], v[34:49]
	v_mfma_f32_32x32x16_bf16 v[50:65], v[110:113], v[122:125], v[50:65]
	v_mfma_f32_32x32x16_bf16 v[2:17], v[114:117], v[118:121], v[2:17]
	v_mfma_f32_32x32x16_bf16 v[18:33], v[114:117], v[122:125], v[18:33]
	ds_read_b128 v[110:113], v87 offset:2048
	ds_read_b128 v[114:117], v87 offset:6144
	ds_read_b128 v[118:121], v91 offset:2048
	ds_read_b128 v[122:125], v91 offset:6144
	v_mfma_f32_32x32x16_bf16 v[34:49], v[126:129], v[134:137], v[34:49]
	v_mfma_f32_32x32x16_bf16 v[50:65], v[126:129], v[138:141], v[50:65]
	v_mfma_f32_32x32x16_bf16 v[2:17], v[130:133], v[134:137], v[2:17]
	v_mfma_f32_32x32x16_bf16 v[18:33], v[130:133], v[138:141], v[18:33]
	ds_read_b128 v[126:129], v88 offset:2048
	ds_read_b128 v[130:133], v88 offset:6144
	ds_read_b128 v[134:137], v92 offset:2048
	ds_read_b128 v[138:141], v92 offset:6144
	v_mfma_f32_32x32x16_bf16 v[34:49], v[142:145], v[150:153], v[34:49]
	v_mfma_f32_32x32x16_bf16 v[50:65], v[142:145], v[154:157], v[50:65]
	v_mfma_f32_32x32x16_bf16 v[2:17], v[146:149], v[150:153], v[2:17]
	v_mfma_f32_32x32x16_bf16 v[18:33], v[146:149], v[154:157], v[18:33]
	ds_read_b128 v[142:145], v89 offset:2048
	ds_read_b128 v[146:149], v89 offset:6144
	ds_read_b128 v[150:153], v93 offset:2048
	ds_read_b128 v[154:157], v93 offset:6144
	s_waitcnt lgkmcnt(0)
	s_barrier
	s_add_u32 m0, s14, 0x600
	s_nop 0
	global_load_lds_dwordx4 v[68:69], off offset:512
	s_add_u32 m0, s14, 0x1600
	s_nop 0
	global_load_lds_dwordx4 v[72:73], off offset:512
	s_add_u32 m0, s14, 0x2600
	s_nop 0
	global_load_lds_dwordx4 v[76:77], off offset:512
	s_add_u32 m0, s14, 0x3600
	s_nop 0
	global_load_lds_dwordx4 v[80:81], off offset:512
	s_add_u32 m0, s14, 0x4600
	s_nop 0
	global_load_lds_dwordx4 v[70:71], off offset:512
	s_add_u32 m0, s14, 0x5600
	s_nop 0
	global_load_lds_dwordx4 v[74:75], off offset:512
	s_add_u32 m0, s14, 0x6600
	s_nop 0
	global_load_lds_dwordx4 v[78:79], off offset:512
	s_add_u32 m0, s14, 0x7600
	s_nop 0
	global_load_lds_dwordx4 v[82:83], off offset:512
	v_mfma_f32_32x32x16_bf16 v[34:49], v[94:97], v[102:105], v[34:49]
	v_mfma_f32_32x32x16_bf16 v[50:65], v[94:97], v[106:109], v[50:65]
	v_mfma_f32_32x32x16_bf16 v[2:17], v[98:101], v[102:105], v[2:17]
	v_mfma_f32_32x32x16_bf16 v[18:33], v[98:101], v[106:109], v[18:33]
	s_waitcnt vmcnt(8)
	s_barrier
	ds_read_b128 v[94:97], v86 offset:34816
	ds_read_b128 v[98:101], v86 offset:38912
	ds_read_b128 v[102:105], v90 offset:34816
	ds_read_b128 v[106:109], v90 offset:38912
	v_mfma_f32_32x32x16_bf16 v[34:49], v[110:113], v[118:121], v[34:49]
	v_mfma_f32_32x32x16_bf16 v[50:65], v[110:113], v[122:125], v[50:65]
	v_mfma_f32_32x32x16_bf16 v[2:17], v[114:117], v[118:121], v[2:17]
	v_mfma_f32_32x32x16_bf16 v[18:33], v[114:117], v[122:125], v[18:33]
	ds_read_b128 v[110:113], v87 offset:34816
	ds_read_b128 v[114:117], v87 offset:38912
	ds_read_b128 v[118:121], v91 offset:34816
	ds_read_b128 v[122:125], v91 offset:38912
	v_mfma_f32_32x32x16_bf16 v[34:49], v[126:129], v[134:137], v[34:49]
	v_mfma_f32_32x32x16_bf16 v[50:65], v[126:129], v[138:141], v[50:65]
	v_mfma_f32_32x32x16_bf16 v[2:17], v[130:133], v[134:137], v[2:17]
	v_mfma_f32_32x32x16_bf16 v[18:33], v[130:133], v[138:141], v[18:33]
	ds_read_b128 v[126:129], v88 offset:34816
	ds_read_b128 v[130:133], v88 offset:38912
	ds_read_b128 v[134:137], v92 offset:34816
	ds_read_b128 v[138:141], v92 offset:38912
	v_mfma_f32_32x32x16_bf16 v[34:49], v[142:145], v[150:153], v[34:49]
	v_mfma_f32_32x32x16_bf16 v[50:65], v[142:145], v[154:157], v[50:65]
	v_mfma_f32_32x32x16_bf16 v[2:17], v[146:149], v[150:153], v[2:17]
	v_mfma_f32_32x32x16_bf16 v[18:33], v[146:149], v[154:157], v[18:33]
	ds_read_b128 v[142:145], v89 offset:34816
	ds_read_b128 v[146:149], v89 offset:38912
	ds_read_b128 v[150:153], v93 offset:34816
	ds_read_b128 v[154:157], v93 offset:38912
	s_waitcnt lgkmcnt(0)
	s_barrier
	s_add_u32 m0, s14, 0x8580
	s_nop 0
	global_load_lds_dwordx4 v[68:69], off offset:640
	s_add_u32 m0, s14, 0x9580
	s_nop 0
	global_load_lds_dwordx4 v[72:73], off offset:640
	s_add_u32 m0, s14, 0xa580
	s_nop 0
	global_load_lds_dwordx4 v[76:77], off offset:640
	s_add_u32 m0, s14, 0xb580
	s_nop 0
	global_load_lds_dwordx4 v[80:81], off offset:640
	s_add_u32 m0, s14, 0xc580
	s_nop 0
	global_load_lds_dwordx4 v[70:71], off offset:640
	s_add_u32 m0, s14, 0xd580
	s_nop 0
	global_load_lds_dwordx4 v[74:75], off offset:640
	s_add_u32 m0, s14, 0xe580
	s_nop 0
	global_load_lds_dwordx4 v[78:79], off offset:640
	s_add_u32 m0, s14, 0xf580
	s_nop 0
	global_load_lds_dwordx4 v[82:83], off offset:640
	v_mfma_f32_32x32x16_bf16 v[34:49], v[94:97], v[102:105], v[34:49]
	v_mfma_f32_32x32x16_bf16 v[50:65], v[94:97], v[106:109], v[50:65]
	v_mfma_f32_32x32x16_bf16 v[2:17], v[98:101], v[102:105], v[2:17]
	v_mfma_f32_32x32x16_bf16 v[18:33], v[98:101], v[106:109], v[18:33]
	s_waitcnt vmcnt(8)
	s_barrier
	ds_read_b128 v[94:97], v86 offset:2048
	ds_read_b128 v[98:101], v86 offset:6144
	ds_read_b128 v[102:105], v90 offset:2048
	ds_read_b128 v[106:109], v90 offset:6144
	v_mfma_f32_32x32x16_bf16 v[34:49], v[110:113], v[118:121], v[34:49]
	v_mfma_f32_32x32x16_bf16 v[50:65], v[110:113], v[122:125], v[50:65]
	v_mfma_f32_32x32x16_bf16 v[2:17], v[114:117], v[118:121], v[2:17]
	v_mfma_f32_32x32x16_bf16 v[18:33], v[114:117], v[122:125], v[18:33]
	ds_read_b128 v[110:113], v87 offset:2048
	ds_read_b128 v[114:117], v87 offset:6144
	ds_read_b128 v[118:121], v91 offset:2048
	ds_read_b128 v[122:125], v91 offset:6144
	v_mfma_f32_32x32x16_bf16 v[34:49], v[126:129], v[134:137], v[34:49]
	v_mfma_f32_32x32x16_bf16 v[50:65], v[126:129], v[138:141], v[50:65]
	v_mfma_f32_32x32x16_bf16 v[2:17], v[130:133], v[134:137], v[2:17]
	v_mfma_f32_32x32x16_bf16 v[18:33], v[130:133], v[138:141], v[18:33]
	ds_read_b128 v[126:129], v88 offset:2048
	ds_read_b128 v[130:133], v88 offset:6144
	ds_read_b128 v[134:137], v92 offset:2048
	ds_read_b128 v[138:141], v92 offset:6144
	v_mfma_f32_32x32x16_bf16 v[34:49], v[142:145], v[150:153], v[34:49]
	v_mfma_f32_32x32x16_bf16 v[50:65], v[142:145], v[154:157], v[50:65]
	v_mfma_f32_32x32x16_bf16 v[2:17], v[146:149], v[150:153], v[2:17]
	v_mfma_f32_32x32x16_bf16 v[18:33], v[146:149], v[154:157], v[18:33]
	ds_read_b128 v[142:145], v89 offset:2048
	ds_read_b128 v[146:149], v89 offset:6144
	ds_read_b128 v[150:153], v93 offset:2048
	ds_read_b128 v[154:157], v93 offset:6144
	s_waitcnt lgkmcnt(0)
	s_barrier
	s_add_u32 m0, s14, 0x500
	s_nop 0
	global_load_lds_dwordx4 v[68:69], off offset:768
	s_add_u32 m0, s14, 0x1500
	s_nop 0
	global_load_lds_dwordx4 v[72:73], off offset:768
	s_add_u32 m0, s14, 0x2500
	s_nop 0
	global_load_lds_dwordx4 v[76:77], off offset:768
	s_add_u32 m0, s14, 0x3500
	s_nop 0
	global_load_lds_dwordx4 v[80:81], off offset:768
	s_add_u32 m0, s14, 0x4500
	s_nop 0
	global_load_lds_dwordx4 v[70:71], off offset:768
	s_add_u32 m0, s14, 0x5500
	s_nop 0
	global_load_lds_dwordx4 v[74:75], off offset:768
	s_add_u32 m0, s14, 0x6500
	s_nop 0
	global_load_lds_dwordx4 v[78:79], off offset:768
	s_add_u32 m0, s14, 0x7500
	s_nop 0
	global_load_lds_dwordx4 v[82:83], off offset:768
	v_mfma_f32_32x32x16_bf16 v[34:49], v[94:97], v[102:105], v[34:49]
	v_mfma_f32_32x32x16_bf16 v[50:65], v[94:97], v[106:109], v[50:65]
	v_mfma_f32_32x32x16_bf16 v[2:17], v[98:101], v[102:105], v[2:17]
	v_mfma_f32_32x32x16_bf16 v[18:33], v[98:101], v[106:109], v[18:33]
	s_waitcnt vmcnt(8)
	s_barrier
	ds_read_b128 v[94:97], v86 offset:34816
	ds_read_b128 v[98:101], v86 offset:38912
	ds_read_b128 v[102:105], v90 offset:34816
	ds_read_b128 v[106:109], v90 offset:38912
	v_mfma_f32_32x32x16_bf16 v[34:49], v[110:113], v[118:121], v[34:49]
	v_mfma_f32_32x32x16_bf16 v[50:65], v[110:113], v[122:125], v[50:65]
	v_mfma_f32_32x32x16_bf16 v[2:17], v[114:117], v[118:121], v[2:17]
	v_mfma_f32_32x32x16_bf16 v[18:33], v[114:117], v[122:125], v[18:33]
	ds_read_b128 v[110:113], v87 offset:34816
	ds_read_b128 v[114:117], v87 offset:38912
	ds_read_b128 v[118:121], v91 offset:34816
	ds_read_b128 v[122:125], v91 offset:38912
	v_mfma_f32_32x32x16_bf16 v[34:49], v[126:129], v[134:137], v[34:49]
	v_mfma_f32_32x32x16_bf16 v[50:65], v[126:129], v[138:141], v[50:65]
	v_mfma_f32_32x32x16_bf16 v[2:17], v[130:133], v[134:137], v[2:17]
	v_mfma_f32_32x32x16_bf16 v[18:33], v[130:133], v[138:141], v[18:33]
	ds_read_b128 v[126:129], v88 offset:34816
	ds_read_b128 v[130:133], v88 offset:38912
	ds_read_b128 v[134:137], v92 offset:34816
	ds_read_b128 v[138:141], v92 offset:38912
	v_mfma_f32_32x32x16_bf16 v[34:49], v[142:145], v[150:153], v[34:49]
	v_mfma_f32_32x32x16_bf16 v[50:65], v[142:145], v[154:157], v[50:65]
	v_mfma_f32_32x32x16_bf16 v[2:17], v[146:149], v[150:153], v[2:17]
	v_mfma_f32_32x32x16_bf16 v[18:33], v[146:149], v[154:157], v[18:33]
	ds_read_b128 v[142:145], v89 offset:34816
	ds_read_b128 v[146:149], v89 offset:38912
	ds_read_b128 v[150:153], v93 offset:34816
	ds_read_b128 v[154:157], v93 offset:38912
	s_waitcnt lgkmcnt(0)
	s_barrier
	s_add_u32 m0, s14, 0x8480
	s_nop 0
	global_load_lds_dwordx4 v[68:69], off offset:896
	s_add_u32 m0, s14, 0x9480
	s_nop 0
	global_load_lds_dwordx4 v[72:73], off offset:896
	s_add_u32 m0, s14, 0xa480
	s_nop 0
	global_load_lds_dwordx4 v[76:77], off offset:896
	s_add_u32 m0, s14, 0xb480
	s_nop 0
	global_load_lds_dwordx4 v[80:81], off offset:896
	s_add_u32 m0, s14, 0xc480
	s_nop 0
	global_load_lds_dwordx4 v[70:71], off offset:896
	s_add_u32 m0, s14, 0xd480
	s_nop 0
	global_load_lds_dwordx4 v[74:75], off offset:896
	s_add_u32 m0, s14, 0xe480
	s_nop 0
	global_load_lds_dwordx4 v[78:79], off offset:896
	s_add_u32 m0, s14, 0xf480
	s_nop 0
	global_load_lds_dwordx4 v[82:83], off offset:896
	v_mfma_f32_32x32x16_bf16 v[34:49], v[94:97], v[102:105], v[34:49]
	v_mfma_f32_32x32x16_bf16 v[50:65], v[94:97], v[106:109], v[50:65]
	v_mfma_f32_32x32x16_bf16 v[2:17], v[98:101], v[102:105], v[2:17]
	v_mfma_f32_32x32x16_bf16 v[18:33], v[98:101], v[106:109], v[18:33]
	s_waitcnt vmcnt(8)
	s_barrier
	ds_read_b128 v[94:97], v86 offset:2048
	ds_read_b128 v[98:101], v86 offset:6144
	ds_read_b128 v[102:105], v90 offset:2048
	ds_read_b128 v[106:109], v90 offset:6144
	v_mfma_f32_32x32x16_bf16 v[34:49], v[110:113], v[118:121], v[34:49]
	v_mfma_f32_32x32x16_bf16 v[50:65], v[110:113], v[122:125], v[50:65]
	v_mfma_f32_32x32x16_bf16 v[2:17], v[114:117], v[118:121], v[2:17]
	v_mfma_f32_32x32x16_bf16 v[18:33], v[114:117], v[122:125], v[18:33]
	ds_read_b128 v[110:113], v87 offset:2048
	ds_read_b128 v[114:117], v87 offset:6144
	ds_read_b128 v[118:121], v91 offset:2048
	ds_read_b128 v[122:125], v91 offset:6144
	v_mfma_f32_32x32x16_bf16 v[34:49], v[126:129], v[134:137], v[34:49]
	v_mfma_f32_32x32x16_bf16 v[50:65], v[126:129], v[138:141], v[50:65]
	v_mfma_f32_32x32x16_bf16 v[2:17], v[130:133], v[134:137], v[2:17]
	v_mfma_f32_32x32x16_bf16 v[18:33], v[130:133], v[138:141], v[18:33]
	ds_read_b128 v[126:129], v88 offset:2048
	ds_read_b128 v[130:133], v88 offset:6144
	ds_read_b128 v[134:137], v92 offset:2048
	ds_read_b128 v[138:141], v92 offset:6144
	v_mfma_f32_32x32x16_bf16 v[34:49], v[142:145], v[150:153], v[34:49]
	v_mfma_f32_32x32x16_bf16 v[50:65], v[142:145], v[154:157], v[50:65]
	v_mfma_f32_32x32x16_bf16 v[2:17], v[146:149], v[150:153], v[2:17]
	v_mfma_f32_32x32x16_bf16 v[18:33], v[146:149], v[154:157], v[18:33]
	ds_read_b128 v[142:145], v89 offset:2048
	ds_read_b128 v[146:149], v89 offset:6144
	ds_read_b128 v[150:153], v93 offset:2048
	ds_read_b128 v[154:157], v93 offset:6144
	s_waitcnt lgkmcnt(0)
	s_barrier
	s_add_u32 m0, s14, 0x400
	s_nop 0
	global_load_lds_dwordx4 v[68:69], off offset:1024
	s_add_u32 m0, s14, 0x1400
	s_nop 0
	global_load_lds_dwordx4 v[72:73], off offset:1024
	s_add_u32 m0, s14, 0x2400
	s_nop 0
	global_load_lds_dwordx4 v[76:77], off offset:1024
	s_add_u32 m0, s14, 0x3400
	s_nop 0
	global_load_lds_dwordx4 v[80:81], off offset:1024
	s_add_u32 m0, s14, 0x4400
	s_nop 0
	global_load_lds_dwordx4 v[70:71], off offset:1024
	s_add_u32 m0, s14, 0x5400
	s_nop 0
	global_load_lds_dwordx4 v[74:75], off offset:1024
	s_add_u32 m0, s14, 0x6400
	s_nop 0
	global_load_lds_dwordx4 v[78:79], off offset:1024
	s_add_u32 m0, s14, 0x7400
	s_nop 0
	global_load_lds_dwordx4 v[82:83], off offset:1024
	v_mfma_f32_32x32x16_bf16 v[34:49], v[94:97], v[102:105], v[34:49]
	v_mfma_f32_32x32x16_bf16 v[50:65], v[94:97], v[106:109], v[50:65]
	v_mfma_f32_32x32x16_bf16 v[2:17], v[98:101], v[102:105], v[2:17]
	v_mfma_f32_32x32x16_bf16 v[18:33], v[98:101], v[106:109], v[18:33]
	s_waitcnt vmcnt(8)
	s_barrier
	ds_read_b128 v[94:97], v86 offset:34816
	ds_read_b128 v[98:101], v86 offset:38912
	ds_read_b128 v[102:105], v90 offset:34816
	ds_read_b128 v[106:109], v90 offset:38912
	v_mfma_f32_32x32x16_bf16 v[34:49], v[110:113], v[118:121], v[34:49]
	v_mfma_f32_32x32x16_bf16 v[50:65], v[110:113], v[122:125], v[50:65]
	v_mfma_f32_32x32x16_bf16 v[2:17], v[114:117], v[118:121], v[2:17]
	v_mfma_f32_32x32x16_bf16 v[18:33], v[114:117], v[122:125], v[18:33]
	ds_read_b128 v[110:113], v87 offset:34816
	ds_read_b128 v[114:117], v87 offset:38912
	ds_read_b128 v[118:121], v91 offset:34816
	ds_read_b128 v[122:125], v91 offset:38912
	v_mfma_f32_32x32x16_bf16 v[34:49], v[126:129], v[134:137], v[34:49]
	v_mfma_f32_32x32x16_bf16 v[50:65], v[126:129], v[138:141], v[50:65]
	v_mfma_f32_32x32x16_bf16 v[2:17], v[130:133], v[134:137], v[2:17]
	v_mfma_f32_32x32x16_bf16 v[18:33], v[130:133], v[138:141], v[18:33]
	ds_read_b128 v[126:129], v88 offset:34816
	ds_read_b128 v[130:133], v88 offset:38912
	ds_read_b128 v[134:137], v92 offset:34816
	ds_read_b128 v[138:141], v92 offset:38912
	v_mfma_f32_32x32x16_bf16 v[34:49], v[142:145], v[150:153], v[34:49]
	v_mfma_f32_32x32x16_bf16 v[50:65], v[142:145], v[154:157], v[50:65]
	v_mfma_f32_32x32x16_bf16 v[2:17], v[146:149], v[150:153], v[2:17]
	v_mfma_f32_32x32x16_bf16 v[18:33], v[146:149], v[154:157], v[18:33]
	ds_read_b128 v[142:145], v89 offset:34816
	ds_read_b128 v[146:149], v89 offset:38912
	ds_read_b128 v[150:153], v93 offset:34816
	ds_read_b128 v[154:157], v93 offset:38912
	s_waitcnt lgkmcnt(0)
	s_barrier
	s_add_u32 m0, s14, 0x8380
	s_nop 0
	global_load_lds_dwordx4 v[68:69], off offset:1152
	s_add_u32 m0, s14, 0x9380
	s_nop 0
	global_load_lds_dwordx4 v[72:73], off offset:1152
	s_add_u32 m0, s14, 0xa380
	s_nop 0
	global_load_lds_dwordx4 v[76:77], off offset:1152
	s_add_u32 m0, s14, 0xb380
	s_nop 0
	global_load_lds_dwordx4 v[80:81], off offset:1152
	s_add_u32 m0, s14, 0xc380
	s_nop 0
	global_load_lds_dwordx4 v[70:71], off offset:1152
	s_add_u32 m0, s14, 0xd380
	s_nop 0
	global_load_lds_dwordx4 v[74:75], off offset:1152
	s_add_u32 m0, s14, 0xe380
	s_nop 0
	global_load_lds_dwordx4 v[78:79], off offset:1152
	s_add_u32 m0, s14, 0xf380
	s_nop 0
	global_load_lds_dwordx4 v[82:83], off offset:1152
	v_mfma_f32_32x32x16_bf16 v[34:49], v[94:97], v[102:105], v[34:49]
	v_mfma_f32_32x32x16_bf16 v[50:65], v[94:97], v[106:109], v[50:65]
	v_mfma_f32_32x32x16_bf16 v[2:17], v[98:101], v[102:105], v[2:17]
	v_mfma_f32_32x32x16_bf16 v[18:33], v[98:101], v[106:109], v[18:33]
	s_waitcnt vmcnt(8)
	s_barrier
	ds_read_b128 v[94:97], v86 offset:2048
	ds_read_b128 v[98:101], v86 offset:6144
	ds_read_b128 v[102:105], v90 offset:2048
	ds_read_b128 v[106:109], v90 offset:6144
	v_mfma_f32_32x32x16_bf16 v[34:49], v[110:113], v[118:121], v[34:49]
	v_mfma_f32_32x32x16_bf16 v[50:65], v[110:113], v[122:125], v[50:65]
	v_mfma_f32_32x32x16_bf16 v[2:17], v[114:117], v[118:121], v[2:17]
	v_mfma_f32_32x32x16_bf16 v[18:33], v[114:117], v[122:125], v[18:33]
	ds_read_b128 v[110:113], v87 offset:2048
	ds_read_b128 v[114:117], v87 offset:6144
	ds_read_b128 v[118:121], v91 offset:2048
	ds_read_b128 v[122:125], v91 offset:6144
	v_mfma_f32_32x32x16_bf16 v[34:49], v[126:129], v[134:137], v[34:49]
	v_mfma_f32_32x32x16_bf16 v[50:65], v[126:129], v[138:141], v[50:65]
	v_mfma_f32_32x32x16_bf16 v[2:17], v[130:133], v[134:137], v[2:17]
	v_mfma_f32_32x32x16_bf16 v[18:33], v[130:133], v[138:141], v[18:33]
	ds_read_b128 v[126:129], v88 offset:2048
	ds_read_b128 v[130:133], v88 offset:6144
	ds_read_b128 v[134:137], v92 offset:2048
	ds_read_b128 v[138:141], v92 offset:6144
	v_mfma_f32_32x32x16_bf16 v[34:49], v[142:145], v[150:153], v[34:49]
	v_mfma_f32_32x32x16_bf16 v[50:65], v[142:145], v[154:157], v[50:65]
	v_mfma_f32_32x32x16_bf16 v[2:17], v[146:149], v[150:153], v[2:17]
	v_mfma_f32_32x32x16_bf16 v[18:33], v[146:149], v[154:157], v[18:33]
	ds_read_b128 v[142:145], v89 offset:2048
	ds_read_b128 v[146:149], v89 offset:6144
	ds_read_b128 v[150:153], v93 offset:2048
	ds_read_b128 v[154:157], v93 offset:6144
	s_waitcnt lgkmcnt(0)
	s_barrier
	s_add_u32 m0, s14, 0x300
	s_nop 0
	global_load_lds_dwordx4 v[68:69], off offset:1280
	s_add_u32 m0, s14, 0x1300
	s_nop 0
	global_load_lds_dwordx4 v[72:73], off offset:1280
	s_add_u32 m0, s14, 0x2300
	s_nop 0
	global_load_lds_dwordx4 v[76:77], off offset:1280
	s_add_u32 m0, s14, 0x3300
	s_nop 0
	global_load_lds_dwordx4 v[80:81], off offset:1280
	s_add_u32 m0, s14, 0x4300
	s_nop 0
	global_load_lds_dwordx4 v[70:71], off offset:1280
	s_add_u32 m0, s14, 0x5300
	s_nop 0
	global_load_lds_dwordx4 v[74:75], off offset:1280
	s_add_u32 m0, s14, 0x6300
	s_nop 0
	global_load_lds_dwordx4 v[78:79], off offset:1280
	s_add_u32 m0, s14, 0x7300
	s_nop 0
	global_load_lds_dwordx4 v[82:83], off offset:1280
	v_mfma_f32_32x32x16_bf16 v[34:49], v[94:97], v[102:105], v[34:49]
	v_mfma_f32_32x32x16_bf16 v[50:65], v[94:97], v[106:109], v[50:65]
	v_mfma_f32_32x32x16_bf16 v[2:17], v[98:101], v[102:105], v[2:17]
	v_mfma_f32_32x32x16_bf16 v[18:33], v[98:101], v[106:109], v[18:33]
	s_waitcnt vmcnt(8)
	s_barrier
	ds_read_b128 v[94:97], v86 offset:34816
	ds_read_b128 v[98:101], v86 offset:38912
	ds_read_b128 v[102:105], v90 offset:34816
	ds_read_b128 v[106:109], v90 offset:38912
	v_mfma_f32_32x32x16_bf16 v[34:49], v[110:113], v[118:121], v[34:49]
	v_mfma_f32_32x32x16_bf16 v[50:65], v[110:113], v[122:125], v[50:65]
	v_mfma_f32_32x32x16_bf16 v[2:17], v[114:117], v[118:121], v[2:17]
	v_mfma_f32_32x32x16_bf16 v[18:33], v[114:117], v[122:125], v[18:33]
	ds_read_b128 v[110:113], v87 offset:34816
	ds_read_b128 v[114:117], v87 offset:38912
	ds_read_b128 v[118:121], v91 offset:34816
	ds_read_b128 v[122:125], v91 offset:38912
	v_mfma_f32_32x32x16_bf16 v[34:49], v[126:129], v[134:137], v[34:49]
	v_mfma_f32_32x32x16_bf16 v[50:65], v[126:129], v[138:141], v[50:65]
	v_mfma_f32_32x32x16_bf16 v[2:17], v[130:133], v[134:137], v[2:17]
	v_mfma_f32_32x32x16_bf16 v[18:33], v[130:133], v[138:141], v[18:33]
	ds_read_b128 v[126:129], v88 offset:34816
	ds_read_b128 v[130:133], v88 offset:38912
	ds_read_b128 v[134:137], v92 offset:34816
	ds_read_b128 v[138:141], v92 offset:38912
	v_mfma_f32_32x32x16_bf16 v[34:49], v[142:145], v[150:153], v[34:49]
	v_mfma_f32_32x32x16_bf16 v[50:65], v[142:145], v[154:157], v[50:65]
	v_mfma_f32_32x32x16_bf16 v[2:17], v[146:149], v[150:153], v[2:17]
	v_mfma_f32_32x32x16_bf16 v[18:33], v[146:149], v[154:157], v[18:33]
	ds_read_b128 v[142:145], v89 offset:34816
	ds_read_b128 v[146:149], v89 offset:38912
	ds_read_b128 v[150:153], v93 offset:34816
	ds_read_b128 v[154:157], v93 offset:38912
	s_waitcnt lgkmcnt(0)
	s_barrier
	s_add_u32 m0, s14, 0x8280
	s_nop 0
	global_load_lds_dwordx4 v[68:69], off offset:1408
	s_add_u32 m0, s14, 0x9280
	s_nop 0
	global_load_lds_dwordx4 v[72:73], off offset:1408
	s_add_u32 m0, s14, 0xa280
	s_nop 0
	global_load_lds_dwordx4 v[76:77], off offset:1408
	s_add_u32 m0, s14, 0xb280
	s_nop 0
	global_load_lds_dwordx4 v[80:81], off offset:1408
	s_add_u32 m0, s14, 0xc280
	s_nop 0
	global_load_lds_dwordx4 v[70:71], off offset:1408
	s_add_u32 m0, s14, 0xd280
	s_nop 0
	global_load_lds_dwordx4 v[74:75], off offset:1408
	s_add_u32 m0, s14, 0xe280
	s_nop 0
	global_load_lds_dwordx4 v[78:79], off offset:1408
	s_add_u32 m0, s14, 0xf280
	s_nop 0
	global_load_lds_dwordx4 v[82:83], off offset:1408
	v_mfma_f32_32x32x16_bf16 v[34:49], v[94:97], v[102:105], v[34:49]
	v_mfma_f32_32x32x16_bf16 v[50:65], v[94:97], v[106:109], v[50:65]
	v_mfma_f32_32x32x16_bf16 v[2:17], v[98:101], v[102:105], v[2:17]
	v_mfma_f32_32x32x16_bf16 v[18:33], v[98:101], v[106:109], v[18:33]
	s_waitcnt vmcnt(8)
	s_barrier
	ds_read_b128 v[94:97], v86 offset:2048
	ds_read_b128 v[98:101], v86 offset:6144
	ds_read_b128 v[102:105], v90 offset:2048
	ds_read_b128 v[106:109], v90 offset:6144
	v_mfma_f32_32x32x16_bf16 v[34:49], v[110:113], v[118:121], v[34:49]
	v_mfma_f32_32x32x16_bf16 v[50:65], v[110:113], v[122:125], v[50:65]
	v_mfma_f32_32x32x16_bf16 v[2:17], v[114:117], v[118:121], v[2:17]
	v_mfma_f32_32x32x16_bf16 v[18:33], v[114:117], v[122:125], v[18:33]
	ds_read_b128 v[110:113], v87 offset:2048
	ds_read_b128 v[114:117], v87 offset:6144
	ds_read_b128 v[118:121], v91 offset:2048
	ds_read_b128 v[122:125], v91 offset:6144
	v_mfma_f32_32x32x16_bf16 v[34:49], v[126:129], v[134:137], v[34:49]
	v_mfma_f32_32x32x16_bf16 v[50:65], v[126:129], v[138:141], v[50:65]
	v_mfma_f32_32x32x16_bf16 v[2:17], v[130:133], v[134:137], v[2:17]
	v_mfma_f32_32x32x16_bf16 v[18:33], v[130:133], v[138:141], v[18:33]
	ds_read_b128 v[126:129], v88 offset:2048
	ds_read_b128 v[130:133], v88 offset:6144
	ds_read_b128 v[134:137], v92 offset:2048
	ds_read_b128 v[138:141], v92 offset:6144
	v_mfma_f32_32x32x16_bf16 v[34:49], v[142:145], v[150:153], v[34:49]
	v_mfma_f32_32x32x16_bf16 v[50:65], v[142:145], v[154:157], v[50:65]
	v_mfma_f32_32x32x16_bf16 v[2:17], v[146:149], v[150:153], v[2:17]
	v_mfma_f32_32x32x16_bf16 v[18:33], v[146:149], v[154:157], v[18:33]
	ds_read_b128 v[142:145], v89 offset:2048
	ds_read_b128 v[146:149], v89 offset:6144
	ds_read_b128 v[150:153], v93 offset:2048
	ds_read_b128 v[154:157], v93 offset:6144
	s_waitcnt lgkmcnt(0)
	s_barrier
	s_add_u32 m0, s14, 0x200
	s_nop 0
	global_load_lds_dwordx4 v[68:69], off offset:1536
	s_add_u32 m0, s14, 0x1200
	s_nop 0
	global_load_lds_dwordx4 v[72:73], off offset:1536
	s_add_u32 m0, s14, 0x2200
	s_nop 0
	global_load_lds_dwordx4 v[76:77], off offset:1536
	s_add_u32 m0, s14, 0x3200
	s_nop 0
	global_load_lds_dwordx4 v[80:81], off offset:1536
	s_add_u32 m0, s14, 0x4200
	s_nop 0
	global_load_lds_dwordx4 v[70:71], off offset:1536
	s_add_u32 m0, s14, 0x5200
	s_nop 0
	global_load_lds_dwordx4 v[74:75], off offset:1536
	s_add_u32 m0, s14, 0x6200
	s_nop 0
	global_load_lds_dwordx4 v[78:79], off offset:1536
	s_add_u32 m0, s14, 0x7200
	s_nop 0
	global_load_lds_dwordx4 v[82:83], off offset:1536
	v_mfma_f32_32x32x16_bf16 v[34:49], v[94:97], v[102:105], v[34:49]
	v_mfma_f32_32x32x16_bf16 v[50:65], v[94:97], v[106:109], v[50:65]
	v_mfma_f32_32x32x16_bf16 v[2:17], v[98:101], v[102:105], v[2:17]
	v_mfma_f32_32x32x16_bf16 v[18:33], v[98:101], v[106:109], v[18:33]
	s_waitcnt vmcnt(8)
	s_barrier
	ds_read_b128 v[94:97], v86 offset:34816
	ds_read_b128 v[98:101], v86 offset:38912
	ds_read_b128 v[102:105], v90 offset:34816
	ds_read_b128 v[106:109], v90 offset:38912
	v_mfma_f32_32x32x16_bf16 v[34:49], v[110:113], v[118:121], v[34:49]
	v_mfma_f32_32x32x16_bf16 v[50:65], v[110:113], v[122:125], v[50:65]
	v_mfma_f32_32x32x16_bf16 v[2:17], v[114:117], v[118:121], v[2:17]
	v_mfma_f32_32x32x16_bf16 v[18:33], v[114:117], v[122:125], v[18:33]
	ds_read_b128 v[110:113], v87 offset:34816
	ds_read_b128 v[114:117], v87 offset:38912
	ds_read_b128 v[118:121], v91 offset:34816
	ds_read_b128 v[122:125], v91 offset:38912
	v_mfma_f32_32x32x16_bf16 v[34:49], v[126:129], v[134:137], v[34:49]
	v_mfma_f32_32x32x16_bf16 v[50:65], v[126:129], v[138:141], v[50:65]
	v_mfma_f32_32x32x16_bf16 v[2:17], v[130:133], v[134:137], v[2:17]
	v_mfma_f32_32x32x16_bf16 v[18:33], v[130:133], v[138:141], v[18:33]
	ds_read_b128 v[126:129], v88 offset:34816
	ds_read_b128 v[130:133], v88 offset:38912
	ds_read_b128 v[134:137], v92 offset:34816
	ds_read_b128 v[138:141], v92 offset:38912
	v_mfma_f32_32x32x16_bf16 v[34:49], v[142:145], v[150:153], v[34:49]
	v_mfma_f32_32x32x16_bf16 v[50:65], v[142:145], v[154:157], v[50:65]
	v_mfma_f32_32x32x16_bf16 v[2:17], v[146:149], v[150:153], v[2:17]
	v_mfma_f32_32x32x16_bf16 v[18:33], v[146:149], v[154:157], v[18:33]
	ds_read_b128 v[142:145], v89 offset:34816
	ds_read_b128 v[146:149], v89 offset:38912
	ds_read_b128 v[150:153], v93 offset:34816
	ds_read_b128 v[154:157], v93 offset:38912
	s_waitcnt lgkmcnt(0)
	s_barrier
	s_add_u32 m0, s14, 0x8180
	s_nop 0
	global_load_lds_dwordx4 v[68:69], off offset:1664
	s_add_u32 m0, s14, 0x9180
	s_nop 0
	global_load_lds_dwordx4 v[72:73], off offset:1664
	s_add_u32 m0, s14, 0xa180
	s_nop 0
	global_load_lds_dwordx4 v[76:77], off offset:1664
	s_add_u32 m0, s14, 0xb180
	s_nop 0
	global_load_lds_dwordx4 v[80:81], off offset:1664
	s_add_u32 m0, s14, 0xc180
	s_nop 0
	global_load_lds_dwordx4 v[70:71], off offset:1664
	s_add_u32 m0, s14, 0xd180
	s_nop 0
	global_load_lds_dwordx4 v[74:75], off offset:1664
	s_add_u32 m0, s14, 0xe180
	s_nop 0
	global_load_lds_dwordx4 v[78:79], off offset:1664
	s_add_u32 m0, s14, 0xf180
	s_nop 0
	global_load_lds_dwordx4 v[82:83], off offset:1664
	v_mfma_f32_32x32x16_bf16 v[34:49], v[94:97], v[102:105], v[34:49]
	v_mfma_f32_32x32x16_bf16 v[50:65], v[94:97], v[106:109], v[50:65]
	v_mfma_f32_32x32x16_bf16 v[2:17], v[98:101], v[102:105], v[2:17]
	v_mfma_f32_32x32x16_bf16 v[18:33], v[98:101], v[106:109], v[18:33]
	s_waitcnt vmcnt(8)
	s_barrier
	ds_read_b128 v[94:97], v86 offset:2048
	ds_read_b128 v[98:101], v86 offset:6144
	ds_read_b128 v[102:105], v90 offset:2048
	ds_read_b128 v[106:109], v90 offset:6144
	v_mfma_f32_32x32x16_bf16 v[34:49], v[110:113], v[118:121], v[34:49]
	v_mfma_f32_32x32x16_bf16 v[50:65], v[110:113], v[122:125], v[50:65]
	v_mfma_f32_32x32x16_bf16 v[2:17], v[114:117], v[118:121], v[2:17]
	v_mfma_f32_32x32x16_bf16 v[18:33], v[114:117], v[122:125], v[18:33]
	ds_read_b128 v[110:113], v87 offset:2048
	ds_read_b128 v[114:117], v87 offset:6144
	ds_read_b128 v[118:121], v91 offset:2048
	ds_read_b128 v[122:125], v91 offset:6144
	v_mfma_f32_32x32x16_bf16 v[34:49], v[126:129], v[134:137], v[34:49]
	v_mfma_f32_32x32x16_bf16 v[50:65], v[126:129], v[138:141], v[50:65]
	v_mfma_f32_32x32x16_bf16 v[2:17], v[130:133], v[134:137], v[2:17]
	v_mfma_f32_32x32x16_bf16 v[18:33], v[130:133], v[138:141], v[18:33]
	ds_read_b128 v[126:129], v88 offset:2048
	ds_read_b128 v[130:133], v88 offset:6144
	ds_read_b128 v[134:137], v92 offset:2048
	ds_read_b128 v[138:141], v92 offset:6144
	v_mfma_f32_32x32x16_bf16 v[34:49], v[142:145], v[150:153], v[34:49]
	v_mfma_f32_32x32x16_bf16 v[50:65], v[142:145], v[154:157], v[50:65]
	v_mfma_f32_32x32x16_bf16 v[2:17], v[146:149], v[150:153], v[2:17]
	v_mfma_f32_32x32x16_bf16 v[18:33], v[146:149], v[154:157], v[18:33]
	ds_read_b128 v[142:145], v89 offset:2048
	ds_read_b128 v[146:149], v89 offset:6144
	ds_read_b128 v[150:153], v93 offset:2048
	ds_read_b128 v[154:157], v93 offset:6144
	s_waitcnt lgkmcnt(0)
	s_barrier
	s_add_u32 m0, s14, 0x100
	s_nop 0
	global_load_lds_dwordx4 v[68:69], off offset:1792
	s_add_u32 m0, s14, 0x1100
	s_nop 0
	global_load_lds_dwordx4 v[72:73], off offset:1792
	s_add_u32 m0, s14, 0x2100
	s_nop 0
	global_load_lds_dwordx4 v[76:77], off offset:1792
	s_add_u32 m0, s14, 0x3100
	s_nop 0
	global_load_lds_dwordx4 v[80:81], off offset:1792
	s_add_u32 m0, s14, 0x4100
	s_nop 0
	global_load_lds_dwordx4 v[70:71], off offset:1792
	s_add_u32 m0, s14, 0x5100
	s_nop 0
	global_load_lds_dwordx4 v[74:75], off offset:1792
	s_add_u32 m0, s14, 0x6100
	s_nop 0
	global_load_lds_dwordx4 v[78:79], off offset:1792
	s_add_u32 m0, s14, 0x7100
	s_nop 0
	global_load_lds_dwordx4 v[82:83], off offset:1792
	v_mfma_f32_32x32x16_bf16 v[34:49], v[94:97], v[102:105], v[34:49]
	v_mfma_f32_32x32x16_bf16 v[50:65], v[94:97], v[106:109], v[50:65]
	v_mfma_f32_32x32x16_bf16 v[2:17], v[98:101], v[102:105], v[2:17]
	v_mfma_f32_32x32x16_bf16 v[18:33], v[98:101], v[106:109], v[18:33]
	s_waitcnt vmcnt(8)
	s_barrier
	ds_read_b128 v[94:97], v86 offset:34816
	ds_read_b128 v[98:101], v86 offset:38912
	ds_read_b128 v[102:105], v90 offset:34816
	ds_read_b128 v[106:109], v90 offset:38912
	v_mfma_f32_32x32x16_bf16 v[34:49], v[110:113], v[118:121], v[34:49]
	v_mfma_f32_32x32x16_bf16 v[50:65], v[110:113], v[122:125], v[50:65]
	v_mfma_f32_32x32x16_bf16 v[2:17], v[114:117], v[118:121], v[2:17]
	v_mfma_f32_32x32x16_bf16 v[18:33], v[114:117], v[122:125], v[18:33]
	ds_read_b128 v[110:113], v87 offset:34816
	ds_read_b128 v[114:117], v87 offset:38912
	ds_read_b128 v[118:121], v91 offset:34816
	ds_read_b128 v[122:125], v91 offset:38912
	v_mfma_f32_32x32x16_bf16 v[34:49], v[126:129], v[134:137], v[34:49]
	v_mfma_f32_32x32x16_bf16 v[50:65], v[126:129], v[138:141], v[50:65]
	v_mfma_f32_32x32x16_bf16 v[2:17], v[130:133], v[134:137], v[2:17]
	v_mfma_f32_32x32x16_bf16 v[18:33], v[130:133], v[138:141], v[18:33]
	ds_read_b128 v[126:129], v88 offset:34816
	ds_read_b128 v[130:133], v88 offset:38912
	ds_read_b128 v[134:137], v92 offset:34816
	ds_read_b128 v[138:141], v92 offset:38912
	v_mfma_f32_32x32x16_bf16 v[34:49], v[142:145], v[150:153], v[34:49]
	v_mfma_f32_32x32x16_bf16 v[50:65], v[142:145], v[154:157], v[50:65]
	v_mfma_f32_32x32x16_bf16 v[2:17], v[146:149], v[150:153], v[2:17]
	v_mfma_f32_32x32x16_bf16 v[18:33], v[146:149], v[154:157], v[18:33]
	ds_read_b128 v[142:145], v89 offset:34816
	ds_read_b128 v[146:149], v89 offset:38912
	ds_read_b128 v[150:153], v93 offset:34816
	ds_read_b128 v[154:157], v93 offset:38912
	s_waitcnt lgkmcnt(0)
	s_barrier
	s_add_u32 m0, s14, 0x8080
	s_nop 0
	global_load_lds_dwordx4 v[68:69], off offset:1920
	s_add_u32 m0, s14, 0x9080
	s_nop 0
	global_load_lds_dwordx4 v[72:73], off offset:1920
	s_add_u32 m0, s14, 0xa080
	s_nop 0
	global_load_lds_dwordx4 v[76:77], off offset:1920
	s_add_u32 m0, s14, 0xb080
	s_nop 0
	global_load_lds_dwordx4 v[80:81], off offset:1920
	s_add_u32 m0, s14, 0xc080
	s_nop 0
	global_load_lds_dwordx4 v[70:71], off offset:1920
	s_add_u32 m0, s14, 0xd080
	s_nop 0
	global_load_lds_dwordx4 v[74:75], off offset:1920
	s_add_u32 m0, s14, 0xe080
	s_nop 0
	global_load_lds_dwordx4 v[78:79], off offset:1920
	s_add_u32 m0, s14, 0xf080
	s_nop 0
	global_load_lds_dwordx4 v[82:83], off offset:1920
	v_mfma_f32_32x32x16_bf16 v[34:49], v[94:97], v[102:105], v[34:49]
	v_mfma_f32_32x32x16_bf16 v[50:65], v[94:97], v[106:109], v[50:65]
	v_mfma_f32_32x32x16_bf16 v[2:17], v[98:101], v[102:105], v[2:17]
	v_mfma_f32_32x32x16_bf16 v[18:33], v[98:101], v[106:109], v[18:33]
	s_waitcnt vmcnt(8)
	s_barrier
	ds_read_b128 v[94:97], v86 offset:2048
	ds_read_b128 v[98:101], v86 offset:6144
	ds_read_b128 v[102:105], v90 offset:2048
	ds_read_b128 v[106:109], v90 offset:6144
	v_mfma_f32_32x32x16_bf16 v[34:49], v[110:113], v[118:121], v[34:49]
	v_mfma_f32_32x32x16_bf16 v[50:65], v[110:113], v[122:125], v[50:65]
	v_mfma_f32_32x32x16_bf16 v[2:17], v[114:117], v[118:121], v[2:17]
	v_mfma_f32_32x32x16_bf16 v[18:33], v[114:117], v[122:125], v[18:33]
	ds_read_b128 v[110:113], v87 offset:2048
	ds_read_b128 v[114:117], v87 offset:6144
	ds_read_b128 v[118:121], v91 offset:2048
	ds_read_b128 v[122:125], v91 offset:6144
	v_mfma_f32_32x32x16_bf16 v[34:49], v[126:129], v[134:137], v[34:49]
	v_mfma_f32_32x32x16_bf16 v[50:65], v[126:129], v[138:141], v[50:65]
	v_mfma_f32_32x32x16_bf16 v[2:17], v[130:133], v[134:137], v[2:17]
	v_mfma_f32_32x32x16_bf16 v[18:33], v[130:133], v[138:141], v[18:33]
	ds_read_b128 v[126:129], v88 offset:2048
	ds_read_b128 v[130:133], v88 offset:6144
	ds_read_b128 v[134:137], v92 offset:2048
	ds_read_b128 v[138:141], v92 offset:6144
	v_mfma_f32_32x32x16_bf16 v[34:49], v[142:145], v[150:153], v[34:49]
	v_mfma_f32_32x32x16_bf16 v[50:65], v[142:145], v[154:157], v[50:65]
	v_mfma_f32_32x32x16_bf16 v[2:17], v[146:149], v[150:153], v[2:17]
	v_mfma_f32_32x32x16_bf16 v[18:33], v[146:149], v[154:157], v[18:33]
	ds_read_b128 v[142:145], v89 offset:2048
	ds_read_b128 v[146:149], v89 offset:6144
	ds_read_b128 v[150:153], v93 offset:2048
	ds_read_b128 v[154:157], v93 offset:6144
	s_waitcnt lgkmcnt(0)
	v_mfma_f32_32x32x16_bf16 v[34:49], v[94:97], v[102:105], v[34:49]
	v_mfma_f32_32x32x16_bf16 v[50:65], v[94:97], v[106:109], v[50:65]
	v_mfma_f32_32x32x16_bf16 v[2:17], v[98:101], v[102:105], v[2:17]
	v_mfma_f32_32x32x16_bf16 v[18:33], v[98:101], v[106:109], v[18:33]
	s_waitcnt vmcnt(0)
	s_barrier
	ds_read_b128 v[94:97], v86 offset:34816
	ds_read_b128 v[98:101], v86 offset:38912
	ds_read_b128 v[102:105], v90 offset:34816
	ds_read_b128 v[106:109], v90 offset:38912
	v_mfma_f32_32x32x16_bf16 v[34:49], v[110:113], v[118:121], v[34:49]
	v_mfma_f32_32x32x16_bf16 v[50:65], v[110:113], v[122:125], v[50:65]
	v_mfma_f32_32x32x16_bf16 v[2:17], v[114:117], v[118:121], v[2:17]
	v_mfma_f32_32x32x16_bf16 v[18:33], v[114:117], v[122:125], v[18:33]
	ds_read_b128 v[110:113], v87 offset:34816
	ds_read_b128 v[114:117], v87 offset:38912
	ds_read_b128 v[118:121], v91 offset:34816
	ds_read_b128 v[122:125], v91 offset:38912
	v_mfma_f32_32x32x16_bf16 v[34:49], v[126:129], v[134:137], v[34:49]
	v_mfma_f32_32x32x16_bf16 v[50:65], v[126:129], v[138:141], v[50:65]
	v_mfma_f32_32x32x16_bf16 v[2:17], v[130:133], v[134:137], v[2:17]
	v_mfma_f32_32x32x16_bf16 v[18:33], v[130:133], v[138:141], v[18:33]
	ds_read_b128 v[126:129], v88 offset:34816
	ds_read_b128 v[130:133], v88 offset:38912
	ds_read_b128 v[134:137], v92 offset:34816
	ds_read_b128 v[138:141], v92 offset:38912
	v_mfma_f32_32x32x16_bf16 v[34:49], v[142:145], v[150:153], v[34:49]
	v_mfma_f32_32x32x16_bf16 v[50:65], v[142:145], v[154:157], v[50:65]
	v_mfma_f32_32x32x16_bf16 v[2:17], v[146:149], v[150:153], v[2:17]
	v_mfma_f32_32x32x16_bf16 v[18:33], v[146:149], v[154:157], v[18:33]
	ds_read_b128 v[142:145], v89 offset:34816
	ds_read_b128 v[146:149], v89 offset:38912
	ds_read_b128 v[150:153], v93 offset:34816
	ds_read_b128 v[154:157], v93 offset:38912
	s_waitcnt lgkmcnt(0)
	v_mfma_f32_32x32x16_bf16 v[34:49], v[94:97], v[102:105], v[34:49]
	v_mfma_f32_32x32x16_bf16 v[50:65], v[94:97], v[106:109], v[50:65]
	v_mfma_f32_32x32x16_bf16 v[2:17], v[98:101], v[102:105], v[2:17]
	v_mfma_f32_32x32x16_bf16 v[18:33], v[98:101], v[106:109], v[18:33]
	v_mfma_f32_32x32x16_bf16 v[34:49], v[110:113], v[118:121], v[34:49]
	v_mfma_f32_32x32x16_bf16 v[50:65], v[110:113], v[122:125], v[50:65]
	v_mfma_f32_32x32x16_bf16 v[2:17], v[114:117], v[118:121], v[2:17]
	v_mfma_f32_32x32x16_bf16 v[18:33], v[114:117], v[122:125], v[18:33]
	v_mfma_f32_32x32x16_bf16 v[34:49], v[126:129], v[134:137], v[34:49]
	v_mfma_f32_32x32x16_bf16 v[50:65], v[126:129], v[138:141], v[50:65]
	v_mfma_f32_32x32x16_bf16 v[2:17], v[130:133], v[134:137], v[2:17]
	v_mfma_f32_32x32x16_bf16 v[18:33], v[130:133], v[138:141], v[18:33]
	v_mfma_f32_32x32x16_bf16 v[34:49], v[142:145], v[150:153], v[34:49]
	v_mfma_f32_32x32x16_bf16 v[50:65], v[142:145], v[154:157], v[50:65]
	v_mfma_f32_32x32x16_bf16 v[2:17], v[146:149], v[150:153], v[2:17]
	v_mfma_f32_32x32x16_bf16 v[18:33], v[146:149], v[154:157], v[18:33]
	v_mov_b32_e32 v66, v178
	s_waitcnt lgkmcnt(0)
	s_barrier
	s_nop 0
	v_lshrrev_b32_e32 v0, 1, v66
	v_and_b32_e32 v0, 0xfffffc0, v0
	v_lshrrev_b32_e32 v67, 3, v66
	v_and_or_b32 v0, v67, 4, v0
	v_and_b32_e32 v67, 0x5f, v66
	v_mul_lo_u32 v0, v0, s83
	v_lshl_add_u32 v0, v67, 2, v0
	s_nop 0
	s_nop 11
	ds_write2_b32 v0, v34, v50 offset1:32
	ds_write2_b32 v0, v35, v51 offset0:132 offset1:164
	s_nop 0
	v_add_u32_e32 v34, 0x400, v0
	ds_write2_b32 v34, v36, v52 offset0:8 offset1:40
	ds_write2_b32 v34, v37, v53 offset0:140 offset1:172
	v_add_u32_e32 v34, 0x1000, v0
	ds_write2_b32 v34, v38, v54 offset0:32 offset1:64
	ds_write2_b32 v34, v39, v55 offset0:164 offset1:196
	v_add_u32_e32 v34, 0x1400, v0
	ds_write2_b32 v34, v40, v56 offset0:40 offset1:72
	ds_write2_b32 v34, v41, v57 offset0:172 offset1:204
	v_add_u32_e32 v34, 0x2000, v0
	s_nop 0
	ds_write2_b32 v34, v42, v58 offset0:64 offset1:96
	ds_write2_b32 v34, v43, v59 offset0:196 offset1:228
	v_add_u32_e32 v34, 0x2400, v0
	ds_write2_b32 v34, v44, v60 offset0:72 offset1:104
	ds_write2_b32 v34, v45, v61 offset0:204 offset1:236
	v_add_u32_e32 v34, 0x3000, v0
	ds_write2_b32 v34, v46, v62 offset0:96 offset1:128
	v_add_u32_e32 v34, 0x3200, v0
	ds_write2_b32 v34, v47, v63 offset0:100 offset1:132
	s_nop 0
	v_add_u32_e32 v34, 0x3400, v0
	ds_write2_b32 v34, v48, v64 offset0:104 offset1:136
	v_add_u32_e32 v34, 0x3600, v0
	ds_write2_b32 v34, v49, v65 offset0:108 offset1:140
	v_add_u32_e32 v34, 0x4000, v0
	s_nop 0
	s_nop 11
	ds_write2_b32 v34, v2, v18 offset0:128 offset1:160
	v_add_u32_e32 v2, 0x4400, v0
	ds_write2_b32 v2, v3, v19 offset0:4 offset1:36
	ds_write2_b32 v2, v4, v20 offset0:136 offset1:168
	v_add_u32_e32 v2, 0x4800, v0
	ds_write2_b32 v2, v5, v21 offset0:12 offset1:44
	v_add_u32_e32 v2, 0x5000, v0
	ds_write2_b32 v2, v6, v22 offset0:160 offset1:192
	v_add_u32_e32 v2, 0x5400, v0
	ds_write2_b32 v2, v7, v23 offset0:36 offset1:68
	ds_write2_b32 v2, v8, v24 offset0:168 offset1:200
	v_add_u32_e32 v2, 0x5800, v0
	ds_write2_b32 v2, v9, v25 offset0:44 offset1:76
	v_add_u32_e32 v2, 0x6000, v0
	ds_write2_b32 v2, v10, v26 offset0:192 offset1:224
	v_add_u32_e32 v2, 0x6400, v0
	ds_write2_b32 v2, v11, v27 offset0:68 offset1:100
	ds_write2_b32 v2, v12, v28 offset0:200 offset1:232
	v_add_u32_e32 v2, 0x6800, v0
	v_lshlrev_b32_e32 v6, 2, v66
	ds_write2_b32 v2, v13, v29 offset0:76 offset1:108
	v_add_u32_e32 v2, 0x7200, v0
	v_and_b32_e32 v6, 4, v6
	ds_write2_b32 v2, v14, v30 offset0:96 offset1:128
	v_add_u32_e32 v2, 0x7400, v0
	v_cvt_f32_ubyte0_e32 v7, v6
	ds_write2_b32 v2, v15, v31 offset0:100 offset1:132
	v_add_u32_e32 v2, 0x7600, v0
	v_add_u32_e32 v0, 0x7800, v0
	v_mul_f32_e32 v7, 0xbfd49a78, v7
	ds_write2_b32 v0, v17, v33 offset0:108 offset1:140
	v_lshlrev_b32_e32 v0, 3, v66
	v_exp_f32_e32 v15, v7
	v_or_b32_e32 v7, 1, v6
	v_and_b32_e32 v0, 0x78, v0
	v_cvt_f32_ubyte0_e32 v7, v7
	ds_write2_b32 v2, v16, v32 offset0:104 offset1:136
	v_or_b32_e32 v2, s0, v0
	v_mov_b32_e32 v4, s0
	s_movk_i32 s0, 0xffe0
	v_mul_f32_e32 v7, 0xbfd49a78, v7
	v_lshlrev_b32_e32 v14, 2, v0
	v_bitop3_b32 v0, v0, s0, v4 bitop3:0xc8
	s_movk_i32 s0, 0x280
	v_exp_f32_e32 v28, v7
	v_or_b32_e32 v7, 2, v6
	v_or_b32_e32 v6, 3, v6
	v_cmp_ne_u32_e64 s[40:41], s0, v0
	s_movk_i32 s0, 0x149f
	v_cvt_f32_ubyte0_e32 v7, v7
	v_cvt_f32_ubyte0_e32 v6, v6
	v_cmp_gt_i32_e64 s[38:39], s1, v2
	v_cmp_lt_i32_e64 s[42:43], s0, v2
	v_mul_f32_e32 v7, 0xbfd49a78, v7
	v_mul_f32_e32 v6, 0xbfd49a78, v6
	v_readlane_b32 s0, v251, 35
	v_mov_b32_e32 v4, v2
	v_mov_b32_e32 v5, v1
	v_exp_f32_e32 v29, v7
	v_exp_f32_e32 v30, v6
	v_readlane_b32 s1, v251, 36
	v_ashrrev_i32_e32 v3, 31, v2
	v_add_u32_e32 v0, 0xfffffd80, v2
	v_lshl_add_u64 v[18:19], v[4:5], 2, s[0:1]
	v_readlane_b32 s0, v249, 11
	v_readlane_b32 s1, v249, 12
	v_cmp_gt_u32_e64 s[44:45], 16, v0
	v_cmp_gt_u32_e64 s[46:47], 14, v0
	v_cmp_gt_u32_e64 s[48:49], 12, v0
	v_cmp_gt_u32_e64 s[50:51], 10, v0
	v_lshl_add_u64 v[16:17], v[2:3], 1, s[78:79]
	v_lshl_add_u64 v[20:21], v[0:1], 1, s[0:1]
	s_waitcnt lgkmcnt(0)
	s_barrier
	s_branch .LBB0_465

.LBB0_582:
	s_add_i32 s0, s25, 0xfffffc00
	s_lshr_b32 s1, s0, 1
	s_lshl_b32 s0, s25, 7
	s_and_b32 s0, s0, 0x80
	s_waitcnt vmcnt(12)
	v_mov_b32_e32 v36, v178
	s_or_b32 s0, s0, 0x300
	s_lshl_b32 s12, s1, 18
	v_readlane_b32 s22, v251, 31
	v_readlane_b32 s23, v251, 32
	v_ashrrev_i32_e32 v34, 3, v36
	s_add_u32 s12, s22, s12
	v_lshlrev_b32_e32 v0, 3, v36
	v_ashrrev_i32_e32 v35, 31, v34
	s_addc_u32 s13, s23, 0
	s_lshl_b32 s22, s0, 11
	v_and_b32_e32 v37, 56, v0
	s_waitcnt vmcnt(5)
	v_lshlrev_b64 v[2:3], 11, v[34:35]
	s_add_u32 s22, s92, s22
	v_lshl_add_u64 v[4:5], s[12:13], 0, v[2:3]
	v_lshlrev_b32_e32 v0, 1, v37
	s_addc_u32 s23, s93, 0
	v_lshl_add_u64 v[68:69], v[4:5], 0, v[0:1]
	v_lshl_add_u64 v[2:3], s[22:23], 0, v[2:3]
	v_lshl_add_u64 v[70:71], v[2:3], 0, v[0:1]
	v_and_b32_e32 v0, 7, v36
	v_bfe_u32 v66, v36, 4, 3
	v_xor_b32_e32 v66, v66, v0
	v_sub_u32_e32 v66, v66, v0
	v_lshlrev_b32_e32 v66, 4, v66
	v_ashrrev_i32_e32 v67, 31, v66
	v_lshl_add_u64 v[68:69], v[68:69], 0, v[66:67]
	v_lshl_add_u64 v[70:71], v[70:71], 0, v[66:67]
	v_add_co_u32_e32 v72, vcc, s73, v68
	s_nop 1
	v_addc_co_u32_e32 v73, vcc, 0, v69, vcc
	v_add_co_u32_e32 v74, vcc, s73, v70
	s_nop 1
	v_addc_co_u32_e32 v75, vcc, 0, v71, vcc
	v_add_co_u32_e32 v76, vcc, s52, v68
	s_nop 1
	v_addc_co_u32_e32 v77, vcc, 0, v69, vcc
	v_add_co_u32_e32 v78, vcc, s52, v70
	s_nop 1
	v_addc_co_u32_e32 v79, vcc, 0, v71, vcc
	v_add_co_u32_e32 v80, vcc, s53, v68
	s_nop 1
	v_addc_co_u32_e32 v81, vcc, 0, v69, vcc
	v_add_co_u32_e32 v82, vcc, s53, v70
	s_nop 1
	v_addc_co_u32_e32 v83, vcc, 0, v71, vcc
	v_and_b32_e32 v0, 31, v36
	v_bfe_u32 v66, v36, 5, 1
	v_bfe_u32 v67, v36, 1, 3
	v_xor_b32_e32 v66, v66, v67
	v_lshlrev_b32_e32 v66, 4, v66
	v_lshl_add_u32 v66, v0, 7, v66
	v_bfe_u32 v67, v36, 7, 1
	v_lshl_add_u32 v86, v67, 13, v66
	v_bfe_u32 v67, v36, 6, 1
	v_lshl_add_u32 v90, v67, 13, v66
	v_add_u32_e32 v90, 0x4000, v90
	v_xor_b32_e32 v87, 32, v86
	v_xor_b32_e32 v91, 32, v90
	v_xor_b32_e32 v88, 64, v86
	v_xor_b32_e32 v92, 64, v90
	v_xor_b32_e32 v89, 96, v86
	v_xor_b32_e32 v93, 96, v90
	v_lshrrev_b32_e32 v66, 6, v36
	v_lshlrev_b32_e32 v66, 10, v66
	s_nop 1
	v_readfirstlane_b32 s14, v66
	s_mov_b32 s12, 0
	s_lshl_b32 s1, s1, 7
	s_add_u32 m0, s14, 0x800
	s_nop 0
	global_load_lds_dwordx4 v[68:69], off
	s_add_u32 m0, s14, 0x1800
	s_nop 0
	global_load_lds_dwordx4 v[72:73], off
	s_add_u32 m0, s14, 0x2800
	s_nop 0
	global_load_lds_dwordx4 v[76:77], off
	s_add_u32 m0, s14, 0x3800
	s_nop 0
	global_load_lds_dwordx4 v[80:81], off
	s_add_u32 m0, s14, 0x4800
	s_nop 0
	global_load_lds_dwordx4 v[70:71], off
	s_add_u32 m0, s14, 0x5800
	s_nop 0
	global_load_lds_dwordx4 v[74:75], off
	s_add_u32 m0, s14, 0x6800
	s_nop 0
	global_load_lds_dwordx4 v[78:79], off
	s_add_u32 m0, s14, 0x7800
	s_nop 0
	global_load_lds_dwordx4 v[82:83], off
	s_add_u32 m0, s14, 0x8780
	s_nop 0
	global_load_lds_dwordx4 v[68:69], off offset:128
	s_add_u32 m0, s14, 0x9780
	s_nop 0
	global_load_lds_dwordx4 v[72:73], off offset:128
	s_add_u32 m0, s14, 0xa780
	s_nop 0
	global_load_lds_dwordx4 v[76:77], off offset:128
	s_add_u32 m0, s14, 0xb780
	s_nop 0
	global_load_lds_dwordx4 v[80:81], off offset:128
	s_add_u32 m0, s14, 0xc780
	s_nop 0
	global_load_lds_dwordx4 v[70:71], off offset:128
	s_add_u32 m0, s14, 0xd780
	s_nop 0
	global_load_lds_dwordx4 v[74:75], off offset:128
	s_add_u32 m0, s14, 0xe780
	s_nop 0
	global_load_lds_dwordx4 v[78:79], off offset:128
	s_add_u32 m0, s14, 0xf780
	s_nop 0
	global_load_lds_dwordx4 v[82:83], off offset:128
	s_waitcnt vmcnt(8)
	s_barrier
	ds_read_b128 v[94:97], v86 offset:2048
	ds_read_b128 v[98:101], v86 offset:6144
	ds_read_b128 v[102:105], v90 offset:2048
	ds_read_b128 v[106:109], v90 offset:6144
	ds_read_b128 v[110:113], v87 offset:2048
	ds_read_b128 v[114:117], v87 offset:6144
	ds_read_b128 v[118:121], v91 offset:2048
	ds_read_b128 v[122:125], v91 offset:6144
	ds_read_b128 v[126:129], v88 offset:2048
	ds_read_b128 v[130:133], v88 offset:6144
	ds_read_b128 v[134:137], v92 offset:2048
	ds_read_b128 v[138:141], v92 offset:6144
	ds_read_b128 v[142:145], v89 offset:2048
	ds_read_b128 v[146:149], v89 offset:6144
	ds_read_b128 v[150:153], v93 offset:2048
	ds_read_b128 v[154:157], v93 offset:6144
	s_waitcnt lgkmcnt(0)
	s_barrier
	s_add_u32 m0, s14, 0x700
	s_nop 0
	global_load_lds_dwordx4 v[68:69], off offset:256
	s_add_u32 m0, s14, 0x1700
	s_nop 0
	global_load_lds_dwordx4 v[72:73], off offset:256
	s_add_u32 m0, s14, 0x2700
	s_nop 0
	global_load_lds_dwordx4 v[76:77], off offset:256
	s_add_u32 m0, s14, 0x3700
	s_nop 0
	global_load_lds_dwordx4 v[80:81], off offset:256
	s_add_u32 m0, s14, 0x4700
	s_nop 0
	global_load_lds_dwordx4 v[70:71], off offset:256
	s_add_u32 m0, s14, 0x5700
	s_nop 0
	global_load_lds_dwordx4 v[74:75], off offset:256
	s_add_u32 m0, s14, 0x6700
	s_nop 0
	global_load_lds_dwordx4 v[78:79], off offset:256
	s_add_u32 m0, s14, 0x7700
	s_nop 0
	global_load_lds_dwordx4 v[82:83], off offset:256
	v_mfma_f32_32x32x16_bf16 v[34:49], v[94:97], v[102:105], 0
	v_mfma_f32_32x32x16_bf16 v[50:65], v[94:97], v[106:109], 0
	v_mfma_f32_32x32x16_bf16 v[2:17], v[98:101], v[102:105], 0
	v_mfma_f32_32x32x16_bf16 v[18:33], v[98:101], v[106:109], 0
	s_waitcnt vmcnt(8)
	s_barrier
	ds_read_b128 v[94:97], v86 offset:34816
	ds_read_b128 v[98:101], v86 offset:38912
	ds_read_b128 v[102:105], v90 offset:34816
	ds_read_b128 v[106:109], v90 offset:38912
	v_mfma_f32_32x32x16_bf16 v[34:49], v[110:113], v[118:121], v[34:49]
	v_mfma_f32_32x32x16_bf16 v[50:65], v[110:113], v[122:125], v[50:65]
	v_mfma_f32_32x32x16_bf16 v[2:17], v[114:117], v[118:121], v[2:17]
	v_mfma_f32_32x32x16_bf16 v[18:33], v[114:117], v[122:125], v[18:33]
	ds_read_b128 v[110:113], v87 offset:34816
	ds_read_b128 v[114:117], v87 offset:38912
	ds_read_b128 v[118:121], v91 offset:34816
	ds_read_b128 v[122:125], v91 offset:38912
	v_mfma_f32_32x32x16_bf16 v[34:49], v[126:129], v[134:137], v[34:49]
	v_mfma_f32_32x32x16_bf16 v[50:65], v[126:129], v[138:141], v[50:65]
	v_mfma_f32_32x32x16_bf16 v[2:17], v[130:133], v[134:137], v[2:17]
	v_mfma_f32_32x32x16_bf16 v[18:33], v[130:133], v[138:141], v[18:33]
	ds_read_b128 v[126:129], v88 offset:34816
	ds_read_b128 v[130:133], v88 offset:38912
	ds_read_b128 v[134:137], v92 offset:34816
	ds_read_b128 v[138:141], v92 offset:38912
	v_mfma_f32_32x32x16_bf16 v[34:49], v[142:145], v[150:153], v[34:49]
	v_mfma_f32_32x32x16_bf16 v[50:65], v[142:145], v[154:157], v[50:65]
	v_mfma_f32_32x32x16_bf16 v[2:17], v[146:149], v[150:153], v[2:17]
	v_mfma_f32_32x32x16_bf16 v[18:33], v[146:149], v[154:157], v[18:33]
	ds_read_b128 v[142:145], v89 offset:34816
	ds_read_b128 v[146:149], v89 offset:38912
	ds_read_b128 v[150:153], v93 offset:34816
	ds_read_b128 v[154:157], v93 offset:38912
	s_waitcnt lgkmcnt(0)
	s_barrier
	s_add_u32 m0, s14, 0x8680
	s_nop 0
	global_load_lds_dwordx4 v[68:69], off offset:384
	s_add_u32 m0, s14, 0x9680
	s_nop 0
	global_load_lds_dwordx4 v[72:73], off offset:384
	s_add_u32 m0, s14, 0xa680
	s_nop 0
	global_load_lds_dwordx4 v[76:77], off offset:384
	s_add_u32 m0, s14, 0xb680
	s_nop 0
	global_load_lds_dwordx4 v[80:81], off offset:384
	s_add_u32 m0, s14, 0xc680
	s_nop 0
	global_load_lds_dwordx4 v[70:71], off offset:384
	s_add_u32 m0, s14, 0xd680
	s_nop 0
	global_load_lds_dwordx4 v[74:75], off offset:384
	s_add_u32 m0, s14, 0xe680
	s_nop 0
	global_load_lds_dwordx4 v[78:79], off offset:384
	s_add_u32 m0, s14, 0xf680
	s_nop 0
	global_load_lds_dwordx4 v[82:83], off offset:384
	v_mfma_f32_32x32x16_bf16 v[34:49], v[94:97], v[102:105], v[34:49]
	v_mfma_f32_32x32x16_bf16 v[50:65], v[94:97], v[106:109], v[50:65]
	v_mfma_f32_32x32x16_bf16 v[2:17], v[98:101], v[102:105], v[2:17]
	v_mfma_f32_32x32x16_bf16 v[18:33], v[98:101], v[106:109], v[18:33]
	s_waitcnt vmcnt(8)
	s_barrier
	ds_read_b128 v[94:97], v86 offset:2048
	ds_read_b128 v[98:101], v86 offset:6144
	ds_read_b128 v[102:105], v90 offset:2048
	ds_read_b128 v[106:109], v90 offset:6144
	v_mfma_f32_32x32x16_bf16 v[34:49], v[110:113], v[118:121], v[34:49]
	v_mfma_f32_32x32x16_bf16 v[50:65], v[110:113], v[122:125], v[50:65]
	v_mfma_f32_32x32x16_bf16 v[2:17], v[114:117], v[118:121], v[2:17]
	v_mfma_f32_32x32x16_bf16 v[18:33], v[114:117], v[122:125], v[18:33]
	ds_read_b128 v[110:113], v87 offset:2048
	ds_read_b128 v[114:117], v87 offset:6144
	ds_read_b128 v[118:121], v91 offset:2048
	ds_read_b128 v[122:125], v91 offset:6144
	v_mfma_f32_32x32x16_bf16 v[34:49], v[126:129], v[134:137], v[34:49]
	v_mfma_f32_32x32x16_bf16 v[50:65], v[126:129], v[138:141], v[50:65]
	v_mfma_f32_32x32x16_bf16 v[2:17], v[130:133], v[134:137], v[2:17]
	v_mfma_f32_32x32x16_bf16 v[18:33], v[130:133], v[138:141], v[18:33]
	ds_read_b128 v[126:129], v88 offset:2048
	ds_read_b128 v[130:133], v88 offset:6144
	ds_read_b128 v[134:137], v92 offset:2048
	ds_read_b128 v[138:141], v92 offset:6144
	v_mfma_f32_32x32x16_bf16 v[34:49], v[142:145], v[150:153], v[34:49]
	v_mfma_f32_32x32x16_bf16 v[50:65], v[142:145], v[154:157], v[50:65]
	v_mfma_f32_32x32x16_bf16 v[2:17], v[146:149], v[150:153], v[2:17]
	v_mfma_f32_32x32x16_bf16 v[18:33], v[146:149], v[154:157], v[18:33]
	ds_read_b128 v[142:145], v89 offset:2048
	ds_read_b128 v[146:149], v89 offset:6144
	ds_read_b128 v[150:153], v93 offset:2048
	ds_read_b128 v[154:157], v93 offset:6144
	s_waitcnt lgkmcnt(0)
	s_barrier
	s_add_u32 m0, s14, 0x600
	s_nop 0
	global_load_lds_dwordx4 v[68:69], off offset:512
	s_add_u32 m0, s14, 0x1600
	s_nop 0
	global_load_lds_dwordx4 v[72:73], off offset:512
	s_add_u32 m0, s14, 0x2600
	s_nop 0
	global_load_lds_dwordx4 v[76:77], off offset:512
	s_add_u32 m0, s14, 0x3600
	s_nop 0
	global_load_lds_dwordx4 v[80:81], off offset:512
	s_add_u32 m0, s14, 0x4600
	s_nop 0
	global_load_lds_dwordx4 v[70:71], off offset:512
	s_add_u32 m0, s14, 0x5600
	s_nop 0
	global_load_lds_dwordx4 v[74:75], off offset:512
	s_add_u32 m0, s14, 0x6600
	s_nop 0
	global_load_lds_dwordx4 v[78:79], off offset:512
	s_add_u32 m0, s14, 0x7600
	s_nop 0
	global_load_lds_dwordx4 v[82:83], off offset:512
	v_mfma_f32_32x32x16_bf16 v[34:49], v[94:97], v[102:105], v[34:49]
	v_mfma_f32_32x32x16_bf16 v[50:65], v[94:97], v[106:109], v[50:65]
	v_mfma_f32_32x32x16_bf16 v[2:17], v[98:101], v[102:105], v[2:17]
	v_mfma_f32_32x32x16_bf16 v[18:33], v[98:101], v[106:109], v[18:33]
	s_waitcnt vmcnt(8)
	s_barrier
	ds_read_b128 v[94:97], v86 offset:34816
	ds_read_b128 v[98:101], v86 offset:38912
	ds_read_b128 v[102:105], v90 offset:34816
	ds_read_b128 v[106:109], v90 offset:38912
	v_mfma_f32_32x32x16_bf16 v[34:49], v[110:113], v[118:121], v[34:49]
	v_mfma_f32_32x32x16_bf16 v[50:65], v[110:113], v[122:125], v[50:65]
	v_mfma_f32_32x32x16_bf16 v[2:17], v[114:117], v[118:121], v[2:17]
	v_mfma_f32_32x32x16_bf16 v[18:33], v[114:117], v[122:125], v[18:33]
	ds_read_b128 v[110:113], v87 offset:34816
	ds_read_b128 v[114:117], v87 offset:38912
	ds_read_b128 v[118:121], v91 offset:34816
	ds_read_b128 v[122:125], v91 offset:38912
	v_mfma_f32_32x32x16_bf16 v[34:49], v[126:129], v[134:137], v[34:49]
	v_mfma_f32_32x32x16_bf16 v[50:65], v[126:129], v[138:141], v[50:65]
	v_mfma_f32_32x32x16_bf16 v[2:17], v[130:133], v[134:137], v[2:17]
	v_mfma_f32_32x32x16_bf16 v[18:33], v[130:133], v[138:141], v[18:33]
	ds_read_b128 v[126:129], v88 offset:34816
	ds_read_b128 v[130:133], v88 offset:38912
	ds_read_b128 v[134:137], v92 offset:34816
	ds_read_b128 v[138:141], v92 offset:38912
	v_mfma_f32_32x32x16_bf16 v[34:49], v[142:145], v[150:153], v[34:49]
	v_mfma_f32_32x32x16_bf16 v[50:65], v[142:145], v[154:157], v[50:65]
	v_mfma_f32_32x32x16_bf16 v[2:17], v[146:149], v[150:153], v[2:17]
	v_mfma_f32_32x32x16_bf16 v[18:33], v[146:149], v[154:157], v[18:33]
	ds_read_b128 v[142:145], v89 offset:34816
	ds_read_b128 v[146:149], v89 offset:38912
	ds_read_b128 v[150:153], v93 offset:34816
	ds_read_b128 v[154:157], v93 offset:38912
	s_waitcnt lgkmcnt(0)
	s_barrier
	s_add_u32 m0, s14, 0x8580
	s_nop 0
	global_load_lds_dwordx4 v[68:69], off offset:640
	s_add_u32 m0, s14, 0x9580
	s_nop 0
	global_load_lds_dwordx4 v[72:73], off offset:640
	s_add_u32 m0, s14, 0xa580
	s_nop 0
	global_load_lds_dwordx4 v[76:77], off offset:640
	s_add_u32 m0, s14, 0xb580
	s_nop 0
	global_load_lds_dwordx4 v[80:81], off offset:640
	s_add_u32 m0, s14, 0xc580
	s_nop 0
	global_load_lds_dwordx4 v[70:71], off offset:640
	s_add_u32 m0, s14, 0xd580
	s_nop 0
	global_load_lds_dwordx4 v[74:75], off offset:640
	s_add_u32 m0, s14, 0xe580
	s_nop 0
	global_load_lds_dwordx4 v[78:79], off offset:640
	s_add_u32 m0, s14, 0xf580
	s_nop 0
	global_load_lds_dwordx4 v[82:83], off offset:640
	v_mfma_f32_32x32x16_bf16 v[34:49], v[94:97], v[102:105], v[34:49]
	v_mfma_f32_32x32x16_bf16 v[50:65], v[94:97], v[106:109], v[50:65]
	v_mfma_f32_32x32x16_bf16 v[2:17], v[98:101], v[102:105], v[2:17]
	v_mfma_f32_32x32x16_bf16 v[18:33], v[98:101], v[106:109], v[18:33]
	s_waitcnt vmcnt(8)
	s_barrier
	ds_read_b128 v[94:97], v86 offset:2048
	ds_read_b128 v[98:101], v86 offset:6144
	ds_read_b128 v[102:105], v90 offset:2048
	ds_read_b128 v[106:109], v90 offset:6144
	v_mfma_f32_32x32x16_bf16 v[34:49], v[110:113], v[118:121], v[34:49]
	v_mfma_f32_32x32x16_bf16 v[50:65], v[110:113], v[122:125], v[50:65]
	v_mfma_f32_32x32x16_bf16 v[2:17], v[114:117], v[118:121], v[2:17]
	v_mfma_f32_32x32x16_bf16 v[18:33], v[114:117], v[122:125], v[18:33]
	ds_read_b128 v[110:113], v87 offset:2048
	ds_read_b128 v[114:117], v87 offset:6144
	ds_read_b128 v[118:121], v91 offset:2048
	ds_read_b128 v[122:125], v91 offset:6144
	v_mfma_f32_32x32x16_bf16 v[34:49], v[126:129], v[134:137], v[34:49]
	v_mfma_f32_32x32x16_bf16 v[50:65], v[126:129], v[138:141], v[50:65]
	v_mfma_f32_32x32x16_bf16 v[2:17], v[130:133], v[134:137], v[2:17]
	v_mfma_f32_32x32x16_bf16 v[18:33], v[130:133], v[138:141], v[18:33]
	ds_read_b128 v[126:129], v88 offset:2048
	ds_read_b128 v[130:133], v88 offset:6144
	ds_read_b128 v[134:137], v92 offset:2048
	ds_read_b128 v[138:141], v92 offset:6144
	v_mfma_f32_32x32x16_bf16 v[34:49], v[142:145], v[150:153], v[34:49]
	v_mfma_f32_32x32x16_bf16 v[50:65], v[142:145], v[154:157], v[50:65]
	v_mfma_f32_32x32x16_bf16 v[2:17], v[146:149], v[150:153], v[2:17]
	v_mfma_f32_32x32x16_bf16 v[18:33], v[146:149], v[154:157], v[18:33]
	ds_read_b128 v[142:145], v89 offset:2048
	ds_read_b128 v[146:149], v89 offset:6144
	ds_read_b128 v[150:153], v93 offset:2048
	ds_read_b128 v[154:157], v93 offset:6144
	s_waitcnt lgkmcnt(0)
	s_barrier
	s_add_u32 m0, s14, 0x500
	s_nop 0
	global_load_lds_dwordx4 v[68:69], off offset:768
	s_add_u32 m0, s14, 0x1500
	s_nop 0
	global_load_lds_dwordx4 v[72:73], off offset:768
	s_add_u32 m0, s14, 0x2500
	s_nop 0
	global_load_lds_dwordx4 v[76:77], off offset:768
	s_add_u32 m0, s14, 0x3500
	s_nop 0
	global_load_lds_dwordx4 v[80:81], off offset:768
	s_add_u32 m0, s14, 0x4500
	s_nop 0
	global_load_lds_dwordx4 v[70:71], off offset:768
	s_add_u32 m0, s14, 0x5500
	s_nop 0
	global_load_lds_dwordx4 v[74:75], off offset:768
	s_add_u32 m0, s14, 0x6500
	s_nop 0
	global_load_lds_dwordx4 v[78:79], off offset:768
	s_add_u32 m0, s14, 0x7500
	s_nop 0
	global_load_lds_dwordx4 v[82:83], off offset:768
	v_mfma_f32_32x32x16_bf16 v[34:49], v[94:97], v[102:105], v[34:49]
	v_mfma_f32_32x32x16_bf16 v[50:65], v[94:97], v[106:109], v[50:65]
	v_mfma_f32_32x32x16_bf16 v[2:17], v[98:101], v[102:105], v[2:17]
	v_mfma_f32_32x32x16_bf16 v[18:33], v[98:101], v[106:109], v[18:33]
	s_waitcnt vmcnt(8)
	s_barrier
	ds_read_b128 v[94:97], v86 offset:34816
	ds_read_b128 v[98:101], v86 offset:38912
	ds_read_b128 v[102:105], v90 offset:34816
	ds_read_b128 v[106:109], v90 offset:38912
	v_mfma_f32_32x32x16_bf16 v[34:49], v[110:113], v[118:121], v[34:49]
	v_mfma_f32_32x32x16_bf16 v[50:65], v[110:113], v[122:125], v[50:65]
	v_mfma_f32_32x32x16_bf16 v[2:17], v[114:117], v[118:121], v[2:17]
	v_mfma_f32_32x32x16_bf16 v[18:33], v[114:117], v[122:125], v[18:33]
	ds_read_b128 v[110:113], v87 offset:34816
	ds_read_b128 v[114:117], v87 offset:38912
	ds_read_b128 v[118:121], v91 offset:34816
	ds_read_b128 v[122:125], v91 offset:38912
	v_mfma_f32_32x32x16_bf16 v[34:49], v[126:129], v[134:137], v[34:49]
	v_mfma_f32_32x32x16_bf16 v[50:65], v[126:129], v[138:141], v[50:65]
	v_mfma_f32_32x32x16_bf16 v[2:17], v[130:133], v[134:137], v[2:17]
	v_mfma_f32_32x32x16_bf16 v[18:33], v[130:133], v[138:141], v[18:33]
	ds_read_b128 v[126:129], v88 offset:34816
	ds_read_b128 v[130:133], v88 offset:38912
	ds_read_b128 v[134:137], v92 offset:34816
	ds_read_b128 v[138:141], v92 offset:38912
	v_mfma_f32_32x32x16_bf16 v[34:49], v[142:145], v[150:153], v[34:49]
	v_mfma_f32_32x32x16_bf16 v[50:65], v[142:145], v[154:157], v[50:65]
	v_mfma_f32_32x32x16_bf16 v[2:17], v[146:149], v[150:153], v[2:17]
	v_mfma_f32_32x32x16_bf16 v[18:33], v[146:149], v[154:157], v[18:33]
	ds_read_b128 v[142:145], v89 offset:34816
	ds_read_b128 v[146:149], v89 offset:38912
	ds_read_b128 v[150:153], v93 offset:34816
	ds_read_b128 v[154:157], v93 offset:38912
	s_waitcnt lgkmcnt(0)
	s_barrier
	s_add_u32 m0, s14, 0x8480
	s_nop 0
	global_load_lds_dwordx4 v[68:69], off offset:896
	s_add_u32 m0, s14, 0x9480
	s_nop 0
	global_load_lds_dwordx4 v[72:73], off offset:896
	s_add_u32 m0, s14, 0xa480
	s_nop 0
	global_load_lds_dwordx4 v[76:77], off offset:896
	s_add_u32 m0, s14, 0xb480
	s_nop 0
	global_load_lds_dwordx4 v[80:81], off offset:896
	s_add_u32 m0, s14, 0xc480
	s_nop 0
	global_load_lds_dwordx4 v[70:71], off offset:896
	s_add_u32 m0, s14, 0xd480
	s_nop 0
	global_load_lds_dwordx4 v[74:75], off offset:896
	s_add_u32 m0, s14, 0xe480
	s_nop 0
	global_load_lds_dwordx4 v[78:79], off offset:896
	s_add_u32 m0, s14, 0xf480
	s_nop 0
	global_load_lds_dwordx4 v[82:83], off offset:896
	v_mfma_f32_32x32x16_bf16 v[34:49], v[94:97], v[102:105], v[34:49]
	v_mfma_f32_32x32x16_bf16 v[50:65], v[94:97], v[106:109], v[50:65]
	v_mfma_f32_32x32x16_bf16 v[2:17], v[98:101], v[102:105], v[2:17]
	v_mfma_f32_32x32x16_bf16 v[18:33], v[98:101], v[106:109], v[18:33]
	s_waitcnt vmcnt(8)
	s_barrier
	ds_read_b128 v[94:97], v86 offset:2048
	ds_read_b128 v[98:101], v86 offset:6144
	ds_read_b128 v[102:105], v90 offset:2048
	ds_read_b128 v[106:109], v90 offset:6144
	v_mfma_f32_32x32x16_bf16 v[34:49], v[110:113], v[118:121], v[34:49]
	v_mfma_f32_32x32x16_bf16 v[50:65], v[110:113], v[122:125], v[50:65]
	v_mfma_f32_32x32x16_bf16 v[2:17], v[114:117], v[118:121], v[2:17]
	v_mfma_f32_32x32x16_bf16 v[18:33], v[114:117], v[122:125], v[18:33]
	ds_read_b128 v[110:113], v87 offset:2048
	ds_read_b128 v[114:117], v87 offset:6144
	ds_read_b128 v[118:121], v91 offset:2048
	ds_read_b128 v[122:125], v91 offset:6144
	v_mfma_f32_32x32x16_bf16 v[34:49], v[126:129], v[134:137], v[34:49]
	v_mfma_f32_32x32x16_bf16 v[50:65], v[126:129], v[138:141], v[50:65]
	v_mfma_f32_32x32x16_bf16 v[2:17], v[130:133], v[134:137], v[2:17]
	v_mfma_f32_32x32x16_bf16 v[18:33], v[130:133], v[138:141], v[18:33]
	ds_read_b128 v[126:129], v88 offset:2048
	ds_read_b128 v[130:133], v88 offset:6144
	ds_read_b128 v[134:137], v92 offset:2048
	ds_read_b128 v[138:141], v92 offset:6144
	v_mfma_f32_32x32x16_bf16 v[34:49], v[142:145], v[150:153], v[34:49]
	v_mfma_f32_32x32x16_bf16 v[50:65], v[142:145], v[154:157], v[50:65]
	v_mfma_f32_32x32x16_bf16 v[2:17], v[146:149], v[150:153], v[2:17]
	v_mfma_f32_32x32x16_bf16 v[18:33], v[146:149], v[154:157], v[18:33]
	ds_read_b128 v[142:145], v89 offset:2048
	ds_read_b128 v[146:149], v89 offset:6144
	ds_read_b128 v[150:153], v93 offset:2048
	ds_read_b128 v[154:157], v93 offset:6144
	s_waitcnt lgkmcnt(0)
	s_barrier
	s_add_u32 m0, s14, 0x400
	s_nop 0
	global_load_lds_dwordx4 v[68:69], off offset:1024
	s_add_u32 m0, s14, 0x1400
	s_nop 0
	global_load_lds_dwordx4 v[72:73], off offset:1024
	s_add_u32 m0, s14, 0x2400
	s_nop 0
	global_load_lds_dwordx4 v[76:77], off offset:1024
	s_add_u32 m0, s14, 0x3400
	s_nop 0
	global_load_lds_dwordx4 v[80:81], off offset:1024
	s_add_u32 m0, s14, 0x4400
	s_nop 0
	global_load_lds_dwordx4 v[70:71], off offset:1024
	s_add_u32 m0, s14, 0x5400
	s_nop 0
	global_load_lds_dwordx4 v[74:75], off offset:1024
	s_add_u32 m0, s14, 0x6400
	s_nop 0
	global_load_lds_dwordx4 v[78:79], off offset:1024
	s_add_u32 m0, s14, 0x7400
	s_nop 0
	global_load_lds_dwordx4 v[82:83], off offset:1024
	v_mfma_f32_32x32x16_bf16 v[34:49], v[94:97], v[102:105], v[34:49]
	v_mfma_f32_32x32x16_bf16 v[50:65], v[94:97], v[106:109], v[50:65]
	v_mfma_f32_32x32x16_bf16 v[2:17], v[98:101], v[102:105], v[2:17]
	v_mfma_f32_32x32x16_bf16 v[18:33], v[98:101], v[106:109], v[18:33]
	s_waitcnt vmcnt(8)
	s_barrier
	ds_read_b128 v[94:97], v86 offset:34816
	ds_read_b128 v[98:101], v86 offset:38912
	ds_read_b128 v[102:105], v90 offset:34816
	ds_read_b128 v[106:109], v90 offset:38912
	v_mfma_f32_32x32x16_bf16 v[34:49], v[110:113], v[118:121], v[34:49]
	v_mfma_f32_32x32x16_bf16 v[50:65], v[110:113], v[122:125], v[50:65]
	v_mfma_f32_32x32x16_bf16 v[2:17], v[114:117], v[118:121], v[2:17]
	v_mfma_f32_32x32x16_bf16 v[18:33], v[114:117], v[122:125], v[18:33]
	ds_read_b128 v[110:113], v87 offset:34816
	ds_read_b128 v[114:117], v87 offset:38912
	ds_read_b128 v[118:121], v91 offset:34816
	ds_read_b128 v[122:125], v91 offset:38912
	v_mfma_f32_32x32x16_bf16 v[34:49], v[126:129], v[134:137], v[34:49]
	v_mfma_f32_32x32x16_bf16 v[50:65], v[126:129], v[138:141], v[50:65]
	v_mfma_f32_32x32x16_bf16 v[2:17], v[130:133], v[134:137], v[2:17]
	v_mfma_f32_32x32x16_bf16 v[18:33], v[130:133], v[138:141], v[18:33]
	ds_read_b128 v[126:129], v88 offset:34816
	ds_read_b128 v[130:133], v88 offset:38912
	ds_read_b128 v[134:137], v92 offset:34816
	ds_read_b128 v[138:141], v92 offset:38912
	v_mfma_f32_32x32x16_bf16 v[34:49], v[142:145], v[150:153], v[34:49]
	v_mfma_f32_32x32x16_bf16 v[50:65], v[142:145], v[154:157], v[50:65]
	v_mfma_f32_32x32x16_bf16 v[2:17], v[146:149], v[150:153], v[2:17]
	v_mfma_f32_32x32x16_bf16 v[18:33], v[146:149], v[154:157], v[18:33]
	ds_read_b128 v[142:145], v89 offset:34816
	ds_read_b128 v[146:149], v89 offset:38912
	ds_read_b128 v[150:153], v93 offset:34816
	ds_read_b128 v[154:157], v93 offset:38912
	s_waitcnt lgkmcnt(0)
	s_barrier
	s_add_u32 m0, s14, 0x8380
	s_nop 0
	global_load_lds_dwordx4 v[68:69], off offset:1152
	s_add_u32 m0, s14, 0x9380
	s_nop 0
	global_load_lds_dwordx4 v[72:73], off offset:1152
	s_add_u32 m0, s14, 0xa380
	s_nop 0
	global_load_lds_dwordx4 v[76:77], off offset:1152
	s_add_u32 m0, s14, 0xb380
	s_nop 0
	global_load_lds_dwordx4 v[80:81], off offset:1152
	s_add_u32 m0, s14, 0xc380
	s_nop 0
	global_load_lds_dwordx4 v[70:71], off offset:1152
	s_add_u32 m0, s14, 0xd380
	s_nop 0
	global_load_lds_dwordx4 v[74:75], off offset:1152
	s_add_u32 m0, s14, 0xe380
	s_nop 0
	global_load_lds_dwordx4 v[78:79], off offset:1152
	s_add_u32 m0, s14, 0xf380
	s_nop 0
	global_load_lds_dwordx4 v[82:83], off offset:1152
	v_mfma_f32_32x32x16_bf16 v[34:49], v[94:97], v[102:105], v[34:49]
	v_mfma_f32_32x32x16_bf16 v[50:65], v[94:97], v[106:109], v[50:65]
	v_mfma_f32_32x32x16_bf16 v[2:17], v[98:101], v[102:105], v[2:17]
	v_mfma_f32_32x32x16_bf16 v[18:33], v[98:101], v[106:109], v[18:33]
	s_waitcnt vmcnt(8)
	s_barrier
	ds_read_b128 v[94:97], v86 offset:2048
	ds_read_b128 v[98:101], v86 offset:6144
	ds_read_b128 v[102:105], v90 offset:2048
	ds_read_b128 v[106:109], v90 offset:6144
	v_mfma_f32_32x32x16_bf16 v[34:49], v[110:113], v[118:121], v[34:49]
	v_mfma_f32_32x32x16_bf16 v[50:65], v[110:113], v[122:125], v[50:65]
	v_mfma_f32_32x32x16_bf16 v[2:17], v[114:117], v[118:121], v[2:17]
	v_mfma_f32_32x32x16_bf16 v[18:33], v[114:117], v[122:125], v[18:33]
	ds_read_b128 v[110:113], v87 offset:2048
	ds_read_b128 v[114:117], v87 offset:6144
	ds_read_b128 v[118:121], v91 offset:2048
	ds_read_b128 v[122:125], v91 offset:6144
	v_mfma_f32_32x32x16_bf16 v[34:49], v[126:129], v[134:137], v[34:49]
	v_mfma_f32_32x32x16_bf16 v[50:65], v[126:129], v[138:141], v[50:65]
	v_mfma_f32_32x32x16_bf16 v[2:17], v[130:133], v[134:137], v[2:17]
	v_mfma_f32_32x32x16_bf16 v[18:33], v[130:133], v[138:141], v[18:33]
	ds_read_b128 v[126:129], v88 offset:2048
	ds_read_b128 v[130:133], v88 offset:6144
	ds_read_b128 v[134:137], v92 offset:2048
	ds_read_b128 v[138:141], v92 offset:6144
	v_mfma_f32_32x32x16_bf16 v[34:49], v[142:145], v[150:153], v[34:49]
	v_mfma_f32_32x32x16_bf16 v[50:65], v[142:145], v[154:157], v[50:65]
	v_mfma_f32_32x32x16_bf16 v[2:17], v[146:149], v[150:153], v[2:17]
	v_mfma_f32_32x32x16_bf16 v[18:33], v[146:149], v[154:157], v[18:33]
	ds_read_b128 v[142:145], v89 offset:2048
	ds_read_b128 v[146:149], v89 offset:6144
	ds_read_b128 v[150:153], v93 offset:2048
	ds_read_b128 v[154:157], v93 offset:6144
	s_waitcnt lgkmcnt(0)
	s_barrier
	s_add_u32 m0, s14, 0x300
	s_nop 0
	global_load_lds_dwordx4 v[68:69], off offset:1280
	s_add_u32 m0, s14, 0x1300
	s_nop 0
	global_load_lds_dwordx4 v[72:73], off offset:1280
	s_add_u32 m0, s14, 0x2300
	s_nop 0
	global_load_lds_dwordx4 v[76:77], off offset:1280
	s_add_u32 m0, s14, 0x3300
	s_nop 0
	global_load_lds_dwordx4 v[80:81], off offset:1280
	s_add_u32 m0, s14, 0x4300
	s_nop 0
	global_load_lds_dwordx4 v[70:71], off offset:1280
	s_add_u32 m0, s14, 0x5300
	s_nop 0
	global_load_lds_dwordx4 v[74:75], off offset:1280
	s_add_u32 m0, s14, 0x6300
	s_nop 0
	global_load_lds_dwordx4 v[78:79], off offset:1280
	s_add_u32 m0, s14, 0x7300
	s_nop 0
	global_load_lds_dwordx4 v[82:83], off offset:1280
	v_mfma_f32_32x32x16_bf16 v[34:49], v[94:97], v[102:105], v[34:49]
	v_mfma_f32_32x32x16_bf16 v[50:65], v[94:97], v[106:109], v[50:65]
	v_mfma_f32_32x32x16_bf16 v[2:17], v[98:101], v[102:105], v[2:17]
	v_mfma_f32_32x32x16_bf16 v[18:33], v[98:101], v[106:109], v[18:33]
	s_waitcnt vmcnt(8)
	s_barrier
	ds_read_b128 v[94:97], v86 offset:34816
	ds_read_b128 v[98:101], v86 offset:38912
	ds_read_b128 v[102:105], v90 offset:34816
	ds_read_b128 v[106:109], v90 offset:38912
	v_mfma_f32_32x32x16_bf16 v[34:49], v[110:113], v[118:121], v[34:49]
	v_mfma_f32_32x32x16_bf16 v[50:65], v[110:113], v[122:125], v[50:65]
	v_mfma_f32_32x32x16_bf16 v[2:17], v[114:117], v[118:121], v[2:17]
	v_mfma_f32_32x32x16_bf16 v[18:33], v[114:117], v[122:125], v[18:33]
	ds_read_b128 v[110:113], v87 offset:34816
	ds_read_b128 v[114:117], v87 offset:38912
	ds_read_b128 v[118:121], v91 offset:34816
	ds_read_b128 v[122:125], v91 offset:38912
	v_mfma_f32_32x32x16_bf16 v[34:49], v[126:129], v[134:137], v[34:49]
	v_mfma_f32_32x32x16_bf16 v[50:65], v[126:129], v[138:141], v[50:65]
	v_mfma_f32_32x32x16_bf16 v[2:17], v[130:133], v[134:137], v[2:17]
	v_mfma_f32_32x32x16_bf16 v[18:33], v[130:133], v[138:141], v[18:33]
	ds_read_b128 v[126:129], v88 offset:34816
	ds_read_b128 v[130:133], v88 offset:38912
	ds_read_b128 v[134:137], v92 offset:34816
	ds_read_b128 v[138:141], v92 offset:38912
	v_mfma_f32_32x32x16_bf16 v[34:49], v[142:145], v[150:153], v[34:49]
	v_mfma_f32_32x32x16_bf16 v[50:65], v[142:145], v[154:157], v[50:65]
	v_mfma_f32_32x32x16_bf16 v[2:17], v[146:149], v[150:153], v[2:17]
	v_mfma_f32_32x32x16_bf16 v[18:33], v[146:149], v[154:157], v[18:33]
	ds_read_b128 v[142:145], v89 offset:34816
	ds_read_b128 v[146:149], v89 offset:38912
	ds_read_b128 v[150:153], v93 offset:34816
	ds_read_b128 v[154:157], v93 offset:38912
	s_waitcnt lgkmcnt(0)
	s_barrier
	s_add_u32 m0, s14, 0x8280
	s_nop 0
	global_load_lds_dwordx4 v[68:69], off offset:1408
	s_add_u32 m0, s14, 0x9280
	s_nop 0
	global_load_lds_dwordx4 v[72:73], off offset:1408
	s_add_u32 m0, s14, 0xa280
	s_nop 0
	global_load_lds_dwordx4 v[76:77], off offset:1408
	s_add_u32 m0, s14, 0xb280
	s_nop 0
	global_load_lds_dwordx4 v[80:81], off offset:1408
	s_add_u32 m0, s14, 0xc280
	s_nop 0
	global_load_lds_dwordx4 v[70:71], off offset:1408
	s_add_u32 m0, s14, 0xd280
	s_nop 0
	global_load_lds_dwordx4 v[74:75], off offset:1408
	s_add_u32 m0, s14, 0xe280
	s_nop 0
	global_load_lds_dwordx4 v[78:79], off offset:1408
	s_add_u32 m0, s14, 0xf280
	s_nop 0
	global_load_lds_dwordx4 v[82:83], off offset:1408
	v_mfma_f32_32x32x16_bf16 v[34:49], v[94:97], v[102:105], v[34:49]
	v_mfma_f32_32x32x16_bf16 v[50:65], v[94:97], v[106:109], v[50:65]
	v_mfma_f32_32x32x16_bf16 v[2:17], v[98:101], v[102:105], v[2:17]
	v_mfma_f32_32x32x16_bf16 v[18:33], v[98:101], v[106:109], v[18:33]
	s_waitcnt vmcnt(8)
	s_barrier
	ds_read_b128 v[94:97], v86 offset:2048
	ds_read_b128 v[98:101], v86 offset:6144
	ds_read_b128 v[102:105], v90 offset:2048
	ds_read_b128 v[106:109], v90 offset:6144
	v_mfma_f32_32x32x16_bf16 v[34:49], v[110:113], v[118:121], v[34:49]
	v_mfma_f32_32x32x16_bf16 v[50:65], v[110:113], v[122:125], v[50:65]
	v_mfma_f32_32x32x16_bf16 v[2:17], v[114:117], v[118:121], v[2:17]
	v_mfma_f32_32x32x16_bf16 v[18:33], v[114:117], v[122:125], v[18:33]
	ds_read_b128 v[110:113], v87 offset:2048
	ds_read_b128 v[114:117], v87 offset:6144
	ds_read_b128 v[118:121], v91 offset:2048
	ds_read_b128 v[122:125], v91 offset:6144
	v_mfma_f32_32x32x16_bf16 v[34:49], v[126:129], v[134:137], v[34:49]
	v_mfma_f32_32x32x16_bf16 v[50:65], v[126:129], v[138:141], v[50:65]
	v_mfma_f32_32x32x16_bf16 v[2:17], v[130:133], v[134:137], v[2:17]
	v_mfma_f32_32x32x16_bf16 v[18:33], v[130:133], v[138:141], v[18:33]
	ds_read_b128 v[126:129], v88 offset:2048
	ds_read_b128 v[130:133], v88 offset:6144
	ds_read_b128 v[134:137], v92 offset:2048
	ds_read_b128 v[138:141], v92 offset:6144
	v_mfma_f32_32x32x16_bf16 v[34:49], v[142:145], v[150:153], v[34:49]
	v_mfma_f32_32x32x16_bf16 v[50:65], v[142:145], v[154:157], v[50:65]
	v_mfma_f32_32x32x16_bf16 v[2:17], v[146:149], v[150:153], v[2:17]
	v_mfma_f32_32x32x16_bf16 v[18:33], v[146:149], v[154:157], v[18:33]
	ds_read_b128 v[142:145], v89 offset:2048
	ds_read_b128 v[146:149], v89 offset:6144
	ds_read_b128 v[150:153], v93 offset:2048
	ds_read_b128 v[154:157], v93 offset:6144
	s_waitcnt lgkmcnt(0)
	s_barrier
	s_add_u32 m0, s14, 0x200
	s_nop 0
	global_load_lds_dwordx4 v[68:69], off offset:1536
	s_add_u32 m0, s14, 0x1200
	s_nop 0
	global_load_lds_dwordx4 v[72:73], off offset:1536
	s_add_u32 m0, s14, 0x2200
	s_nop 0
	global_load_lds_dwordx4 v[76:77], off offset:1536
	s_add_u32 m0, s14, 0x3200
	s_nop 0
	global_load_lds_dwordx4 v[80:81], off offset:1536
	s_add_u32 m0, s14, 0x4200
	s_nop 0
	global_load_lds_dwordx4 v[70:71], off offset:1536
	s_add_u32 m0, s14, 0x5200
	s_nop 0
	global_load_lds_dwordx4 v[74:75], off offset:1536
	s_add_u32 m0, s14, 0x6200
	s_nop 0
	global_load_lds_dwordx4 v[78:79], off offset:1536
	s_add_u32 m0, s14, 0x7200
	s_nop 0
	global_load_lds_dwordx4 v[82:83], off offset:1536
	v_mfma_f32_32x32x16_bf16 v[34:49], v[94:97], v[102:105], v[34:49]
	v_mfma_f32_32x32x16_bf16 v[50:65], v[94:97], v[106:109], v[50:65]
	v_mfma_f32_32x32x16_bf16 v[2:17], v[98:101], v[102:105], v[2:17]
	v_mfma_f32_32x32x16_bf16 v[18:33], v[98:101], v[106:109], v[18:33]
	s_waitcnt vmcnt(8)
	s_barrier
	ds_read_b128 v[94:97], v86 offset:34816
	ds_read_b128 v[98:101], v86 offset:38912
	ds_read_b128 v[102:105], v90 offset:34816
	ds_read_b128 v[106:109], v90 offset:38912
	v_mfma_f32_32x32x16_bf16 v[34:49], v[110:113], v[118:121], v[34:49]
	v_mfma_f32_32x32x16_bf16 v[50:65], v[110:113], v[122:125], v[50:65]
	v_mfma_f32_32x32x16_bf16 v[2:17], v[114:117], v[118:121], v[2:17]
	v_mfma_f32_32x32x16_bf16 v[18:33], v[114:117], v[122:125], v[18:33]
	ds_read_b128 v[110:113], v87 offset:34816
	ds_read_b128 v[114:117], v87 offset:38912
	ds_read_b128 v[118:121], v91 offset:34816
	ds_read_b128 v[122:125], v91 offset:38912
	v_mfma_f32_32x32x16_bf16 v[34:49], v[126:129], v[134:137], v[34:49]
	v_mfma_f32_32x32x16_bf16 v[50:65], v[126:129], v[138:141], v[50:65]
	v_mfma_f32_32x32x16_bf16 v[2:17], v[130:133], v[134:137], v[2:17]
	v_mfma_f32_32x32x16_bf16 v[18:33], v[130:133], v[138:141], v[18:33]
	ds_read_b128 v[126:129], v88 offset:34816
	ds_read_b128 v[130:133], v88 offset:38912
	ds_read_b128 v[134:137], v92 offset:34816
	ds_read_b128 v[138:141], v92 offset:38912
	v_mfma_f32_32x32x16_bf16 v[34:49], v[142:145], v[150:153], v[34:49]
	v_mfma_f32_32x32x16_bf16 v[50:65], v[142:145], v[154:157], v[50:65]
	v_mfma_f32_32x32x16_bf16 v[2:17], v[146:149], v[150:153], v[2:17]
	v_mfma_f32_32x32x16_bf16 v[18:33], v[146:149], v[154:157], v[18:33]
	ds_read_b128 v[142:145], v89 offset:34816
	ds_read_b128 v[146:149], v89 offset:38912
	ds_read_b128 v[150:153], v93 offset:34816
	ds_read_b128 v[154:157], v93 offset:38912
	s_waitcnt lgkmcnt(0)
	s_barrier
	s_add_u32 m0, s14, 0x8180
	s_nop 0
	global_load_lds_dwordx4 v[68:69], off offset:1664
	s_add_u32 m0, s14, 0x9180
	s_nop 0
	global_load_lds_dwordx4 v[72:73], off offset:1664
	s_add_u32 m0, s14, 0xa180
	s_nop 0
	global_load_lds_dwordx4 v[76:77], off offset:1664
	s_add_u32 m0, s14, 0xb180
	s_nop 0
	global_load_lds_dwordx4 v[80:81], off offset:1664
	s_add_u32 m0, s14, 0xc180
	s_nop 0
	global_load_lds_dwordx4 v[70:71], off offset:1664
	s_add_u32 m0, s14, 0xd180
	s_nop 0
	global_load_lds_dwordx4 v[74:75], off offset:1664
	s_add_u32 m0, s14, 0xe180
	s_nop 0
	global_load_lds_dwordx4 v[78:79], off offset:1664
	s_add_u32 m0, s14, 0xf180
	s_nop 0
	global_load_lds_dwordx4 v[82:83], off offset:1664
	v_mfma_f32_32x32x16_bf16 v[34:49], v[94:97], v[102:105], v[34:49]
	v_mfma_f32_32x32x16_bf16 v[50:65], v[94:97], v[106:109], v[50:65]
	v_mfma_f32_32x32x16_bf16 v[2:17], v[98:101], v[102:105], v[2:17]
	v_mfma_f32_32x32x16_bf16 v[18:33], v[98:101], v[106:109], v[18:33]
	s_waitcnt vmcnt(8)
	s_barrier
	ds_read_b128 v[94:97], v86 offset:2048
	ds_read_b128 v[98:101], v86 offset:6144
	ds_read_b128 v[102:105], v90 offset:2048
	ds_read_b128 v[106:109], v90 offset:6144
	v_mfma_f32_32x32x16_bf16 v[34:49], v[110:113], v[118:121], v[34:49]
	v_mfma_f32_32x32x16_bf16 v[50:65], v[110:113], v[122:125], v[50:65]
	v_mfma_f32_32x32x16_bf16 v[2:17], v[114:117], v[118:121], v[2:17]
	v_mfma_f32_32x32x16_bf16 v[18:33], v[114:117], v[122:125], v[18:33]
	ds_read_b128 v[110:113], v87 offset:2048
	ds_read_b128 v[114:117], v87 offset:6144
	ds_read_b128 v[118:121], v91 offset:2048
	ds_read_b128 v[122:125], v91 offset:6144
	v_mfma_f32_32x32x16_bf16 v[34:49], v[126:129], v[134:137], v[34:49]
	v_mfma_f32_32x32x16_bf16 v[50:65], v[126:129], v[138:141], v[50:65]
	v_mfma_f32_32x32x16_bf16 v[2:17], v[130:133], v[134:137], v[2:17]
	v_mfma_f32_32x32x16_bf16 v[18:33], v[130:133], v[138:141], v[18:33]
	ds_read_b128 v[126:129], v88 offset:2048
	ds_read_b128 v[130:133], v88 offset:6144
	ds_read_b128 v[134:137], v92 offset:2048
	ds_read_b128 v[138:141], v92 offset:6144
	v_mfma_f32_32x32x16_bf16 v[34:49], v[142:145], v[150:153], v[34:49]
	v_mfma_f32_32x32x16_bf16 v[50:65], v[142:145], v[154:157], v[50:65]
	v_mfma_f32_32x32x16_bf16 v[2:17], v[146:149], v[150:153], v[2:17]
	v_mfma_f32_32x32x16_bf16 v[18:33], v[146:149], v[154:157], v[18:33]
	ds_read_b128 v[142:145], v89 offset:2048
	ds_read_b128 v[146:149], v89 offset:6144
	ds_read_b128 v[150:153], v93 offset:2048
	ds_read_b128 v[154:157], v93 offset:6144
	s_waitcnt lgkmcnt(0)
	s_barrier
	s_add_u32 m0, s14, 0x100
	s_nop 0
	global_load_lds_dwordx4 v[68:69], off offset:1792
	s_add_u32 m0, s14, 0x1100
	s_nop 0
	global_load_lds_dwordx4 v[72:73], off offset:1792
	s_add_u32 m0, s14, 0x2100
	s_nop 0
	global_load_lds_dwordx4 v[76:77], off offset:1792
	s_add_u32 m0, s14, 0x3100
	s_nop 0
	global_load_lds_dwordx4 v[80:81], off offset:1792
	s_add_u32 m0, s14, 0x4100
	s_nop 0
	global_load_lds_dwordx4 v[70:71], off offset:1792
	s_add_u32 m0, s14, 0x5100
	s_nop 0
	global_load_lds_dwordx4 v[74:75], off offset:1792
	s_add_u32 m0, s14, 0x6100
	s_nop 0
	global_load_lds_dwordx4 v[78:79], off offset:1792
	s_add_u32 m0, s14, 0x7100
	s_nop 0
	global_load_lds_dwordx4 v[82:83], off offset:1792
	v_mfma_f32_32x32x16_bf16 v[34:49], v[94:97], v[102:105], v[34:49]
	v_mfma_f32_32x32x16_bf16 v[50:65], v[94:97], v[106:109], v[50:65]
	v_mfma_f32_32x32x16_bf16 v[2:17], v[98:101], v[102:105], v[2:17]
	v_mfma_f32_32x32x16_bf16 v[18:33], v[98:101], v[106:109], v[18:33]
	s_waitcnt vmcnt(8)
	s_barrier
	ds_read_b128 v[94:97], v86 offset:34816
	ds_read_b128 v[98:101], v86 offset:38912
	ds_read_b128 v[102:105], v90 offset:34816
	ds_read_b128 v[106:109], v90 offset:38912
	v_mfma_f32_32x32x16_bf16 v[34:49], v[110:113], v[118:121], v[34:49]
	v_mfma_f32_32x32x16_bf16 v[50:65], v[110:113], v[122:125], v[50:65]
	v_mfma_f32_32x32x16_bf16 v[2:17], v[114:117], v[118:121], v[2:17]
	v_mfma_f32_32x32x16_bf16 v[18:33], v[114:117], v[122:125], v[18:33]
	ds_read_b128 v[110:113], v87 offset:34816
	ds_read_b128 v[114:117], v87 offset:38912
	ds_read_b128 v[118:121], v91 offset:34816
	ds_read_b128 v[122:125], v91 offset:38912
	v_mfma_f32_32x32x16_bf16 v[34:49], v[126:129], v[134:137], v[34:49]
	v_mfma_f32_32x32x16_bf16 v[50:65], v[126:129], v[138:141], v[50:65]
	v_mfma_f32_32x32x16_bf16 v[2:17], v[130:133], v[134:137], v[2:17]
	v_mfma_f32_32x32x16_bf16 v[18:33], v[130:133], v[138:141], v[18:33]
	ds_read_b128 v[126:129], v88 offset:34816
	ds_read_b128 v[130:133], v88 offset:38912
	ds_read_b128 v[134:137], v92 offset:34816
	ds_read_b128 v[138:141], v92 offset:38912
	v_mfma_f32_32x32x16_bf16 v[34:49], v[142:145], v[150:153], v[34:49]
	v_mfma_f32_32x32x16_bf16 v[50:65], v[142:145], v[154:157], v[50:65]
	v_mfma_f32_32x32x16_bf16 v[2:17], v[146:149], v[150:153], v[2:17]
	v_mfma_f32_32x32x16_bf16 v[18:33], v[146:149], v[154:157], v[18:33]
	ds_read_b128 v[142:145], v89 offset:34816
	ds_read_b128 v[146:149], v89 offset:38912
	ds_read_b128 v[150:153], v93 offset:34816
	ds_read_b128 v[154:157], v93 offset:38912
	s_waitcnt lgkmcnt(0)
	s_barrier
	s_add_u32 m0, s14, 0x8080
	s_nop 0
	global_load_lds_dwordx4 v[68:69], off offset:1920
	s_add_u32 m0, s14, 0x9080
	s_nop 0
	global_load_lds_dwordx4 v[72:73], off offset:1920
	s_add_u32 m0, s14, 0xa080
	s_nop 0
	global_load_lds_dwordx4 v[76:77], off offset:1920
	s_add_u32 m0, s14, 0xb080
	s_nop 0
	global_load_lds_dwordx4 v[80:81], off offset:1920
	s_add_u32 m0, s14, 0xc080
	s_nop 0
	global_load_lds_dwordx4 v[70:71], off offset:1920
	s_add_u32 m0, s14, 0xd080
	s_nop 0
	global_load_lds_dwordx4 v[74:75], off offset:1920
	s_add_u32 m0, s14, 0xe080
	s_nop 0
	global_load_lds_dwordx4 v[78:79], off offset:1920
	s_add_u32 m0, s14, 0xf080
	s_nop 0
	global_load_lds_dwordx4 v[82:83], off offset:1920
	v_mfma_f32_32x32x16_bf16 v[34:49], v[94:97], v[102:105], v[34:49]
	v_mfma_f32_32x32x16_bf16 v[50:65], v[94:97], v[106:109], v[50:65]
	v_mfma_f32_32x32x16_bf16 v[2:17], v[98:101], v[102:105], v[2:17]
	v_mfma_f32_32x32x16_bf16 v[18:33], v[98:101], v[106:109], v[18:33]
	s_waitcnt vmcnt(8)
	s_barrier
	ds_read_b128 v[94:97], v86 offset:2048
	ds_read_b128 v[98:101], v86 offset:6144
	ds_read_b128 v[102:105], v90 offset:2048
	ds_read_b128 v[106:109], v90 offset:6144
	v_mfma_f32_32x32x16_bf16 v[34:49], v[110:113], v[118:121], v[34:49]
	v_mfma_f32_32x32x16_bf16 v[50:65], v[110:113], v[122:125], v[50:65]
	v_mfma_f32_32x32x16_bf16 v[2:17], v[114:117], v[118:121], v[2:17]
	v_mfma_f32_32x32x16_bf16 v[18:33], v[114:117], v[122:125], v[18:33]
	ds_read_b128 v[110:113], v87 offset:2048
	ds_read_b128 v[114:117], v87 offset:6144
	ds_read_b128 v[118:121], v91 offset:2048
	ds_read_b128 v[122:125], v91 offset:6144
	v_mfma_f32_32x32x16_bf16 v[34:49], v[126:129], v[134:137], v[34:49]
	v_mfma_f32_32x32x16_bf16 v[50:65], v[126:129], v[138:141], v[50:65]
	v_mfma_f32_32x32x16_bf16 v[2:17], v[130:133], v[134:137], v[2:17]
	v_mfma_f32_32x32x16_bf16 v[18:33], v[130:133], v[138:141], v[18:33]
	ds_read_b128 v[126:129], v88 offset:2048
	ds_read_b128 v[130:133], v88 offset:6144
	ds_read_b128 v[134:137], v92 offset:2048
	ds_read_b128 v[138:141], v92 offset:6144
	v_mfma_f32_32x32x16_bf16 v[34:49], v[142:145], v[150:153], v[34:49]
	v_mfma_f32_32x32x16_bf16 v[50:65], v[142:145], v[154:157], v[50:65]
	v_mfma_f32_32x32x16_bf16 v[2:17], v[146:149], v[150:153], v[2:17]
	v_mfma_f32_32x32x16_bf16 v[18:33], v[146:149], v[154:157], v[18:33]
	ds_read_b128 v[142:145], v89 offset:2048
	ds_read_b128 v[146:149], v89 offset:6144
	ds_read_b128 v[150:153], v93 offset:2048
	ds_read_b128 v[154:157], v93 offset:6144
	s_waitcnt lgkmcnt(0)
	v_mfma_f32_32x32x16_bf16 v[34:49], v[94:97], v[102:105], v[34:49]
	v_mfma_f32_32x32x16_bf16 v[50:65], v[94:97], v[106:109], v[50:65]
	v_mfma_f32_32x32x16_bf16 v[2:17], v[98:101], v[102:105], v[2:17]
	v_mfma_f32_32x32x16_bf16 v[18:33], v[98:101], v[106:109], v[18:33]
	s_waitcnt vmcnt(0)
	s_barrier
	ds_read_b128 v[94:97], v86 offset:34816
	ds_read_b128 v[98:101], v86 offset:38912
	ds_read_b128 v[102:105], v90 offset:34816
	ds_read_b128 v[106:109], v90 offset:38912
	v_mfma_f32_32x32x16_bf16 v[34:49], v[110:113], v[118:121], v[34:49]
	v_mfma_f32_32x32x16_bf16 v[50:65], v[110:113], v[122:125], v[50:65]
	v_mfma_f32_32x32x16_bf16 v[2:17], v[114:117], v[118:121], v[2:17]
	v_mfma_f32_32x32x16_bf16 v[18:33], v[114:117], v[122:125], v[18:33]
	ds_read_b128 v[110:113], v87 offset:34816
	ds_read_b128 v[114:117], v87 offset:38912
	ds_read_b128 v[118:121], v91 offset:34816
	ds_read_b128 v[122:125], v91 offset:38912
	v_mfma_f32_32x32x16_bf16 v[34:49], v[126:129], v[134:137], v[34:49]
	v_mfma_f32_32x32x16_bf16 v[50:65], v[126:129], v[138:141], v[50:65]
	v_mfma_f32_32x32x16_bf16 v[2:17], v[130:133], v[134:137], v[2:17]
	v_mfma_f32_32x32x16_bf16 v[18:33], v[130:133], v[138:141], v[18:33]
	ds_read_b128 v[126:129], v88 offset:34816
	ds_read_b128 v[130:133], v88 offset:38912
	ds_read_b128 v[134:137], v92 offset:34816
	ds_read_b128 v[138:141], v92 offset:38912
	v_mfma_f32_32x32x16_bf16 v[34:49], v[142:145], v[150:153], v[34:49]
	v_mfma_f32_32x32x16_bf16 v[50:65], v[142:145], v[154:157], v[50:65]
	v_mfma_f32_32x32x16_bf16 v[2:17], v[146:149], v[150:153], v[2:17]
	v_mfma_f32_32x32x16_bf16 v[18:33], v[146:149], v[154:157], v[18:33]
	ds_read_b128 v[142:145], v89 offset:34816
	ds_read_b128 v[146:149], v89 offset:38912
	ds_read_b128 v[150:153], v93 offset:34816
	ds_read_b128 v[154:157], v93 offset:38912
	s_waitcnt lgkmcnt(0)
	v_mfma_f32_32x32x16_bf16 v[34:49], v[94:97], v[102:105], v[34:49]
	v_mfma_f32_32x32x16_bf16 v[50:65], v[94:97], v[106:109], v[50:65]
	v_mfma_f32_32x32x16_bf16 v[2:17], v[98:101], v[102:105], v[2:17]
	v_mfma_f32_32x32x16_bf16 v[18:33], v[98:101], v[106:109], v[18:33]
	v_mfma_f32_32x32x16_bf16 v[34:49], v[110:113], v[118:121], v[34:49]
	v_mfma_f32_32x32x16_bf16 v[50:65], v[110:113], v[122:125], v[50:65]
	v_mfma_f32_32x32x16_bf16 v[2:17], v[114:117], v[118:121], v[2:17]
	v_mfma_f32_32x32x16_bf16 v[18:33], v[114:117], v[122:125], v[18:33]
	v_mfma_f32_32x32x16_bf16 v[34:49], v[126:129], v[134:137], v[34:49]
	v_mfma_f32_32x32x16_bf16 v[50:65], v[126:129], v[138:141], v[50:65]
	v_mfma_f32_32x32x16_bf16 v[2:17], v[130:133], v[134:137], v[2:17]
	v_mfma_f32_32x32x16_bf16 v[18:33], v[130:133], v[138:141], v[18:33]
	v_mfma_f32_32x32x16_bf16 v[34:49], v[142:145], v[150:153], v[34:49]
	v_mfma_f32_32x32x16_bf16 v[50:65], v[142:145], v[154:157], v[50:65]
	v_mfma_f32_32x32x16_bf16 v[2:17], v[146:149], v[150:153], v[2:17]
	v_mfma_f32_32x32x16_bf16 v[18:33], v[146:149], v[154:157], v[18:33]
	v_mov_b32_e32 v66, v178
	s_waitcnt lgkmcnt(0)
	s_barrier
	s_nop 0
	v_lshrrev_b32_e32 v0, 1, v66
	v_and_b32_e32 v0, 0xfffffc0, v0
	v_lshrrev_b32_e32 v67, 3, v66
	v_and_or_b32 v0, v67, 4, v0
	v_and_b32_e32 v67, 0x5f, v66
	v_mul_lo_u32 v0, v0, s83
	v_lshl_add_u32 v0, v67, 2, v0
	s_nop 0
	s_nop 11
	ds_write2_b32 v0, v34, v50 offset1:32
	ds_write2_b32 v0, v35, v51 offset0:132 offset1:164
	s_nop 0
	v_add_u32_e32 v34, 0x400, v0
	ds_write2_b32 v34, v36, v52 offset0:8 offset1:40
	ds_write2_b32 v34, v37, v53 offset0:140 offset1:172
	v_add_u32_e32 v34, 0x1000, v0
	ds_write2_b32 v34, v38, v54 offset0:32 offset1:64
	ds_write2_b32 v34, v39, v55 offset0:164 offset1:196
	v_add_u32_e32 v34, 0x1400, v0
	ds_write2_b32 v34, v40, v56 offset0:40 offset1:72
	ds_write2_b32 v34, v41, v57 offset0:172 offset1:204
	v_add_u32_e32 v34, 0x2000, v0
	s_nop 0
	ds_write2_b32 v34, v42, v58 offset0:64 offset1:96
	ds_write2_b32 v34, v43, v59 offset0:196 offset1:228
	v_add_u32_e32 v34, 0x2400, v0
	ds_write2_b32 v34, v44, v60 offset0:72 offset1:104
	ds_write2_b32 v34, v45, v61 offset0:204 offset1:236
	v_add_u32_e32 v34, 0x3000, v0
	ds_write2_b32 v34, v46, v62 offset0:96 offset1:128
	v_add_u32_e32 v34, 0x3200, v0
	ds_write2_b32 v34, v47, v63 offset0:100 offset1:132
	s_nop 0
	v_add_u32_e32 v34, 0x3400, v0
	ds_write2_b32 v34, v48, v64 offset0:104 offset1:136
	v_add_u32_e32 v34, 0x3600, v0
	ds_write2_b32 v34, v49, v65 offset0:108 offset1:140
	v_add_u32_e32 v34, 0x4000, v0
	s_nop 0
	s_nop 11
	ds_write2_b32 v34, v2, v18 offset0:128 offset1:160
	v_add_u32_e32 v2, 0x4400, v0
	ds_write2_b32 v2, v3, v19 offset0:4 offset1:36
	ds_write2_b32 v2, v4, v20 offset0:136 offset1:168
	v_add_u32_e32 v2, 0x4800, v0
	ds_write2_b32 v2, v5, v21 offset0:12 offset1:44
	v_add_u32_e32 v2, 0x5000, v0
	ds_write2_b32 v2, v6, v22 offset0:160 offset1:192
	v_add_u32_e32 v2, 0x5400, v0
	ds_write2_b32 v2, v7, v23 offset0:36 offset1:68
	ds_write2_b32 v2, v8, v24 offset0:168 offset1:200
	v_add_u32_e32 v2, 0x5800, v0
	ds_write2_b32 v2, v9, v25 offset0:44 offset1:76
	v_add_u32_e32 v2, 0x6000, v0
	ds_write2_b32 v2, v10, v26 offset0:192 offset1:224
	v_add_u32_e32 v2, 0x6400, v0
	ds_write2_b32 v2, v11, v27 offset0:68 offset1:100
	ds_write2_b32 v2, v12, v28 offset0:200 offset1:232
	v_add_u32_e32 v2, 0x6800, v0
	ds_write2_b32 v2, v13, v29 offset0:76 offset1:108
	v_add_u32_e32 v2, 0x7200, v0
	ds_write2_b32 v2, v14, v30 offset0:96 offset1:128
	v_add_u32_e32 v2, 0x7400, v0
	ds_write2_b32 v2, v15, v31 offset0:100 offset1:132
	v_add_u32_e32 v2, 0x7600, v0
	v_add_u32_e32 v0, 0x7800, v0
	ds_write2_b32 v0, v17, v33 offset0:108 offset1:140
	v_lshlrev_b32_e32 v0, 3, v66
	v_and_b32_e32 v0, 0x78, v0
	ds_write2_b32 v2, v16, v32 offset0:104 offset1:136
	v_lshlrev_b32_e32 v2, 2, v0
	v_or_b32_e32 v0, s0, v0
	v_lshlrev_b32_e32 v0, 1, v0
	s_waitcnt lgkmcnt(0)
	s_barrier
	v_lshl_add_u64 v[4:5], s[78:79], 0, v[0:1]

.LBB0_855:
	s_lshl_b32 s0, s45, 10
	s_waitcnt vmcnt(3)
	v_mov_b32_e32 v6, v178
	s_add_i32 s0, s24, s0
	s_ashr_i32 s1, s0, 31
	v_ashrrev_i32_e32 v34, 3, v6
	v_lshlrev_b32_e32 v0, 3, v6
	v_ashrrev_i32_e32 v35, 31, v34
	s_lshl_b64 s[0:1], s[0:1], 11
	v_and_b32_e32 v36, 56, v0
	v_lshlrev_b64 v[2:3], 11, v[34:35]
	s_add_u32 s0, s92, s0
	v_lshl_add_u64 v[4:5], s[40:41], 0, v[2:3]
	v_lshlrev_b32_e32 v0, 1, v36
	s_addc_u32 s1, s93, s1
	v_lshl_add_u64 v[148:149], v[4:5], 0, v[0:1]
	v_lshl_add_u64 v[2:3], s[0:1], 0, v[2:3]
	v_lshl_add_u64 v[150:151], v[2:3], 0, v[0:1]
	v_and_b32_e32 v0, 7, v178
	v_bfe_u32 v146, v178, 4, 3
	v_xor_b32_e32 v146, v146, v0
	v_sub_u32_e32 v146, v146, v0
	v_lshlrev_b32_e32 v146, 4, v146
	v_ashrrev_i32_e32 v147, 31, v146
	v_lshl_add_u64 v[148:149], v[148:149], 0, v[146:147]
	v_lshl_add_u64 v[150:151], v[150:151], 0, v[146:147]
	v_add_co_u32_e32 v152, vcc, s73, v148
	s_nop 1
	v_addc_co_u32_e32 v153, vcc, 0, v149, vcc
	v_add_co_u32_e32 v154, vcc, s73, v150
	s_nop 1
	v_addc_co_u32_e32 v155, vcc, 0, v151, vcc
	v_add_co_u32_e32 v156, vcc, s52, v148
	s_nop 1
	v_addc_co_u32_e32 v157, vcc, 0, v149, vcc
	v_add_co_u32_e32 v158, vcc, s52, v150
	s_nop 1
	v_addc_co_u32_e32 v159, vcc, 0, v151, vcc
	v_add_co_u32_e32 v160, vcc, s53, v148
	s_nop 1
	v_addc_co_u32_e32 v161, vcc, 0, v149, vcc
	v_add_co_u32_e32 v162, vcc, s53, v150
	s_nop 1
	v_addc_co_u32_e32 v163, vcc, 0, v151, vcc
	v_and_b32_e32 v0, 31, v178
	v_bfe_u32 v146, v178, 5, 1
	v_bfe_u32 v147, v178, 1, 3
	v_xor_b32_e32 v146, v146, v147
	v_lshlrev_b32_e32 v146, 4, v146
	v_lshl_add_u32 v146, v0, 7, v146
	v_bfe_u32 v147, v178, 7, 1
	v_lshl_add_u32 v130, v147, 13, v146
	v_bfe_u32 v147, v178, 6, 1
	v_lshl_add_u32 v134, v147, 13, v146
	v_add_u32_e32 v134, 0x4000, v134
	v_xor_b32_e32 v131, 32, v130
	v_xor_b32_e32 v135, 32, v134
	v_xor_b32_e32 v132, 64, v130
	v_xor_b32_e32 v136, 64, v134
	v_xor_b32_e32 v133, 96, v130
	v_xor_b32_e32 v137, 96, v134
	v_lshrrev_b32_e32 v146, 6, v178
	v_lshlrev_b32_e32 v146, 10, v146
	s_nop 1
	v_readfirstlane_b32 s14, v146
	s_add_u32 m0, s14, 0x800
	s_nop 0
	global_load_lds_dwordx4 v[148:149], off
	s_add_u32 m0, s14, 0x1800
	s_nop 0
	global_load_lds_dwordx4 v[152:153], off
	s_add_u32 m0, s14, 0x2800
	s_nop 0
	global_load_lds_dwordx4 v[156:157], off
	s_add_u32 m0, s14, 0x3800
	s_nop 0
	global_load_lds_dwordx4 v[160:161], off
	s_add_u32 m0, s14, 0x4800
	s_nop 0
	global_load_lds_dwordx4 v[150:151], off
	s_add_u32 m0, s14, 0x5800
	s_nop 0
	global_load_lds_dwordx4 v[154:155], off
	s_add_u32 m0, s14, 0x6800
	s_nop 0
	global_load_lds_dwordx4 v[158:159], off
	s_add_u32 m0, s14, 0x7800
	s_nop 0
	global_load_lds_dwordx4 v[162:163], off
	s_add_u32 m0, s14, 0x8780
	s_nop 0
	global_load_lds_dwordx4 v[148:149], off offset:128
	s_add_u32 m0, s14, 0x9780
	s_nop 0
	global_load_lds_dwordx4 v[152:153], off offset:128
	s_add_u32 m0, s14, 0xa780
	s_nop 0
	global_load_lds_dwordx4 v[156:157], off offset:128
	s_add_u32 m0, s14, 0xb780
	s_nop 0
	global_load_lds_dwordx4 v[160:161], off offset:128
	s_add_u32 m0, s14, 0xc780
	s_nop 0
	global_load_lds_dwordx4 v[150:151], off offset:128
	s_add_u32 m0, s14, 0xd780
	s_nop 0
	global_load_lds_dwordx4 v[154:155], off offset:128
	s_add_u32 m0, s14, 0xe780
	s_nop 0
	global_load_lds_dwordx4 v[158:159], off offset:128
	s_add_u32 m0, s14, 0xf780
	s_nop 0
	global_load_lds_dwordx4 v[162:163], off offset:128
	s_waitcnt vmcnt(8)
	s_barrier
	ds_read_b128 v[66:69], v130 offset:2048
	ds_read_b128 v[70:73], v130 offset:6144
	ds_read_b128 v[74:77], v134 offset:2048
	ds_read_b128 v[78:81], v134 offset:6144
	ds_read_b128 v[82:85], v131 offset:2048
	ds_read_b128 v[86:89], v131 offset:6144
	ds_read_b128 v[90:93], v135 offset:2048
	ds_read_b128 v[94:97], v135 offset:6144
	ds_read_b128 v[98:101], v132 offset:2048
	ds_read_b128 v[102:105], v132 offset:6144
	ds_read_b128 v[106:109], v136 offset:2048
	ds_read_b128 v[110:113], v136 offset:6144
	ds_read_b128 v[114:117], v133 offset:2048
	ds_read_b128 v[118:121], v133 offset:6144
	ds_read_b128 v[122:125], v137 offset:2048
	ds_read_b128 v[126:129], v137 offset:6144
	s_waitcnt lgkmcnt(0)
	s_barrier
	s_add_u32 m0, s14, 0x700
	s_nop 0
	global_load_lds_dwordx4 v[148:149], off offset:256
	s_add_u32 m0, s14, 0x1700
	s_nop 0
	global_load_lds_dwordx4 v[152:153], off offset:256
	s_add_u32 m0, s14, 0x2700
	s_nop 0
	global_load_lds_dwordx4 v[156:157], off offset:256
	s_add_u32 m0, s14, 0x3700
	s_nop 0
	global_load_lds_dwordx4 v[160:161], off offset:256
	s_add_u32 m0, s14, 0x4700
	s_nop 0
	global_load_lds_dwordx4 v[150:151], off offset:256
	s_add_u32 m0, s14, 0x5700
	s_nop 0
	global_load_lds_dwordx4 v[154:155], off offset:256
	s_add_u32 m0, s14, 0x6700
	s_nop 0
	global_load_lds_dwordx4 v[158:159], off offset:256
	s_add_u32 m0, s14, 0x7700
	s_nop 0
	global_load_lds_dwordx4 v[162:163], off offset:256
	v_mfma_f32_32x32x16_bf16 v[50:65], v[66:69], v[74:77], 0
	v_mfma_f32_32x32x16_bf16 v[34:49], v[66:69], v[78:81], 0
	v_mfma_f32_32x32x16_bf16 v[18:33], v[70:73], v[74:77], 0
	v_mfma_f32_32x32x16_bf16 v[2:17], v[70:73], v[78:81], 0
	s_waitcnt vmcnt(8)
	s_barrier
	ds_read_b128 v[66:69], v130 offset:34816
	ds_read_b128 v[70:73], v130 offset:38912
	ds_read_b128 v[74:77], v134 offset:34816
	ds_read_b128 v[78:81], v134 offset:38912
	v_mfma_f32_32x32x16_bf16 v[50:65], v[82:85], v[90:93], v[50:65]
	v_mfma_f32_32x32x16_bf16 v[34:49], v[82:85], v[94:97], v[34:49]
	v_mfma_f32_32x32x16_bf16 v[18:33], v[86:89], v[90:93], v[18:33]
	v_mfma_f32_32x32x16_bf16 v[2:17], v[86:89], v[94:97], v[2:17]
	ds_read_b128 v[82:85], v131 offset:34816
	ds_read_b128 v[86:89], v131 offset:38912
	ds_read_b128 v[90:93], v135 offset:34816
	ds_read_b128 v[94:97], v135 offset:38912
	v_mfma_f32_32x32x16_bf16 v[50:65], v[98:101], v[106:109], v[50:65]
	v_mfma_f32_32x32x16_bf16 v[34:49], v[98:101], v[110:113], v[34:49]
	v_mfma_f32_32x32x16_bf16 v[18:33], v[102:105], v[106:109], v[18:33]
	v_mfma_f32_32x32x16_bf16 v[2:17], v[102:105], v[110:113], v[2:17]
	ds_read_b128 v[98:101], v132 offset:34816
	ds_read_b128 v[102:105], v132 offset:38912
	ds_read_b128 v[106:109], v136 offset:34816
	ds_read_b128 v[110:113], v136 offset:38912
	v_mfma_f32_32x32x16_bf16 v[50:65], v[114:117], v[122:125], v[50:65]
	v_mfma_f32_32x32x16_bf16 v[34:49], v[114:117], v[126:129], v[34:49]
	v_mfma_f32_32x32x16_bf16 v[18:33], v[118:121], v[122:125], v[18:33]
	v_mfma_f32_32x32x16_bf16 v[2:17], v[118:121], v[126:129], v[2:17]
	ds_read_b128 v[114:117], v133 offset:34816
	ds_read_b128 v[118:121], v133 offset:38912
	ds_read_b128 v[122:125], v137 offset:34816
	ds_read_b128 v[126:129], v137 offset:38912
	s_waitcnt lgkmcnt(0)
	s_barrier
	s_add_u32 m0, s14, 0x8680
	s_nop 0
	global_load_lds_dwordx4 v[148:149], off offset:384
	s_add_u32 m0, s14, 0x9680
	s_nop 0
	global_load_lds_dwordx4 v[152:153], off offset:384
	s_add_u32 m0, s14, 0xa680
	s_nop 0
	global_load_lds_dwordx4 v[156:157], off offset:384
	s_add_u32 m0, s14, 0xb680
	s_nop 0
	global_load_lds_dwordx4 v[160:161], off offset:384
	s_add_u32 m0, s14, 0xc680
	s_nop 0
	global_load_lds_dwordx4 v[150:151], off offset:384
	s_add_u32 m0, s14, 0xd680
	s_nop 0
	global_load_lds_dwordx4 v[154:155], off offset:384
	s_add_u32 m0, s14, 0xe680
	s_nop 0
	global_load_lds_dwordx4 v[158:159], off offset:384
	s_add_u32 m0, s14, 0xf680
	s_nop 0
	global_load_lds_dwordx4 v[162:163], off offset:384
	v_mfma_f32_32x32x16_bf16 v[50:65], v[66:69], v[74:77], v[50:65]
	v_mfma_f32_32x32x16_bf16 v[34:49], v[66:69], v[78:81], v[34:49]
	v_mfma_f32_32x32x16_bf16 v[18:33], v[70:73], v[74:77], v[18:33]
	v_mfma_f32_32x32x16_bf16 v[2:17], v[70:73], v[78:81], v[2:17]
	s_waitcnt vmcnt(8)
	s_barrier
	ds_read_b128 v[66:69], v130 offset:2048
	ds_read_b128 v[70:73], v130 offset:6144
	ds_read_b128 v[74:77], v134 offset:2048
	ds_read_b128 v[78:81], v134 offset:6144
	v_mfma_f32_32x32x16_bf16 v[50:65], v[82:85], v[90:93], v[50:65]
	v_mfma_f32_32x32x16_bf16 v[34:49], v[82:85], v[94:97], v[34:49]
	v_mfma_f32_32x32x16_bf16 v[18:33], v[86:89], v[90:93], v[18:33]
	v_mfma_f32_32x32x16_bf16 v[2:17], v[86:89], v[94:97], v[2:17]
	ds_read_b128 v[82:85], v131 offset:2048
	ds_read_b128 v[86:89], v131 offset:6144
	ds_read_b128 v[90:93], v135 offset:2048
	ds_read_b128 v[94:97], v135 offset:6144
	v_mfma_f32_32x32x16_bf16 v[50:65], v[98:101], v[106:109], v[50:65]
	v_mfma_f32_32x32x16_bf16 v[34:49], v[98:101], v[110:113], v[34:49]
	v_mfma_f32_32x32x16_bf16 v[18:33], v[102:105], v[106:109], v[18:33]
	v_mfma_f32_32x32x16_bf16 v[2:17], v[102:105], v[110:113], v[2:17]
	ds_read_b128 v[98:101], v132 offset:2048
	ds_read_b128 v[102:105], v132 offset:6144
	ds_read_b128 v[106:109], v136 offset:2048
	ds_read_b128 v[110:113], v136 offset:6144
	v_mfma_f32_32x32x16_bf16 v[50:65], v[114:117], v[122:125], v[50:65]
	v_mfma_f32_32x32x16_bf16 v[34:49], v[114:117], v[126:129], v[34:49]
	v_mfma_f32_32x32x16_bf16 v[18:33], v[118:121], v[122:125], v[18:33]
	v_mfma_f32_32x32x16_bf16 v[2:17], v[118:121], v[126:129], v[2:17]
	ds_read_b128 v[114:117], v133 offset:2048
	ds_read_b128 v[118:121], v133 offset:6144
	ds_read_b128 v[122:125], v137 offset:2048
	ds_read_b128 v[126:129], v137 offset:6144
	s_waitcnt lgkmcnt(0)
	s_barrier
	s_add_u32 m0, s14, 0x600
	s_nop 0
	global_load_lds_dwordx4 v[148:149], off offset:512
	s_add_u32 m0, s14, 0x1600
	s_nop 0
	global_load_lds_dwordx4 v[152:153], off offset:512
	s_add_u32 m0, s14, 0x2600
	s_nop 0
	global_load_lds_dwordx4 v[156:157], off offset:512
	s_add_u32 m0, s14, 0x3600
	s_nop 0
	global_load_lds_dwordx4 v[160:161], off offset:512
	s_add_u32 m0, s14, 0x4600
	s_nop 0
	global_load_lds_dwordx4 v[150:151], off offset:512
	s_add_u32 m0, s14, 0x5600
	s_nop 0
	global_load_lds_dwordx4 v[154:155], off offset:512
	s_add_u32 m0, s14, 0x6600
	s_nop 0
	global_load_lds_dwordx4 v[158:159], off offset:512
	s_add_u32 m0, s14, 0x7600
	s_nop 0
	global_load_lds_dwordx4 v[162:163], off offset:512
	v_mfma_f32_32x32x16_bf16 v[50:65], v[66:69], v[74:77], v[50:65]
	v_mfma_f32_32x32x16_bf16 v[34:49], v[66:69], v[78:81], v[34:49]
	v_mfma_f32_32x32x16_bf16 v[18:33], v[70:73], v[74:77], v[18:33]
	v_mfma_f32_32x32x16_bf16 v[2:17], v[70:73], v[78:81], v[2:17]
	s_waitcnt vmcnt(8)
	s_barrier
	ds_read_b128 v[66:69], v130 offset:34816
	ds_read_b128 v[70:73], v130 offset:38912
	ds_read_b128 v[74:77], v134 offset:34816
	ds_read_b128 v[78:81], v134 offset:38912
	v_mfma_f32_32x32x16_bf16 v[50:65], v[82:85], v[90:93], v[50:65]
	v_mfma_f32_32x32x16_bf16 v[34:49], v[82:85], v[94:97], v[34:49]
	v_mfma_f32_32x32x16_bf16 v[18:33], v[86:89], v[90:93], v[18:33]
	v_mfma_f32_32x32x16_bf16 v[2:17], v[86:89], v[94:97], v[2:17]
	ds_read_b128 v[82:85], v131 offset:34816
	ds_read_b128 v[86:89], v131 offset:38912
	ds_read_b128 v[90:93], v135 offset:34816
	ds_read_b128 v[94:97], v135 offset:38912
	v_mfma_f32_32x32x16_bf16 v[50:65], v[98:101], v[106:109], v[50:65]
	v_mfma_f32_32x32x16_bf16 v[34:49], v[98:101], v[110:113], v[34:49]
	v_mfma_f32_32x32x16_bf16 v[18:33], v[102:105], v[106:109], v[18:33]
	v_mfma_f32_32x32x16_bf16 v[2:17], v[102:105], v[110:113], v[2:17]
	ds_read_b128 v[98:101], v132 offset:34816
	ds_read_b128 v[102:105], v132 offset:38912
	ds_read_b128 v[106:109], v136 offset:34816
	ds_read_b128 v[110:113], v136 offset:38912
	v_mfma_f32_32x32x16_bf16 v[50:65], v[114:117], v[122:125], v[50:65]
	v_mfma_f32_32x32x16_bf16 v[34:49], v[114:117], v[126:129], v[34:49]
	v_mfma_f32_32x32x16_bf16 v[18:33], v[118:121], v[122:125], v[18:33]
	v_mfma_f32_32x32x16_bf16 v[2:17], v[118:121], v[126:129], v[2:17]
	ds_read_b128 v[114:117], v133 offset:34816
	ds_read_b128 v[118:121], v133 offset:38912
	ds_read_b128 v[122:125], v137 offset:34816
	ds_read_b128 v[126:129], v137 offset:38912
	s_waitcnt lgkmcnt(0)
	s_barrier
	s_add_u32 m0, s14, 0x8580
	s_nop 0
	global_load_lds_dwordx4 v[148:149], off offset:640
	s_add_u32 m0, s14, 0x9580
	s_nop 0
	global_load_lds_dwordx4 v[152:153], off offset:640
	s_add_u32 m0, s14, 0xa580
	s_nop 0
	global_load_lds_dwordx4 v[156:157], off offset:640
	s_add_u32 m0, s14, 0xb580
	s_nop 0
	global_load_lds_dwordx4 v[160:161], off offset:640
	s_add_u32 m0, s14, 0xc580
	s_nop 0
	global_load_lds_dwordx4 v[150:151], off offset:640
	s_add_u32 m0, s14, 0xd580
	s_nop 0
	global_load_lds_dwordx4 v[154:155], off offset:640
	s_add_u32 m0, s14, 0xe580
	s_nop 0
	global_load_lds_dwordx4 v[158:159], off offset:640
	s_add_u32 m0, s14, 0xf580
	s_nop 0
	global_load_lds_dwordx4 v[162:163], off offset:640
	v_mfma_f32_32x32x16_bf16 v[50:65], v[66:69], v[74:77], v[50:65]
	v_mfma_f32_32x32x16_bf16 v[34:49], v[66:69], v[78:81], v[34:49]
	v_mfma_f32_32x32x16_bf16 v[18:33], v[70:73], v[74:77], v[18:33]
	v_mfma_f32_32x32x16_bf16 v[2:17], v[70:73], v[78:81], v[2:17]
	s_waitcnt vmcnt(8)
	s_barrier
	ds_read_b128 v[66:69], v130 offset:2048
	ds_read_b128 v[70:73], v130 offset:6144
	ds_read_b128 v[74:77], v134 offset:2048
	ds_read_b128 v[78:81], v134 offset:6144
	v_mfma_f32_32x32x16_bf16 v[50:65], v[82:85], v[90:93], v[50:65]
	v_mfma_f32_32x32x16_bf16 v[34:49], v[82:85], v[94:97], v[34:49]
	v_mfma_f32_32x32x16_bf16 v[18:33], v[86:89], v[90:93], v[18:33]
	v_mfma_f32_32x32x16_bf16 v[2:17], v[86:89], v[94:97], v[2:17]
	ds_read_b128 v[82:85], v131 offset:2048
	ds_read_b128 v[86:89], v131 offset:6144
	ds_read_b128 v[90:93], v135 offset:2048
	ds_read_b128 v[94:97], v135 offset:6144
	v_mfma_f32_32x32x16_bf16 v[50:65], v[98:101], v[106:109], v[50:65]
	v_mfma_f32_32x32x16_bf16 v[34:49], v[98:101], v[110:113], v[34:49]
	v_mfma_f32_32x32x16_bf16 v[18:33], v[102:105], v[106:109], v[18:33]
	v_mfma_f32_32x32x16_bf16 v[2:17], v[102:105], v[110:113], v[2:17]
	ds_read_b128 v[98:101], v132 offset:2048
	ds_read_b128 v[102:105], v132 offset:6144
	ds_read_b128 v[106:109], v136 offset:2048
	ds_read_b128 v[110:113], v136 offset:6144
	v_mfma_f32_32x32x16_bf16 v[50:65], v[114:117], v[122:125], v[50:65]
	v_mfma_f32_32x32x16_bf16 v[34:49], v[114:117], v[126:129], v[34:49]
	v_mfma_f32_32x32x16_bf16 v[18:33], v[118:121], v[122:125], v[18:33]
	v_mfma_f32_32x32x16_bf16 v[2:17], v[118:121], v[126:129], v[2:17]
	ds_read_b128 v[114:117], v133 offset:2048
	ds_read_b128 v[118:121], v133 offset:6144
	ds_read_b128 v[122:125], v137 offset:2048
	ds_read_b128 v[126:129], v137 offset:6144
	s_waitcnt lgkmcnt(0)
	s_barrier
	s_add_u32 m0, s14, 0x500
	s_nop 0
	global_load_lds_dwordx4 v[148:149], off offset:768
	s_add_u32 m0, s14, 0x1500
	s_nop 0
	global_load_lds_dwordx4 v[152:153], off offset:768
	s_add_u32 m0, s14, 0x2500
	s_nop 0
	global_load_lds_dwordx4 v[156:157], off offset:768
	s_add_u32 m0, s14, 0x3500
	s_nop 0
	global_load_lds_dwordx4 v[160:161], off offset:768
	s_add_u32 m0, s14, 0x4500
	s_nop 0
	global_load_lds_dwordx4 v[150:151], off offset:768
	s_add_u32 m0, s14, 0x5500
	s_nop 0
	global_load_lds_dwordx4 v[154:155], off offset:768
	s_add_u32 m0, s14, 0x6500
	s_nop 0
	global_load_lds_dwordx4 v[158:159], off offset:768
	s_add_u32 m0, s14, 0x7500
	s_nop 0
	global_load_lds_dwordx4 v[162:163], off offset:768
	v_mfma_f32_32x32x16_bf16 v[50:65], v[66:69], v[74:77], v[50:65]
	v_mfma_f32_32x32x16_bf16 v[34:49], v[66:69], v[78:81], v[34:49]
	v_mfma_f32_32x32x16_bf16 v[18:33], v[70:73], v[74:77], v[18:33]
	v_mfma_f32_32x32x16_bf16 v[2:17], v[70:73], v[78:81], v[2:17]
	s_waitcnt vmcnt(8)
	s_barrier
	ds_read_b128 v[66:69], v130 offset:34816
	ds_read_b128 v[70:73], v130 offset:38912
	ds_read_b128 v[74:77], v134 offset:34816
	ds_read_b128 v[78:81], v134 offset:38912
	v_mfma_f32_32x32x16_bf16 v[50:65], v[82:85], v[90:93], v[50:65]
	v_mfma_f32_32x32x16_bf16 v[34:49], v[82:85], v[94:97], v[34:49]
	v_mfma_f32_32x32x16_bf16 v[18:33], v[86:89], v[90:93], v[18:33]
	v_mfma_f32_32x32x16_bf16 v[2:17], v[86:89], v[94:97], v[2:17]
	ds_read_b128 v[82:85], v131 offset:34816
	ds_read_b128 v[86:89], v131 offset:38912
	ds_read_b128 v[90:93], v135 offset:34816
	ds_read_b128 v[94:97], v135 offset:38912
	v_mfma_f32_32x32x16_bf16 v[50:65], v[98:101], v[106:109], v[50:65]
	v_mfma_f32_32x32x16_bf16 v[34:49], v[98:101], v[110:113], v[34:49]
	v_mfma_f32_32x32x16_bf16 v[18:33], v[102:105], v[106:109], v[18:33]
	v_mfma_f32_32x32x16_bf16 v[2:17], v[102:105], v[110:113], v[2:17]
	ds_read_b128 v[98:101], v132 offset:34816
	ds_read_b128 v[102:105], v132 offset:38912
	ds_read_b128 v[106:109], v136 offset:34816
	ds_read_b128 v[110:113], v136 offset:38912
	v_mfma_f32_32x32x16_bf16 v[50:65], v[114:117], v[122:125], v[50:65]
	v_mfma_f32_32x32x16_bf16 v[34:49], v[114:117], v[126:129], v[34:49]
	v_mfma_f32_32x32x16_bf16 v[18:33], v[118:121], v[122:125], v[18:33]
	v_mfma_f32_32x32x16_bf16 v[2:17], v[118:121], v[126:129], v[2:17]
	ds_read_b128 v[114:117], v133 offset:34816
	ds_read_b128 v[118:121], v133 offset:38912
	ds_read_b128 v[122:125], v137 offset:34816
	ds_read_b128 v[126:129], v137 offset:38912
	s_waitcnt lgkmcnt(0)
	s_barrier
	s_add_u32 m0, s14, 0x8480
	s_nop 0
	global_load_lds_dwordx4 v[148:149], off offset:896
	s_add_u32 m0, s14, 0x9480
	s_nop 0
	global_load_lds_dwordx4 v[152:153], off offset:896
	s_add_u32 m0, s14, 0xa480
	s_nop 0
	global_load_lds_dwordx4 v[156:157], off offset:896
	s_add_u32 m0, s14, 0xb480
	s_nop 0
	global_load_lds_dwordx4 v[160:161], off offset:896
	s_add_u32 m0, s14, 0xc480
	s_nop 0
	global_load_lds_dwordx4 v[150:151], off offset:896
	s_add_u32 m0, s14, 0xd480
	s_nop 0
	global_load_lds_dwordx4 v[154:155], off offset:896
	s_add_u32 m0, s14, 0xe480
	s_nop 0
	global_load_lds_dwordx4 v[158:159], off offset:896
	s_add_u32 m0, s14, 0xf480
	s_nop 0
	global_load_lds_dwordx4 v[162:163], off offset:896
	v_mfma_f32_32x32x16_bf16 v[50:65], v[66:69], v[74:77], v[50:65]
	v_mfma_f32_32x32x16_bf16 v[34:49], v[66:69], v[78:81], v[34:49]
	v_mfma_f32_32x32x16_bf16 v[18:33], v[70:73], v[74:77], v[18:33]
	v_mfma_f32_32x32x16_bf16 v[2:17], v[70:73], v[78:81], v[2:17]
	s_waitcnt vmcnt(8)
	s_barrier
	ds_read_b128 v[66:69], v130 offset:2048
	ds_read_b128 v[70:73], v130 offset:6144
	ds_read_b128 v[74:77], v134 offset:2048
	ds_read_b128 v[78:81], v134 offset:6144
	v_mfma_f32_32x32x16_bf16 v[50:65], v[82:85], v[90:93], v[50:65]
	v_mfma_f32_32x32x16_bf16 v[34:49], v[82:85], v[94:97], v[34:49]
	v_mfma_f32_32x32x16_bf16 v[18:33], v[86:89], v[90:93], v[18:33]
	v_mfma_f32_32x32x16_bf16 v[2:17], v[86:89], v[94:97], v[2:17]
	ds_read_b128 v[82:85], v131 offset:2048
	ds_read_b128 v[86:89], v131 offset:6144
	ds_read_b128 v[90:93], v135 offset:2048
	ds_read_b128 v[94:97], v135 offset:6144
	v_mfma_f32_32x32x16_bf16 v[50:65], v[98:101], v[106:109], v[50:65]
	v_mfma_f32_32x32x16_bf16 v[34:49], v[98:101], v[110:113], v[34:49]
	v_mfma_f32_32x32x16_bf16 v[18:33], v[102:105], v[106:109], v[18:33]
	v_mfma_f32_32x32x16_bf16 v[2:17], v[102:105], v[110:113], v[2:17]
	ds_read_b128 v[98:101], v132 offset:2048
	ds_read_b128 v[102:105], v132 offset:6144
	ds_read_b128 v[106:109], v136 offset:2048
	ds_read_b128 v[110:113], v136 offset:6144
	v_mfma_f32_32x32x16_bf16 v[50:65], v[114:117], v[122:125], v[50:65]
	v_mfma_f32_32x32x16_bf16 v[34:49], v[114:117], v[126:129], v[34:49]
	v_mfma_f32_32x32x16_bf16 v[18:33], v[118:121], v[122:125], v[18:33]
	v_mfma_f32_32x32x16_bf16 v[2:17], v[118:121], v[126:129], v[2:17]
	ds_read_b128 v[114:117], v133 offset:2048
	ds_read_b128 v[118:121], v133 offset:6144
	ds_read_b128 v[122:125], v137 offset:2048
	ds_read_b128 v[126:129], v137 offset:6144
	s_waitcnt lgkmcnt(0)
	s_barrier
	s_add_u32 m0, s14, 0x400
	s_nop 0
	global_load_lds_dwordx4 v[148:149], off offset:1024
	s_add_u32 m0, s14, 0x1400
	s_nop 0
	global_load_lds_dwordx4 v[152:153], off offset:1024
	s_add_u32 m0, s14, 0x2400
	s_nop 0
	global_load_lds_dwordx4 v[156:157], off offset:1024
	s_add_u32 m0, s14, 0x3400
	s_nop 0
	global_load_lds_dwordx4 v[160:161], off offset:1024
	s_add_u32 m0, s14, 0x4400
	s_nop 0
	global_load_lds_dwordx4 v[150:151], off offset:1024
	s_add_u32 m0, s14, 0x5400
	s_nop 0
	global_load_lds_dwordx4 v[154:155], off offset:1024
	s_add_u32 m0, s14, 0x6400
	s_nop 0
	global_load_lds_dwordx4 v[158:159], off offset:1024
	s_add_u32 m0, s14, 0x7400
	s_nop 0
	global_load_lds_dwordx4 v[162:163], off offset:1024
	v_mfma_f32_32x32x16_bf16 v[50:65], v[66:69], v[74:77], v[50:65]
	v_mfma_f32_32x32x16_bf16 v[34:49], v[66:69], v[78:81], v[34:49]
	v_mfma_f32_32x32x16_bf16 v[18:33], v[70:73], v[74:77], v[18:33]
	v_mfma_f32_32x32x16_bf16 v[2:17], v[70:73], v[78:81], v[2:17]
	s_waitcnt vmcnt(8)
	s_barrier
	ds_read_b128 v[66:69], v130 offset:34816
	ds_read_b128 v[70:73], v130 offset:38912
	ds_read_b128 v[74:77], v134 offset:34816
	ds_read_b128 v[78:81], v134 offset:38912
	v_mfma_f32_32x32x16_bf16 v[50:65], v[82:85], v[90:93], v[50:65]
	v_mfma_f32_32x32x16_bf16 v[34:49], v[82:85], v[94:97], v[34:49]
	v_mfma_f32_32x32x16_bf16 v[18:33], v[86:89], v[90:93], v[18:33]
	v_mfma_f32_32x32x16_bf16 v[2:17], v[86:89], v[94:97], v[2:17]
	ds_read_b128 v[82:85], v131 offset:34816
	ds_read_b128 v[86:89], v131 offset:38912
	ds_read_b128 v[90:93], v135 offset:34816
	ds_read_b128 v[94:97], v135 offset:38912
	v_mfma_f32_32x32x16_bf16 v[50:65], v[98:101], v[106:109], v[50:65]
	v_mfma_f32_32x32x16_bf16 v[34:49], v[98:101], v[110:113], v[34:49]
	v_mfma_f32_32x32x16_bf16 v[18:33], v[102:105], v[106:109], v[18:33]
	v_mfma_f32_32x32x16_bf16 v[2:17], v[102:105], v[110:113], v[2:17]
	ds_read_b128 v[98:101], v132 offset:34816
	ds_read_b128 v[102:105], v132 offset:38912
	ds_read_b128 v[106:109], v136 offset:34816
	ds_read_b128 v[110:113], v136 offset:38912
	v_mfma_f32_32x32x16_bf16 v[50:65], v[114:117], v[122:125], v[50:65]
	v_mfma_f32_32x32x16_bf16 v[34:49], v[114:117], v[126:129], v[34:49]
	v_mfma_f32_32x32x16_bf16 v[18:33], v[118:121], v[122:125], v[18:33]
	v_mfma_f32_32x32x16_bf16 v[2:17], v[118:121], v[126:129], v[2:17]
	ds_read_b128 v[114:117], v133 offset:34816
	ds_read_b128 v[118:121], v133 offset:38912
	ds_read_b128 v[122:125], v137 offset:34816
	ds_read_b128 v[126:129], v137 offset:38912
	s_waitcnt lgkmcnt(0)
	s_barrier
	s_add_u32 m0, s14, 0x8380
	s_nop 0
	global_load_lds_dwordx4 v[148:149], off offset:1152
	s_add_u32 m0, s14, 0x9380
	s_nop 0
	global_load_lds_dwordx4 v[152:153], off offset:1152
	s_add_u32 m0, s14, 0xa380
	s_nop 0
	global_load_lds_dwordx4 v[156:157], off offset:1152
	s_add_u32 m0, s14, 0xb380
	s_nop 0
	global_load_lds_dwordx4 v[160:161], off offset:1152
	s_add_u32 m0, s14, 0xc380
	s_nop 0
	global_load_lds_dwordx4 v[150:151], off offset:1152
	s_add_u32 m0, s14, 0xd380
	s_nop 0
	global_load_lds_dwordx4 v[154:155], off offset:1152
	s_add_u32 m0, s14, 0xe380
	s_nop 0
	global_load_lds_dwordx4 v[158:159], off offset:1152
	s_add_u32 m0, s14, 0xf380
	s_nop 0
	global_load_lds_dwordx4 v[162:163], off offset:1152
	v_mfma_f32_32x32x16_bf16 v[50:65], v[66:69], v[74:77], v[50:65]
	v_mfma_f32_32x32x16_bf16 v[34:49], v[66:69], v[78:81], v[34:49]
	v_mfma_f32_32x32x16_bf16 v[18:33], v[70:73], v[74:77], v[18:33]
	v_mfma_f32_32x32x16_bf16 v[2:17], v[70:73], v[78:81], v[2:17]
	s_waitcnt vmcnt(8)
	s_barrier
	ds_read_b128 v[66:69], v130 offset:2048
	ds_read_b128 v[70:73], v130 offset:6144
	ds_read_b128 v[74:77], v134 offset:2048
	ds_read_b128 v[78:81], v134 offset:6144
	v_mfma_f32_32x32x16_bf16 v[50:65], v[82:85], v[90:93], v[50:65]
	v_mfma_f32_32x32x16_bf16 v[34:49], v[82:85], v[94:97], v[34:49]
	v_mfma_f32_32x32x16_bf16 v[18:33], v[86:89], v[90:93], v[18:33]
	v_mfma_f32_32x32x16_bf16 v[2:17], v[86:89], v[94:97], v[2:17]
	ds_read_b128 v[82:85], v131 offset:2048
	ds_read_b128 v[86:89], v131 offset:6144
	ds_read_b128 v[90:93], v135 offset:2048
	ds_read_b128 v[94:97], v135 offset:6144
	v_mfma_f32_32x32x16_bf16 v[50:65], v[98:101], v[106:109], v[50:65]
	v_mfma_f32_32x32x16_bf16 v[34:49], v[98:101], v[110:113], v[34:49]
	v_mfma_f32_32x32x16_bf16 v[18:33], v[102:105], v[106:109], v[18:33]
	v_mfma_f32_32x32x16_bf16 v[2:17], v[102:105], v[110:113], v[2:17]
	ds_read_b128 v[98:101], v132 offset:2048
	ds_read_b128 v[102:105], v132 offset:6144
	ds_read_b128 v[106:109], v136 offset:2048
	ds_read_b128 v[110:113], v136 offset:6144
	v_mfma_f32_32x32x16_bf16 v[50:65], v[114:117], v[122:125], v[50:65]
	v_mfma_f32_32x32x16_bf16 v[34:49], v[114:117], v[126:129], v[34:49]
	v_mfma_f32_32x32x16_bf16 v[18:33], v[118:121], v[122:125], v[18:33]
	v_mfma_f32_32x32x16_bf16 v[2:17], v[118:121], v[126:129], v[2:17]
	ds_read_b128 v[114:117], v133 offset:2048
	ds_read_b128 v[118:121], v133 offset:6144
	ds_read_b128 v[122:125], v137 offset:2048
	ds_read_b128 v[126:129], v137 offset:6144
	s_waitcnt lgkmcnt(0)
	s_barrier
	s_add_u32 m0, s14, 0x300
	s_nop 0
	global_load_lds_dwordx4 v[148:149], off offset:1280
	s_add_u32 m0, s14, 0x1300
	s_nop 0
	global_load_lds_dwordx4 v[152:153], off offset:1280
	s_add_u32 m0, s14, 0x2300
	s_nop 0
	global_load_lds_dwordx4 v[156:157], off offset:1280
	s_add_u32 m0, s14, 0x3300
	s_nop 0
	global_load_lds_dwordx4 v[160:161], off offset:1280
	s_add_u32 m0, s14, 0x4300
	s_nop 0
	global_load_lds_dwordx4 v[150:151], off offset:1280
	s_add_u32 m0, s14, 0x5300
	s_nop 0
	global_load_lds_dwordx4 v[154:155], off offset:1280
	s_add_u32 m0, s14, 0x6300
	s_nop 0
	global_load_lds_dwordx4 v[158:159], off offset:1280
	s_add_u32 m0, s14, 0x7300
	s_nop 0
	global_load_lds_dwordx4 v[162:163], off offset:1280
	v_mfma_f32_32x32x16_bf16 v[50:65], v[66:69], v[74:77], v[50:65]
	v_mfma_f32_32x32x16_bf16 v[34:49], v[66:69], v[78:81], v[34:49]
	v_mfma_f32_32x32x16_bf16 v[18:33], v[70:73], v[74:77], v[18:33]
	v_mfma_f32_32x32x16_bf16 v[2:17], v[70:73], v[78:81], v[2:17]
	s_waitcnt vmcnt(8)
	s_barrier
	ds_read_b128 v[66:69], v130 offset:34816
	ds_read_b128 v[70:73], v130 offset:38912
	ds_read_b128 v[74:77], v134 offset:34816
	ds_read_b128 v[78:81], v134 offset:38912
	v_mfma_f32_32x32x16_bf16 v[50:65], v[82:85], v[90:93], v[50:65]
	v_mfma_f32_32x32x16_bf16 v[34:49], v[82:85], v[94:97], v[34:49]
	v_mfma_f32_32x32x16_bf16 v[18:33], v[86:89], v[90:93], v[18:33]
	v_mfma_f32_32x32x16_bf16 v[2:17], v[86:89], v[94:97], v[2:17]
	ds_read_b128 v[82:85], v131 offset:34816
	ds_read_b128 v[86:89], v131 offset:38912
	ds_read_b128 v[90:93], v135 offset:34816
	ds_read_b128 v[94:97], v135 offset:38912
	v_mfma_f32_32x32x16_bf16 v[50:65], v[98:101], v[106:109], v[50:65]
	v_mfma_f32_32x32x16_bf16 v[34:49], v[98:101], v[110:113], v[34:49]
	v_mfma_f32_32x32x16_bf16 v[18:33], v[102:105], v[106:109], v[18:33]
	v_mfma_f32_32x32x16_bf16 v[2:17], v[102:105], v[110:113], v[2:17]
	ds_read_b128 v[98:101], v132 offset:34816
	ds_read_b128 v[102:105], v132 offset:38912
	ds_read_b128 v[106:109], v136 offset:34816
	ds_read_b128 v[110:113], v136 offset:38912
	v_mfma_f32_32x32x16_bf16 v[50:65], v[114:117], v[122:125], v[50:65]
	v_mfma_f32_32x32x16_bf16 v[34:49], v[114:117], v[126:129], v[34:49]
	v_mfma_f32_32x32x16_bf16 v[18:33], v[118:121], v[122:125], v[18:33]
	v_mfma_f32_32x32x16_bf16 v[2:17], v[118:121], v[126:129], v[2:17]
	ds_read_b128 v[114:117], v133 offset:34816
	ds_read_b128 v[118:121], v133 offset:38912
	ds_read_b128 v[122:125], v137 offset:34816
	ds_read_b128 v[126:129], v137 offset:38912
	s_waitcnt lgkmcnt(0)
	s_barrier
	s_add_u32 m0, s14, 0x8280
	s_nop 0
	global_load_lds_dwordx4 v[148:149], off offset:1408
	s_add_u32 m0, s14, 0x9280
	s_nop 0
	global_load_lds_dwordx4 v[152:153], off offset:1408
	s_add_u32 m0, s14, 0xa280
	s_nop 0
	global_load_lds_dwordx4 v[156:157], off offset:1408
	s_add_u32 m0, s14, 0xb280
	s_nop 0
	global_load_lds_dwordx4 v[160:161], off offset:1408
	s_add_u32 m0, s14, 0xc280
	s_nop 0
	global_load_lds_dwordx4 v[150:151], off offset:1408
	s_add_u32 m0, s14, 0xd280
	s_nop 0
	global_load_lds_dwordx4 v[154:155], off offset:1408
	s_add_u32 m0, s14, 0xe280
	s_nop 0
	global_load_lds_dwordx4 v[158:159], off offset:1408
	s_add_u32 m0, s14, 0xf280
	s_nop 0
	global_load_lds_dwordx4 v[162:163], off offset:1408
	v_mfma_f32_32x32x16_bf16 v[50:65], v[66:69], v[74:77], v[50:65]
	v_mfma_f32_32x32x16_bf16 v[34:49], v[66:69], v[78:81], v[34:49]
	v_mfma_f32_32x32x16_bf16 v[18:33], v[70:73], v[74:77], v[18:33]
	v_mfma_f32_32x32x16_bf16 v[2:17], v[70:73], v[78:81], v[2:17]
	s_waitcnt vmcnt(8)
	s_barrier
	ds_read_b128 v[66:69], v130 offset:2048
	ds_read_b128 v[70:73], v130 offset:6144
	ds_read_b128 v[74:77], v134 offset:2048
	ds_read_b128 v[78:81], v134 offset:6144
	v_mfma_f32_32x32x16_bf16 v[50:65], v[82:85], v[90:93], v[50:65]
	v_mfma_f32_32x32x16_bf16 v[34:49], v[82:85], v[94:97], v[34:49]
	v_mfma_f32_32x32x16_bf16 v[18:33], v[86:89], v[90:93], v[18:33]
	v_mfma_f32_32x32x16_bf16 v[2:17], v[86:89], v[94:97], v[2:17]
	ds_read_b128 v[82:85], v131 offset:2048
	ds_read_b128 v[86:89], v131 offset:6144
	ds_read_b128 v[90:93], v135 offset:2048
	ds_read_b128 v[94:97], v135 offset:6144
	v_mfma_f32_32x32x16_bf16 v[50:65], v[98:101], v[106:109], v[50:65]
	v_mfma_f32_32x32x16_bf16 v[34:49], v[98:101], v[110:113], v[34:49]
	v_mfma_f32_32x32x16_bf16 v[18:33], v[102:105], v[106:109], v[18:33]
	v_mfma_f32_32x32x16_bf16 v[2:17], v[102:105], v[110:113], v[2:17]
	ds_read_b128 v[98:101], v132 offset:2048
	ds_read_b128 v[102:105], v132 offset:6144
	ds_read_b128 v[106:109], v136 offset:2048
	ds_read_b128 v[110:113], v136 offset:6144
	v_mfma_f32_32x32x16_bf16 v[50:65], v[114:117], v[122:125], v[50:65]
	v_mfma_f32_32x32x16_bf16 v[34:49], v[114:117], v[126:129], v[34:49]
	v_mfma_f32_32x32x16_bf16 v[18:33], v[118:121], v[122:125], v[18:33]
	v_mfma_f32_32x32x16_bf16 v[2:17], v[118:121], v[126:129], v[2:17]
	ds_read_b128 v[114:117], v133 offset:2048
	ds_read_b128 v[118:121], v133 offset:6144
	ds_read_b128 v[122:125], v137 offset:2048
	ds_read_b128 v[126:129], v137 offset:6144
	s_waitcnt lgkmcnt(0)
	s_barrier
	s_add_u32 m0, s14, 0x200
	s_nop 0
	global_load_lds_dwordx4 v[148:149], off offset:1536
	s_add_u32 m0, s14, 0x1200
	s_nop 0
	global_load_lds_dwordx4 v[152:153], off offset:1536
	s_add_u32 m0, s14, 0x2200
	s_nop 0
	global_load_lds_dwordx4 v[156:157], off offset:1536
	s_add_u32 m0, s14, 0x3200
	s_nop 0
	global_load_lds_dwordx4 v[160:161], off offset:1536
	s_add_u32 m0, s14, 0x4200
	s_nop 0
	global_load_lds_dwordx4 v[150:151], off offset:1536
	s_add_u32 m0, s14, 0x5200
	s_nop 0
	global_load_lds_dwordx4 v[154:155], off offset:1536
	s_add_u32 m0, s14, 0x6200
	s_nop 0
	global_load_lds_dwordx4 v[158:159], off offset:1536
	s_add_u32 m0, s14, 0x7200
	s_nop 0
	global_load_lds_dwordx4 v[162:163], off offset:1536
	v_mfma_f32_32x32x16_bf16 v[50:65], v[66:69], v[74:77], v[50:65]
	v_mfma_f32_32x32x16_bf16 v[34:49], v[66:69], v[78:81], v[34:49]
	v_mfma_f32_32x32x16_bf16 v[18:33], v[70:73], v[74:77], v[18:33]
	v_mfma_f32_32x32x16_bf16 v[2:17], v[70:73], v[78:81], v[2:17]
	s_waitcnt vmcnt(8)
	s_barrier
	ds_read_b128 v[66:69], v130 offset:34816
	ds_read_b128 v[70:73], v130 offset:38912
	ds_read_b128 v[74:77], v134 offset:34816
	ds_read_b128 v[78:81], v134 offset:38912
	v_mfma_f32_32x32x16_bf16 v[50:65], v[82:85], v[90:93], v[50:65]
	v_mfma_f32_32x32x16_bf16 v[34:49], v[82:85], v[94:97], v[34:49]
	v_mfma_f32_32x32x16_bf16 v[18:33], v[86:89], v[90:93], v[18:33]
	v_mfma_f32_32x32x16_bf16 v[2:17], v[86:89], v[94:97], v[2:17]
	ds_read_b128 v[82:85], v131 offset:34816
	ds_read_b128 v[86:89], v131 offset:38912
	ds_read_b128 v[90:93], v135 offset:34816
	ds_read_b128 v[94:97], v135 offset:38912
	v_mfma_f32_32x32x16_bf16 v[50:65], v[98:101], v[106:109], v[50:65]
	v_mfma_f32_32x32x16_bf16 v[34:49], v[98:101], v[110:113], v[34:49]
	v_mfma_f32_32x32x16_bf16 v[18:33], v[102:105], v[106:109], v[18:33]
	v_mfma_f32_32x32x16_bf16 v[2:17], v[102:105], v[110:113], v[2:17]
	ds_read_b128 v[98:101], v132 offset:34816
	ds_read_b128 v[102:105], v132 offset:38912
	ds_read_b128 v[106:109], v136 offset:34816
	ds_read_b128 v[110:113], v136 offset:38912
	v_mfma_f32_32x32x16_bf16 v[50:65], v[114:117], v[122:125], v[50:65]
	v_mfma_f32_32x32x16_bf16 v[34:49], v[114:117], v[126:129], v[34:49]
	v_mfma_f32_32x32x16_bf16 v[18:33], v[118:121], v[122:125], v[18:33]
	v_mfma_f32_32x32x16_bf16 v[2:17], v[118:121], v[126:129], v[2:17]
	ds_read_b128 v[114:117], v133 offset:34816
	ds_read_b128 v[118:121], v133 offset:38912
	ds_read_b128 v[122:125], v137 offset:34816
	ds_read_b128 v[126:129], v137 offset:38912
	s_waitcnt lgkmcnt(0)
	s_barrier
	s_add_u32 m0, s14, 0x8180
	s_nop 0
	global_load_lds_dwordx4 v[148:149], off offset:1664
	s_add_u32 m0, s14, 0x9180
	s_nop 0
	global_load_lds_dwordx4 v[152:153], off offset:1664
	s_add_u32 m0, s14, 0xa180
	s_nop 0
	global_load_lds_dwordx4 v[156:157], off offset:1664
	s_add_u32 m0, s14, 0xb180
	s_nop 0
	global_load_lds_dwordx4 v[160:161], off offset:1664
	s_add_u32 m0, s14, 0xc180
	s_nop 0
	global_load_lds_dwordx4 v[150:151], off offset:1664
	s_add_u32 m0, s14, 0xd180
	s_nop 0
	global_load_lds_dwordx4 v[154:155], off offset:1664
	s_add_u32 m0, s14, 0xe180
	s_nop 0
	global_load_lds_dwordx4 v[158:159], off offset:1664
	s_add_u32 m0, s14, 0xf180
	s_nop 0
	global_load_lds_dwordx4 v[162:163], off offset:1664
	v_mfma_f32_32x32x16_bf16 v[50:65], v[66:69], v[74:77], v[50:65]
	v_mfma_f32_32x32x16_bf16 v[34:49], v[66:69], v[78:81], v[34:49]
	v_mfma_f32_32x32x16_bf16 v[18:33], v[70:73], v[74:77], v[18:33]
	v_mfma_f32_32x32x16_bf16 v[2:17], v[70:73], v[78:81], v[2:17]
	s_waitcnt vmcnt(8)
	s_barrier
	ds_read_b128 v[66:69], v130 offset:2048
	ds_read_b128 v[70:73], v130 offset:6144
	ds_read_b128 v[74:77], v134 offset:2048
	ds_read_b128 v[78:81], v134 offset:6144
	v_mfma_f32_32x32x16_bf16 v[50:65], v[82:85], v[90:93], v[50:65]
	v_mfma_f32_32x32x16_bf16 v[34:49], v[82:85], v[94:97], v[34:49]
	v_mfma_f32_32x32x16_bf16 v[18:33], v[86:89], v[90:93], v[18:33]
	v_mfma_f32_32x32x16_bf16 v[2:17], v[86:89], v[94:97], v[2:17]
	ds_read_b128 v[82:85], v131 offset:2048
	ds_read_b128 v[86:89], v131 offset:6144
	ds_read_b128 v[90:93], v135 offset:2048
	ds_read_b128 v[94:97], v135 offset:6144
	v_mfma_f32_32x32x16_bf16 v[50:65], v[98:101], v[106:109], v[50:65]
	v_mfma_f32_32x32x16_bf16 v[34:49], v[98:101], v[110:113], v[34:49]
	v_mfma_f32_32x32x16_bf16 v[18:33], v[102:105], v[106:109], v[18:33]
	v_mfma_f32_32x32x16_bf16 v[2:17], v[102:105], v[110:113], v[2:17]
	ds_read_b128 v[98:101], v132 offset:2048
	ds_read_b128 v[102:105], v132 offset:6144
	ds_read_b128 v[106:109], v136 offset:2048
	ds_read_b128 v[110:113], v136 offset:6144
	v_mfma_f32_32x32x16_bf16 v[50:65], v[114:117], v[122:125], v[50:65]
	v_mfma_f32_32x32x16_bf16 v[34:49], v[114:117], v[126:129], v[34:49]
	v_mfma_f32_32x32x16_bf16 v[18:33], v[118:121], v[122:125], v[18:33]
	v_mfma_f32_32x32x16_bf16 v[2:17], v[118:121], v[126:129], v[2:17]
	ds_read_b128 v[114:117], v133 offset:2048
	ds_read_b128 v[118:121], v133 offset:6144
	ds_read_b128 v[122:125], v137 offset:2048
	ds_read_b128 v[126:129], v137 offset:6144
	s_waitcnt lgkmcnt(0)
	s_barrier
	s_add_u32 m0, s14, 0x100
	s_nop 0
	global_load_lds_dwordx4 v[148:149], off offset:1792
	s_add_u32 m0, s14, 0x1100
	s_nop 0
	global_load_lds_dwordx4 v[152:153], off offset:1792
	s_add_u32 m0, s14, 0x2100
	s_nop 0
	global_load_lds_dwordx4 v[156:157], off offset:1792
	s_add_u32 m0, s14, 0x3100
	s_nop 0
	global_load_lds_dwordx4 v[160:161], off offset:1792
	s_add_u32 m0, s14, 0x4100
	s_nop 0
	global_load_lds_dwordx4 v[150:151], off offset:1792
	s_add_u32 m0, s14, 0x5100
	s_nop 0
	global_load_lds_dwordx4 v[154:155], off offset:1792
	s_add_u32 m0, s14, 0x6100
	s_nop 0
	global_load_lds_dwordx4 v[158:159], off offset:1792
	s_add_u32 m0, s14, 0x7100
	s_nop 0
	global_load_lds_dwordx4 v[162:163], off offset:1792
	v_mfma_f32_32x32x16_bf16 v[50:65], v[66:69], v[74:77], v[50:65]
	v_mfma_f32_32x32x16_bf16 v[34:49], v[66:69], v[78:81], v[34:49]
	v_mfma_f32_32x32x16_bf16 v[18:33], v[70:73], v[74:77], v[18:33]
	v_mfma_f32_32x32x16_bf16 v[2:17], v[70:73], v[78:81], v[2:17]
	s_waitcnt vmcnt(8)
	s_barrier
	ds_read_b128 v[66:69], v130 offset:34816
	ds_read_b128 v[70:73], v130 offset:38912
	ds_read_b128 v[74:77], v134 offset:34816
	ds_read_b128 v[78:81], v134 offset:38912
	v_mfma_f32_32x32x16_bf16 v[50:65], v[82:85], v[90:93], v[50:65]
	v_mfma_f32_32x32x16_bf16 v[34:49], v[82:85], v[94:97], v[34:49]
	v_mfma_f32_32x32x16_bf16 v[18:33], v[86:89], v[90:93], v[18:33]
	v_mfma_f32_32x32x16_bf16 v[2:17], v[86:89], v[94:97], v[2:17]
	ds_read_b128 v[82:85], v131 offset:34816
	ds_read_b128 v[86:89], v131 offset:38912
	ds_read_b128 v[90:93], v135 offset:34816
	ds_read_b128 v[94:97], v135 offset:38912
	v_mfma_f32_32x32x16_bf16 v[50:65], v[98:101], v[106:109], v[50:65]
	v_mfma_f32_32x32x16_bf16 v[34:49], v[98:101], v[110:113], v[34:49]
	v_mfma_f32_32x32x16_bf16 v[18:33], v[102:105], v[106:109], v[18:33]
	v_mfma_f32_32x32x16_bf16 v[2:17], v[102:105], v[110:113], v[2:17]
	ds_read_b128 v[98:101], v132 offset:34816
	ds_read_b128 v[102:105], v132 offset:38912
	ds_read_b128 v[106:109], v136 offset:34816
	ds_read_b128 v[110:113], v136 offset:38912
	v_mfma_f32_32x32x16_bf16 v[50:65], v[114:117], v[122:125], v[50:65]
	v_mfma_f32_32x32x16_bf16 v[34:49], v[114:117], v[126:129], v[34:49]
	v_mfma_f32_32x32x16_bf16 v[18:33], v[118:121], v[122:125], v[18:33]
	v_mfma_f32_32x32x16_bf16 v[2:17], v[118:121], v[126:129], v[2:17]
	ds_read_b128 v[114:117], v133 offset:34816
	ds_read_b128 v[118:121], v133 offset:38912
	ds_read_b128 v[122:125], v137 offset:34816
	ds_read_b128 v[126:129], v137 offset:38912
	s_waitcnt lgkmcnt(0)
	s_barrier
	s_add_u32 m0, s14, 0x8080
	s_nop 0
	global_load_lds_dwordx4 v[148:149], off offset:1920
	s_add_u32 m0, s14, 0x9080
	s_nop 0
	global_load_lds_dwordx4 v[152:153], off offset:1920
	s_add_u32 m0, s14, 0xa080
	s_nop 0
	global_load_lds_dwordx4 v[156:157], off offset:1920
	s_add_u32 m0, s14, 0xb080
	s_nop 0
	global_load_lds_dwordx4 v[160:161], off offset:1920
	s_add_u32 m0, s14, 0xc080
	s_nop 0
	global_load_lds_dwordx4 v[150:151], off offset:1920
	s_add_u32 m0, s14, 0xd080
	s_nop 0
	global_load_lds_dwordx4 v[154:155], off offset:1920
	s_add_u32 m0, s14, 0xe080
	s_nop 0
	global_load_lds_dwordx4 v[158:159], off offset:1920
	s_add_u32 m0, s14, 0xf080
	s_nop 0
	global_load_lds_dwordx4 v[162:163], off offset:1920
	v_mfma_f32_32x32x16_bf16 v[50:65], v[66:69], v[74:77], v[50:65]
	v_mfma_f32_32x32x16_bf16 v[34:49], v[66:69], v[78:81], v[34:49]
	v_mfma_f32_32x32x16_bf16 v[18:33], v[70:73], v[74:77], v[18:33]
	v_mfma_f32_32x32x16_bf16 v[2:17], v[70:73], v[78:81], v[2:17]
	s_waitcnt vmcnt(8)
	s_barrier
	ds_read_b128 v[66:69], v130 offset:2048
	ds_read_b128 v[70:73], v130 offset:6144
	ds_read_b128 v[74:77], v134 offset:2048
	ds_read_b128 v[78:81], v134 offset:6144
	v_mfma_f32_32x32x16_bf16 v[50:65], v[82:85], v[90:93], v[50:65]
	v_mfma_f32_32x32x16_bf16 v[34:49], v[82:85], v[94:97], v[34:49]
	v_mfma_f32_32x32x16_bf16 v[18:33], v[86:89], v[90:93], v[18:33]
	v_mfma_f32_32x32x16_bf16 v[2:17], v[86:89], v[94:97], v[2:17]
	ds_read_b128 v[82:85], v131 offset:2048
	ds_read_b128 v[86:89], v131 offset:6144
	ds_read_b128 v[90:93], v135 offset:2048
	ds_read_b128 v[94:97], v135 offset:6144
	v_mfma_f32_32x32x16_bf16 v[50:65], v[98:101], v[106:109], v[50:65]
	v_mfma_f32_32x32x16_bf16 v[34:49], v[98:101], v[110:113], v[34:49]
	v_mfma_f32_32x32x16_bf16 v[18:33], v[102:105], v[106:109], v[18:33]
	v_mfma_f32_32x32x16_bf16 v[2:17], v[102:105], v[110:113], v[2:17]
	ds_read_b128 v[98:101], v132 offset:2048
	ds_read_b128 v[102:105], v132 offset:6144
	ds_read_b128 v[106:109], v136 offset:2048
	ds_read_b128 v[110:113], v136 offset:6144
	v_mfma_f32_32x32x16_bf16 v[50:65], v[114:117], v[122:125], v[50:65]
	v_mfma_f32_32x32x16_bf16 v[34:49], v[114:117], v[126:129], v[34:49]
	v_mfma_f32_32x32x16_bf16 v[18:33], v[118:121], v[122:125], v[18:33]
	v_mfma_f32_32x32x16_bf16 v[2:17], v[118:121], v[126:129], v[2:17]
	ds_read_b128 v[114:117], v133 offset:2048
	ds_read_b128 v[118:121], v133 offset:6144
	ds_read_b128 v[122:125], v137 offset:2048
	ds_read_b128 v[126:129], v137 offset:6144
	s_waitcnt lgkmcnt(0)
	v_mfma_f32_32x32x16_bf16 v[50:65], v[66:69], v[74:77], v[50:65]
	v_mfma_f32_32x32x16_bf16 v[34:49], v[66:69], v[78:81], v[34:49]
	v_mfma_f32_32x32x16_bf16 v[18:33], v[70:73], v[74:77], v[18:33]
	v_mfma_f32_32x32x16_bf16 v[2:17], v[70:73], v[78:81], v[2:17]
	s_waitcnt vmcnt(0)
	s_barrier
	ds_read_b128 v[66:69], v130 offset:34816
	ds_read_b128 v[70:73], v130 offset:38912
	ds_read_b128 v[74:77], v134 offset:34816
	ds_read_b128 v[78:81], v134 offset:38912
	v_mfma_f32_32x32x16_bf16 v[50:65], v[82:85], v[90:93], v[50:65]
	v_mfma_f32_32x32x16_bf16 v[34:49], v[82:85], v[94:97], v[34:49]
	v_mfma_f32_32x32x16_bf16 v[18:33], v[86:89], v[90:93], v[18:33]
	v_mfma_f32_32x32x16_bf16 v[2:17], v[86:89], v[94:97], v[2:17]
	ds_read_b128 v[82:85], v131 offset:34816
	ds_read_b128 v[86:89], v131 offset:38912
	ds_read_b128 v[90:93], v135 offset:34816
	ds_read_b128 v[94:97], v135 offset:38912
	v_mfma_f32_32x32x16_bf16 v[50:65], v[98:101], v[106:109], v[50:65]
	v_mfma_f32_32x32x16_bf16 v[34:49], v[98:101], v[110:113], v[34:49]
	v_mfma_f32_32x32x16_bf16 v[18:33], v[102:105], v[106:109], v[18:33]
	v_mfma_f32_32x32x16_bf16 v[2:17], v[102:105], v[110:113], v[2:17]
	ds_read_b128 v[98:101], v132 offset:34816
	ds_read_b128 v[102:105], v132 offset:38912
	ds_read_b128 v[106:109], v136 offset:34816
	ds_read_b128 v[110:113], v136 offset:38912
	v_mfma_f32_32x32x16_bf16 v[50:65], v[114:117], v[122:125], v[50:65]
	v_mfma_f32_32x32x16_bf16 v[34:49], v[114:117], v[126:129], v[34:49]
	v_mfma_f32_32x32x16_bf16 v[18:33], v[118:121], v[122:125], v[18:33]
	v_mfma_f32_32x32x16_bf16 v[2:17], v[118:121], v[126:129], v[2:17]
	ds_read_b128 v[114:117], v133 offset:34816
	ds_read_b128 v[118:121], v133 offset:38912
	ds_read_b128 v[122:125], v137 offset:34816
	ds_read_b128 v[126:129], v137 offset:38912
	s_waitcnt lgkmcnt(0)
	v_mfma_f32_32x32x16_bf16 v[50:65], v[66:69], v[74:77], v[50:65]
	v_mfma_f32_32x32x16_bf16 v[34:49], v[66:69], v[78:81], v[34:49]
	v_mfma_f32_32x32x16_bf16 v[18:33], v[70:73], v[74:77], v[18:33]
	v_mfma_f32_32x32x16_bf16 v[2:17], v[70:73], v[78:81], v[2:17]
	v_mfma_f32_32x32x16_bf16 v[50:65], v[82:85], v[90:93], v[50:65]
	v_mfma_f32_32x32x16_bf16 v[34:49], v[82:85], v[94:97], v[34:49]
	v_mfma_f32_32x32x16_bf16 v[18:33], v[86:89], v[90:93], v[18:33]
	v_mfma_f32_32x32x16_bf16 v[2:17], v[86:89], v[94:97], v[2:17]
	v_mfma_f32_32x32x16_bf16 v[50:65], v[98:101], v[106:109], v[50:65]
	v_mfma_f32_32x32x16_bf16 v[34:49], v[98:101], v[110:113], v[34:49]
	v_mfma_f32_32x32x16_bf16 v[18:33], v[102:105], v[106:109], v[18:33]
	v_mfma_f32_32x32x16_bf16 v[2:17], v[102:105], v[110:113], v[2:17]
	v_mfma_f32_32x32x16_bf16 v[50:65], v[114:117], v[122:125], v[50:65]
	v_mfma_f32_32x32x16_bf16 v[34:49], v[114:117], v[126:129], v[34:49]
	v_mfma_f32_32x32x16_bf16 v[18:33], v[118:121], v[122:125], v[18:33]
	v_mfma_f32_32x32x16_bf16 v[2:17], v[118:121], v[126:129], v[2:17]
	s_cmp_eq_u32 s45, 1
	s_waitcnt lgkmcnt(0)
	s_barrier
	s_nop 0
	s_nop 0
	s_nop 10
	v_mul_f32_e32 v0, 0xbfb8aa3b, v50
	v_exp_f32_e32 v0, v0
	s_nop 0
	v_add_f32_e32 v0, 1.0, v0
	v_div_scale_f32 v50, s[0:1], v0, v0, 1.0
	v_rcp_f32_e32 v66, v50
	s_nop 0
	v_fma_f32 v67, -v50, v66, 1.0
	v_fmac_f32_e32 v66, v67, v66
	v_div_scale_f32 v67, vcc, 1.0, v0, 1.0
	v_mul_f32_e32 v68, v67, v66
	v_fma_f32 v69, -v50, v68, v67
	v_fmac_f32_e32 v68, v69, v66
	v_fma_f32 v50, -v50, v68, v67
	v_div_fmas_f32 v50, v50, v66, v68
	v_div_fixup_f32 v0, v50, v0, 1.0
	v_fma_f32 v0, v0, s80, 0.5
	v_cvt_u32_f32_e32 v116, v0
	v_mul_f32_e32 v0, 0xbfb8aa3b, v51
	v_exp_f32_e32 v0, v0
	s_nop 0
	v_add_f32_e32 v0, 1.0, v0
	v_div_scale_f32 v50, s[0:1], v0, v0, 1.0
	v_rcp_f32_e32 v51, v50
	s_nop 0
	v_fma_f32 v66, -v50, v51, 1.0
	v_fmac_f32_e32 v51, v66, v51
	v_div_scale_f32 v66, vcc, 1.0, v0, 1.0
	v_mul_f32_e32 v67, v66, v51
	v_fma_f32 v68, -v50, v67, v66
	v_fmac_f32_e32 v67, v68, v51
	v_fma_f32 v50, -v50, v67, v66
	v_div_fmas_f32 v50, v50, v51, v67
	v_div_fixup_f32 v0, v50, v0, 1.0
	v_mul_f32_e32 v50, 0xbfb8aa3b, v52
	v_exp_f32_e32 v50, v50
	v_fma_f32 v0, v0, s80, 0.5
	v_cvt_u32_f32_e32 v0, v0
	v_add_f32_e32 v50, 1.0, v50
	v_div_scale_f32 v51, s[0:1], v50, v50, 1.0
	v_rcp_f32_e32 v52, v51
	v_lshl_or_b32 v118, v0, 8, v116
	v_mul_f32_e32 v0, 0xbfb8aa3b, v54
	v_exp_f32_e32 v0, v0
	v_fma_f32 v66, -v51, v52, 1.0
	v_fmac_f32_e32 v52, v66, v52
	v_div_scale_f32 v66, vcc, 1.0, v50, 1.0
	v_mul_f32_e32 v67, v66, v52
	v_fma_f32 v68, -v51, v67, v66
	v_fmac_f32_e32 v67, v68, v52
	v_fma_f32 v51, -v51, v67, v66
	v_div_fmas_f32 v51, v51, v52, v67
	v_div_fixup_f32 v50, v51, v50, 1.0
	v_mul_f32_e32 v51, 0xbfb8aa3b, v53
	v_exp_f32_e32 v51, v51
	v_fma_f32 v50, v50, s80, 0.5
	v_cvt_u32_f32_sdwa v50, v50 dst_sel:WORD_1 dst_unused:UNUSED_PAD src0_sel:DWORD
	v_add_f32_e32 v0, 1.0, v0
	v_add_f32_e32 v51, 1.0, v51
	v_div_scale_f32 v52, s[0:1], v51, v51, 1.0
	v_rcp_f32_e32 v53, v52
	s_nop 0
	v_fma_f32 v66, -v52, v53, 1.0
	v_fmac_f32_e32 v53, v66, v53
	v_div_scale_f32 v66, vcc, 1.0, v51, 1.0
	v_mul_f32_e32 v67, v66, v53
	v_fma_f32 v68, -v52, v67, v66
	v_fmac_f32_e32 v67, v68, v53
	v_fma_f32 v52, -v52, v67, v66
	v_div_fmas_f32 v52, v52, v53, v67
	v_div_fixup_f32 v51, v52, v51, 1.0
	v_fma_f32 v51, v51, s80, 0.5
	v_cvt_u32_f32_sdwa v51, v51 dst_sel:BYTE_3 dst_unused:UNUSED_PAD src0_sel:DWORD
	s_nop 0
	v_or3_b32 v117, v50, v51, v118
	v_div_scale_f32 v50, s[0:1], v0, v0, 1.0
	v_rcp_f32_e32 v51, v50
	s_nop 0
	v_fma_f32 v52, -v50, v51, 1.0
	v_fmac_f32_e32 v51, v52, v51
	v_div_scale_f32 v52, vcc, 1.0, v0, 1.0
	v_mul_f32_e32 v53, v52, v51
	v_fma_f32 v54, -v50, v53, v52
	v_fmac_f32_e32 v53, v54, v51
	v_fma_f32 v50, -v50, v53, v52
	v_div_fmas_f32 v50, v50, v51, v53
	v_div_fixup_f32 v0, v50, v0, 1.0
	v_fma_f32 v0, v0, s80, 0.5
	v_cvt_u32_f32_e32 v119, v0
	v_mul_f32_e32 v0, 0xbfb8aa3b, v55
	v_exp_f32_e32 v0, v0
	s_nop 0
	v_add_f32_e32 v0, 1.0, v0
	v_div_scale_f32 v50, s[0:1], v0, v0, 1.0
	v_rcp_f32_e32 v51, v50
	s_nop 0
	v_fma_f32 v52, -v50, v51, 1.0
	v_fmac_f32_e32 v51, v52, v51
	v_div_scale_f32 v52, vcc, 1.0, v0, 1.0
	v_mul_f32_e32 v53, v52, v51
	v_fma_f32 v54, -v50, v53, v52
	v_fmac_f32_e32 v53, v54, v51
	v_fma_f32 v50, -v50, v53, v52
	v_div_fmas_f32 v50, v50, v51, v53
	v_div_fixup_f32 v0, v50, v0, 1.0
	v_mul_f32_e32 v50, 0xbfb8aa3b, v56
	v_exp_f32_e32 v50, v50
	v_fma_f32 v0, v0, s80, 0.5
	v_cvt_u32_f32_e32 v0, v0
	v_add_f32_e32 v50, 1.0, v50
	v_div_scale_f32 v51, s[0:1], v50, v50, 1.0
	v_rcp_f32_e32 v52, v51
	v_lshl_or_b32 v121, v0, 8, v119
	v_mul_f32_e32 v0, 0xbfb8aa3b, v58
	v_exp_f32_e32 v0, v0
	v_fma_f32 v53, -v51, v52, 1.0
	v_fmac_f32_e32 v52, v53, v52
	v_div_scale_f32 v53, vcc, 1.0, v50, 1.0
	v_mul_f32_e32 v54, v53, v52
	v_fma_f32 v55, -v51, v54, v53
	v_fmac_f32_e32 v54, v55, v52
	v_fma_f32 v51, -v51, v54, v53
	v_div_fmas_f32 v51, v51, v52, v54
	v_div_fixup_f32 v50, v51, v50, 1.0
	v_mul_f32_e32 v51, 0xbfb8aa3b, v57
	v_exp_f32_e32 v51, v51
	v_fma_f32 v50, v50, s80, 0.5
	v_cvt_u32_f32_sdwa v50, v50 dst_sel:WORD_1 dst_unused:UNUSED_PAD src0_sel:DWORD
	v_add_f32_e32 v0, 1.0, v0
	v_add_f32_e32 v51, 1.0, v51
	v_div_scale_f32 v52, s[0:1], v51, v51, 1.0
	v_rcp_f32_e32 v53, v52
	s_nop 0
	v_fma_f32 v54, -v52, v53, 1.0
	v_fmac_f32_e32 v53, v54, v53
	v_div_scale_f32 v54, vcc, 1.0, v51, 1.0
	v_mul_f32_e32 v55, v54, v53
	v_fma_f32 v56, -v52, v55, v54
	v_fmac_f32_e32 v55, v56, v53
	v_fma_f32 v52, -v52, v55, v54
	v_div_fmas_f32 v52, v52, v53, v55
	v_div_fixup_f32 v51, v52, v51, 1.0
	v_fma_f32 v51, v51, s80, 0.5
	v_cvt_u32_f32_sdwa v51, v51 dst_sel:BYTE_3 dst_unused:UNUSED_PAD src0_sel:DWORD
	s_nop 0
	v_or3_b32 v120, v50, v51, v121
	v_div_scale_f32 v50, s[0:1], v0, v0, 1.0
	v_rcp_f32_e32 v51, v50
	s_nop 0
	v_fma_f32 v52, -v50, v51, 1.0
	v_fmac_f32_e32 v51, v52, v51
	v_div_scale_f32 v52, vcc, 1.0, v0, 1.0
	v_mul_f32_e32 v53, v52, v51
	v_fma_f32 v54, -v50, v53, v52
	v_fmac_f32_e32 v53, v54, v51
	v_fma_f32 v50, -v50, v53, v52
	v_div_fmas_f32 v50, v50, v51, v53
	v_div_fixup_f32 v0, v50, v0, 1.0
	v_fma_f32 v0, v0, s80, 0.5
	v_cvt_u32_f32_e32 v122, v0
	v_mul_f32_e32 v0, 0xbfb8aa3b, v59
	v_exp_f32_e32 v0, v0
	s_nop 0
	v_add_f32_e32 v0, 1.0, v0
	v_div_scale_f32 v50, s[0:1], v0, v0, 1.0
	v_rcp_f32_e32 v51, v50
	s_nop 0
	v_fma_f32 v52, -v50, v51, 1.0
	v_fmac_f32_e32 v51, v52, v51
	v_div_scale_f32 v52, vcc, 1.0, v0, 1.0
	v_mul_f32_e32 v53, v52, v51
	v_fma_f32 v54, -v50, v53, v52
	v_fmac_f32_e32 v53, v54, v51
	v_fma_f32 v50, -v50, v53, v52
	v_div_fmas_f32 v50, v50, v51, v53
	v_div_fixup_f32 v0, v50, v0, 1.0
	v_mul_f32_e32 v50, 0xbfb8aa3b, v60
	v_exp_f32_e32 v50, v50
	v_fma_f32 v0, v0, s80, 0.5
	v_cvt_u32_f32_e32 v0, v0
	v_add_f32_e32 v50, 1.0, v50
	v_div_scale_f32 v51, s[0:1], v50, v50, 1.0
	v_rcp_f32_e32 v52, v51
	v_lshl_or_b32 v124, v0, 8, v122
	v_mul_f32_e32 v0, 0xbfb8aa3b, v62
	v_exp_f32_e32 v0, v0
	v_fma_f32 v53, -v51, v52, 1.0
	v_fmac_f32_e32 v52, v53, v52
	v_div_scale_f32 v53, vcc, 1.0, v50, 1.0
	v_mul_f32_e32 v54, v53, v52
	v_fma_f32 v55, -v51, v54, v53
	v_fmac_f32_e32 v54, v55, v52
	v_fma_f32 v51, -v51, v54, v53
	v_div_fmas_f32 v51, v51, v52, v54
	v_div_fixup_f32 v50, v51, v50, 1.0
	v_mul_f32_e32 v51, 0xbfb8aa3b, v61
	v_exp_f32_e32 v51, v51
	v_fma_f32 v50, v50, s80, 0.5
	v_cvt_u32_f32_sdwa v50, v50 dst_sel:WORD_1 dst_unused:UNUSED_PAD src0_sel:DWORD
	v_add_f32_e32 v0, 1.0, v0
	v_add_f32_e32 v51, 1.0, v51
	v_div_scale_f32 v52, s[0:1], v51, v51, 1.0
	v_rcp_f32_e32 v53, v52
	s_nop 0
	v_fma_f32 v54, -v52, v53, 1.0
	v_fmac_f32_e32 v53, v54, v53
	v_div_scale_f32 v54, vcc, 1.0, v51, 1.0
	v_mul_f32_e32 v55, v54, v53
	v_fma_f32 v56, -v52, v55, v54
	v_fmac_f32_e32 v55, v56, v53
	v_fma_f32 v52, -v52, v55, v54
	v_div_fmas_f32 v52, v52, v53, v55
	v_div_fixup_f32 v51, v52, v51, 1.0
	v_fma_f32 v51, v51, s80, 0.5
	v_cvt_u32_f32_sdwa v51, v51 dst_sel:BYTE_3 dst_unused:UNUSED_PAD src0_sel:DWORD
	s_nop 0
	v_or3_b32 v123, v50, v51, v124
	v_div_scale_f32 v50, s[0:1], v0, v0, 1.0
	v_rcp_f32_e32 v51, v50
	s_nop 0
	v_fma_f32 v52, -v50, v51, 1.0
	v_fmac_f32_e32 v51, v52, v51
	v_div_scale_f32 v52, vcc, 1.0, v0, 1.0
	v_mul_f32_e32 v53, v52, v51
	v_fma_f32 v54, -v50, v53, v52
	v_fmac_f32_e32 v53, v54, v51
	v_fma_f32 v50, -v50, v53, v52
	v_div_fmas_f32 v50, v50, v51, v53
	v_div_fixup_f32 v0, v50, v0, 1.0
	v_fma_f32 v0, v0, s80, 0.5
	v_cvt_u32_f32_e32 v125, v0
	v_mul_f32_e32 v0, 0xbfb8aa3b, v63
	v_exp_f32_e32 v0, v0
	s_nop 0
	v_add_f32_e32 v0, 1.0, v0
	v_div_scale_f32 v50, s[0:1], v0, v0, 1.0
	v_rcp_f32_e32 v51, v50
	s_nop 0
	v_fma_f32 v52, -v50, v51, 1.0
	v_fmac_f32_e32 v51, v52, v51
	v_div_scale_f32 v52, vcc, 1.0, v0, 1.0
	v_mul_f32_e32 v53, v52, v51
	v_fma_f32 v54, -v50, v53, v52
	v_fmac_f32_e32 v53, v54, v51
	v_fma_f32 v50, -v50, v53, v52
	v_div_fmas_f32 v50, v50, v51, v53
	v_div_fixup_f32 v0, v50, v0, 1.0
	v_mul_f32_e32 v50, 0xbfb8aa3b, v64
	v_exp_f32_e32 v50, v50
	v_fma_f32 v0, v0, s80, 0.5
	v_cvt_u32_f32_e32 v0, v0
	v_add_f32_e32 v50, 1.0, v50
	v_div_scale_f32 v51, s[0:1], v50, v50, 1.0
	v_rcp_f32_e32 v52, v51
	v_lshl_or_b32 v127, v0, 8, v125
	v_mul_f32_e32 v0, 0xbfb8aa3b, v34
	v_exp_f32_e32 v0, v0
	v_fma_f32 v53, -v51, v52, 1.0
	v_fmac_f32_e32 v52, v53, v52
	v_div_scale_f32 v53, vcc, 1.0, v50, 1.0
	v_mul_f32_e32 v54, v53, v52
	v_fma_f32 v55, -v51, v54, v53
	v_fmac_f32_e32 v54, v55, v52
	v_fma_f32 v51, -v51, v54, v53
	v_div_fmas_f32 v51, v51, v52, v54
	v_div_fixup_f32 v50, v51, v50, 1.0
	v_mul_f32_e32 v51, 0xbfb8aa3b, v65
	v_exp_f32_e32 v51, v51
	v_fma_f32 v50, v50, s80, 0.5
	v_cvt_u32_f32_sdwa v50, v50 dst_sel:WORD_1 dst_unused:UNUSED_PAD src0_sel:DWORD
	v_add_f32_e32 v0, 1.0, v0
	v_add_f32_e32 v51, 1.0, v51
	v_div_scale_f32 v52, s[0:1], v51, v51, 1.0
	v_rcp_f32_e32 v53, v52
	v_div_scale_f32 v34, s[0:1], v0, v0, 1.0
	v_fma_f32 v54, -v52, v53, 1.0
	v_fmac_f32_e32 v53, v54, v53
	v_div_scale_f32 v54, vcc, 1.0, v51, 1.0
	v_mul_f32_e32 v55, v54, v53
	v_fma_f32 v56, -v52, v55, v54
	v_fmac_f32_e32 v55, v56, v53
	v_fma_f32 v52, -v52, v55, v54
	v_div_fmas_f32 v52, v52, v53, v55
	v_div_fixup_f32 v51, v52, v51, 1.0
	v_fma_f32 v51, v51, s80, 0.5
	v_cvt_u32_f32_sdwa v51, v51 dst_sel:BYTE_3 dst_unused:UNUSED_PAD src0_sel:DWORD
	s_nop 0
	v_or3_b32 v126, v50, v51, v127
	v_rcp_f32_e32 v50, v34
	s_nop 0
	v_fma_f32 v51, -v34, v50, 1.0
	v_fmac_f32_e32 v50, v51, v50
	v_div_scale_f32 v51, vcc, 1.0, v0, 1.0
	v_mul_f32_e32 v52, v51, v50
	v_fma_f32 v53, -v34, v52, v51
	v_fmac_f32_e32 v52, v53, v50
	v_fma_f32 v34, -v34, v52, v51
	v_div_fmas_f32 v34, v34, v50, v52
	v_div_fixup_f32 v0, v34, v0, 1.0
	v_fma_f32 v0, v0, s80, 0.5
	v_cvt_u32_f32_e32 v128, v0
	v_mul_f32_e32 v0, 0xbfb8aa3b, v35
	v_exp_f32_e32 v0, v0
	s_nop 0
	v_add_f32_e32 v0, 1.0, v0
	v_div_scale_f32 v34, s[0:1], v0, v0, 1.0
	v_rcp_f32_e32 v35, v34
	s_nop 0
	v_fma_f32 v50, -v34, v35, 1.0
	v_fmac_f32_e32 v35, v50, v35
	v_div_scale_f32 v50, vcc, 1.0, v0, 1.0
	v_mul_f32_e32 v51, v50, v35
	v_fma_f32 v52, -v34, v51, v50
	v_fmac_f32_e32 v51, v52, v35
	v_fma_f32 v34, -v34, v51, v50
	v_div_fmas_f32 v34, v34, v35, v51
	v_div_fixup_f32 v0, v34, v0, 1.0
	v_mul_f32_e32 v34, 0xbfb8aa3b, v36
	v_exp_f32_e32 v34, v34
	v_fma_f32 v0, v0, s80, 0.5
	v_cvt_u32_f32_e32 v0, v0
	v_add_f32_e32 v34, 1.0, v34
	v_div_scale_f32 v35, s[0:1], v34, v34, 1.0
	v_rcp_f32_e32 v36, v35
	v_lshl_or_b32 v130, v0, 8, v128
	v_mul_f32_e32 v0, 0xbfb8aa3b, v38
	v_exp_f32_e32 v0, v0
	v_fma_f32 v50, -v35, v36, 1.0
	v_fmac_f32_e32 v36, v50, v36
	v_div_scale_f32 v50, vcc, 1.0, v34, 1.0
	v_mul_f32_e32 v51, v50, v36
	v_fma_f32 v52, -v35, v51, v50
	v_fmac_f32_e32 v51, v52, v36
	v_fma_f32 v35, -v35, v51, v50
	v_div_fmas_f32 v35, v35, v36, v51
	v_div_fixup_f32 v34, v35, v34, 1.0
	v_mul_f32_e32 v35, 0xbfb8aa3b, v37
	v_exp_f32_e32 v35, v35
	v_fma_f32 v34, v34, s80, 0.5
	v_cvt_u32_f32_sdwa v34, v34 dst_sel:WORD_1 dst_unused:UNUSED_PAD src0_sel:DWORD
	v_add_f32_e32 v0, 1.0, v0
	v_add_f32_e32 v35, 1.0, v35
	v_div_scale_f32 v36, s[0:1], v35, v35, 1.0
	v_rcp_f32_e32 v37, v36
	s_nop 0
	v_fma_f32 v50, -v36, v37, 1.0
	v_fmac_f32_e32 v37, v50, v37
	v_div_scale_f32 v50, vcc, 1.0, v35, 1.0
	v_mul_f32_e32 v51, v50, v37
	v_fma_f32 v52, -v36, v51, v50
	v_fmac_f32_e32 v51, v52, v37
	v_fma_f32 v36, -v36, v51, v50
	v_div_fmas_f32 v36, v36, v37, v51
	v_div_fixup_f32 v35, v36, v35, 1.0
	v_fma_f32 v35, v35, s80, 0.5
	v_cvt_u32_f32_sdwa v35, v35 dst_sel:BYTE_3 dst_unused:UNUSED_PAD src0_sel:DWORD
	s_nop 0
	v_or3_b32 v129, v34, v35, v130
	v_div_scale_f32 v34, s[0:1], v0, v0, 1.0
	v_rcp_f32_e32 v35, v34
	s_nop 0
	v_fma_f32 v36, -v34, v35, 1.0
	v_fmac_f32_e32 v35, v36, v35
	v_div_scale_f32 v36, vcc, 1.0, v0, 1.0
	v_mul_f32_e32 v37, v36, v35
	v_fma_f32 v38, -v34, v37, v36
	v_fmac_f32_e32 v37, v38, v35
	v_fma_f32 v34, -v34, v37, v36
	v_div_fmas_f32 v34, v34, v35, v37
	v_div_fixup_f32 v0, v34, v0, 1.0
	v_fma_f32 v0, v0, s80, 0.5
	v_cvt_u32_f32_e32 v131, v0
	v_mul_f32_e32 v0, 0xbfb8aa3b, v39
	v_exp_f32_e32 v0, v0
	s_nop 0
	v_add_f32_e32 v0, 1.0, v0
	v_div_scale_f32 v34, s[0:1], v0, v0, 1.0
	v_rcp_f32_e32 v35, v34
	s_nop 0
	v_fma_f32 v36, -v34, v35, 1.0
	v_fmac_f32_e32 v35, v36, v35
	v_div_scale_f32 v36, vcc, 1.0, v0, 1.0
	v_mul_f32_e32 v37, v36, v35
	v_fma_f32 v38, -v34, v37, v36
	v_fmac_f32_e32 v37, v38, v35
	v_fma_f32 v34, -v34, v37, v36
	v_div_fmas_f32 v34, v34, v35, v37
	v_div_fixup_f32 v0, v34, v0, 1.0
	v_mul_f32_e32 v34, 0xbfb8aa3b, v40
	v_exp_f32_e32 v34, v34
	v_fma_f32 v0, v0, s80, 0.5
	v_cvt_u32_f32_e32 v0, v0
	v_add_f32_e32 v34, 1.0, v34
	v_div_scale_f32 v35, s[0:1], v34, v34, 1.0
	v_rcp_f32_e32 v36, v35
	v_lshl_or_b32 v133, v0, 8, v131
	v_mul_f32_e32 v0, 0xbfb8aa3b, v42
	v_exp_f32_e32 v0, v0
	v_fma_f32 v37, -v35, v36, 1.0
	v_fmac_f32_e32 v36, v37, v36
	v_div_scale_f32 v37, vcc, 1.0, v34, 1.0
	v_mul_f32_e32 v38, v37, v36
	v_fma_f32 v39, -v35, v38, v37
	v_fmac_f32_e32 v38, v39, v36
	v_fma_f32 v35, -v35, v38, v37
	v_div_fmas_f32 v35, v35, v36, v38
	v_div_fixup_f32 v34, v35, v34, 1.0
	v_mul_f32_e32 v35, 0xbfb8aa3b, v41
	v_exp_f32_e32 v35, v35
	v_fma_f32 v34, v34, s80, 0.5
	v_cvt_u32_f32_sdwa v34, v34 dst_sel:WORD_1 dst_unused:UNUSED_PAD src0_sel:DWORD
	v_add_f32_e32 v0, 1.0, v0
	v_add_f32_e32 v35, 1.0, v35
	v_div_scale_f32 v36, s[0:1], v35, v35, 1.0
	v_rcp_f32_e32 v37, v36
	s_nop 0
	v_fma_f32 v38, -v36, v37, 1.0
	v_fmac_f32_e32 v37, v38, v37
	v_div_scale_f32 v38, vcc, 1.0, v35, 1.0
	v_mul_f32_e32 v39, v38, v37
	v_fma_f32 v40, -v36, v39, v38
	v_fmac_f32_e32 v39, v40, v37
	v_fma_f32 v36, -v36, v39, v38
	v_div_fmas_f32 v36, v36, v37, v39
	v_div_fixup_f32 v35, v36, v35, 1.0
	v_fma_f32 v35, v35, s80, 0.5
	v_cvt_u32_f32_sdwa v35, v35 dst_sel:BYTE_3 dst_unused:UNUSED_PAD src0_sel:DWORD
	s_nop 0
	v_or3_b32 v132, v34, v35, v133
	v_div_scale_f32 v34, s[0:1], v0, v0, 1.0
	v_rcp_f32_e32 v35, v34
	s_nop 0
	v_fma_f32 v36, -v34, v35, 1.0
	v_fmac_f32_e32 v35, v36, v35
	v_div_scale_f32 v36, vcc, 1.0, v0, 1.0
	v_mul_f32_e32 v37, v36, v35
	v_fma_f32 v38, -v34, v37, v36
	v_fmac_f32_e32 v37, v38, v35
	v_fma_f32 v34, -v34, v37, v36
	v_div_fmas_f32 v34, v34, v35, v37
	v_div_fixup_f32 v0, v34, v0, 1.0
	v_fma_f32 v0, v0, s80, 0.5
	v_cvt_u32_f32_e32 v134, v0
	v_mul_f32_e32 v0, 0xbfb8aa3b, v43
	v_exp_f32_e32 v0, v0
	s_nop 0
	v_add_f32_e32 v0, 1.0, v0
	v_div_scale_f32 v34, s[0:1], v0, v0, 1.0
	v_rcp_f32_e32 v35, v34
	s_nop 0
	v_fma_f32 v36, -v34, v35, 1.0
	v_fmac_f32_e32 v35, v36, v35
	v_div_scale_f32 v36, vcc, 1.0, v0, 1.0
	v_mul_f32_e32 v37, v36, v35
	v_fma_f32 v38, -v34, v37, v36
	v_fmac_f32_e32 v37, v38, v35
	v_fma_f32 v34, -v34, v37, v36
	v_div_fmas_f32 v34, v34, v35, v37
	v_div_fixup_f32 v0, v34, v0, 1.0
	v_mul_f32_e32 v34, 0xbfb8aa3b, v44
	v_exp_f32_e32 v34, v34
	v_fma_f32 v0, v0, s80, 0.5
	v_cvt_u32_f32_e32 v0, v0
	v_add_f32_e32 v34, 1.0, v34
	v_div_scale_f32 v35, s[0:1], v34, v34, 1.0
	v_rcp_f32_e32 v36, v35
	v_lshl_or_b32 v136, v0, 8, v134
	v_mul_f32_e32 v0, 0xbfb8aa3b, v46
	v_exp_f32_e32 v0, v0
	v_fma_f32 v37, -v35, v36, 1.0
	v_fmac_f32_e32 v36, v37, v36
	v_div_scale_f32 v37, vcc, 1.0, v34, 1.0
	v_mul_f32_e32 v38, v37, v36
	v_fma_f32 v39, -v35, v38, v37
	v_fmac_f32_e32 v38, v39, v36
	v_fma_f32 v35, -v35, v38, v37
	v_div_fmas_f32 v35, v35, v36, v38
	v_div_fixup_f32 v34, v35, v34, 1.0
	v_mul_f32_e32 v35, 0xbfb8aa3b, v45
	v_exp_f32_e32 v35, v35
	v_fma_f32 v34, v34, s80, 0.5
	v_cvt_u32_f32_sdwa v34, v34 dst_sel:WORD_1 dst_unused:UNUSED_PAD src0_sel:DWORD
	v_add_f32_e32 v0, 1.0, v0
	v_add_f32_e32 v35, 1.0, v35
	v_div_scale_f32 v36, s[0:1], v35, v35, 1.0
	v_rcp_f32_e32 v37, v36
	s_nop 0
	v_fma_f32 v38, -v36, v37, 1.0
	v_fmac_f32_e32 v37, v38, v37
	v_div_scale_f32 v38, vcc, 1.0, v35, 1.0
	v_mul_f32_e32 v39, v38, v37
	v_fma_f32 v40, -v36, v39, v38
	v_fmac_f32_e32 v39, v40, v37
	v_fma_f32 v36, -v36, v39, v38
	v_div_fmas_f32 v36, v36, v37, v39
	v_div_fixup_f32 v35, v36, v35, 1.0
	v_fma_f32 v35, v35, s80, 0.5
	v_cvt_u32_f32_sdwa v35, v35 dst_sel:BYTE_3 dst_unused:UNUSED_PAD src0_sel:DWORD
	s_nop 0
	v_or3_b32 v135, v34, v35, v136
	v_div_scale_f32 v34, s[0:1], v0, v0, 1.0
	v_rcp_f32_e32 v35, v34
	s_nop 0
	v_fma_f32 v36, -v34, v35, 1.0
	v_fmac_f32_e32 v35, v36, v35
	v_div_scale_f32 v36, vcc, 1.0, v0, 1.0
	v_mul_f32_e32 v37, v36, v35
	v_fma_f32 v38, -v34, v37, v36
	v_fmac_f32_e32 v37, v38, v35
	v_fma_f32 v34, -v34, v37, v36
	v_div_fmas_f32 v34, v34, v35, v37
	v_div_fixup_f32 v0, v34, v0, 1.0
	v_fma_f32 v0, v0, s80, 0.5
	v_cvt_u32_f32_e32 v137, v0
	v_mul_f32_e32 v0, 0xbfb8aa3b, v47
	v_exp_f32_e32 v0, v0
	s_nop 0
	v_add_f32_e32 v0, 1.0, v0
	v_div_scale_f32 v34, s[0:1], v0, v0, 1.0
	v_rcp_f32_e32 v35, v34
	s_nop 0
	v_fma_f32 v36, -v34, v35, 1.0
	v_fmac_f32_e32 v35, v36, v35
	v_div_scale_f32 v36, vcc, 1.0, v0, 1.0
	v_mul_f32_e32 v37, v36, v35
	v_fma_f32 v38, -v34, v37, v36
	v_fmac_f32_e32 v37, v38, v35
	v_fma_f32 v34, -v34, v37, v36
	v_div_fmas_f32 v34, v34, v35, v37
	v_div_fixup_f32 v0, v34, v0, 1.0
	v_mul_f32_e32 v34, 0xbfb8aa3b, v48
	v_exp_f32_e32 v34, v34
	v_fma_f32 v0, v0, s80, 0.5
	v_cvt_u32_f32_e32 v0, v0
	v_add_f32_e32 v34, 1.0, v34
	v_div_scale_f32 v35, s[0:1], v34, v34, 1.0
	v_rcp_f32_e32 v36, v35
	v_lshl_or_b32 v139, v0, 8, v137
	v_mul_f32_e32 v0, 0xbfb8aa3b, v18
	v_exp_f32_e32 v0, v0
	v_fma_f32 v37, -v35, v36, 1.0
	v_fmac_f32_e32 v36, v37, v36
	v_div_scale_f32 v37, vcc, 1.0, v34, 1.0
	v_mul_f32_e32 v38, v37, v36
	v_fma_f32 v39, -v35, v38, v37
	v_fmac_f32_e32 v38, v39, v36
	v_fma_f32 v35, -v35, v38, v37
	v_div_fmas_f32 v35, v35, v36, v38
	v_div_fixup_f32 v34, v35, v34, 1.0
	v_mul_f32_e32 v35, 0xbfb8aa3b, v49
	v_exp_f32_e32 v35, v35
	v_fma_f32 v34, v34, s80, 0.5
	v_cvt_u32_f32_sdwa v34, v34 dst_sel:WORD_1 dst_unused:UNUSED_PAD src0_sel:DWORD
	v_add_f32_e32 v0, 1.0, v0
	v_add_f32_e32 v35, 1.0, v35
	v_div_scale_f32 v36, s[0:1], v35, v35, 1.0
	v_rcp_f32_e32 v37, v36
	v_div_scale_f32 v18, s[0:1], v0, v0, 1.0
	v_fma_f32 v38, -v36, v37, 1.0
	v_fmac_f32_e32 v37, v38, v37
	v_div_scale_f32 v38, vcc, 1.0, v35, 1.0
	v_mul_f32_e32 v39, v38, v37
	v_fma_f32 v40, -v36, v39, v38
	v_fmac_f32_e32 v39, v40, v37
	v_fma_f32 v36, -v36, v39, v38
	v_div_fmas_f32 v36, v36, v37, v39
	v_div_fixup_f32 v35, v36, v35, 1.0
	v_fma_f32 v35, v35, s80, 0.5
	v_cvt_u32_f32_sdwa v35, v35 dst_sel:BYTE_3 dst_unused:UNUSED_PAD src0_sel:DWORD
	s_nop 0
	v_or3_b32 v138, v34, v35, v139
	v_rcp_f32_e32 v34, v18
	s_nop 0
	v_fma_f32 v35, -v18, v34, 1.0
	v_fmac_f32_e32 v34, v35, v34
	v_div_scale_f32 v35, vcc, 1.0, v0, 1.0
	v_mul_f32_e32 v36, v35, v34
	v_fma_f32 v37, -v18, v36, v35
	v_fmac_f32_e32 v36, v37, v34
	v_fma_f32 v18, -v18, v36, v35
	v_div_fmas_f32 v18, v18, v34, v36
	v_div_fixup_f32 v0, v18, v0, 1.0
	v_fma_f32 v0, v0, s80, 0.5
	v_cvt_u32_f32_e32 v140, v0
	v_mul_f32_e32 v0, 0xbfb8aa3b, v19
	v_exp_f32_e32 v0, v0
	s_nop 0
	v_add_f32_e32 v0, 1.0, v0
	v_div_scale_f32 v18, s[0:1], v0, v0, 1.0
	v_rcp_f32_e32 v19, v18
	s_nop 0
	v_fma_f32 v34, -v18, v19, 1.0
	v_fmac_f32_e32 v19, v34, v19
	v_div_scale_f32 v34, vcc, 1.0, v0, 1.0
	v_mul_f32_e32 v35, v34, v19
	v_fma_f32 v36, -v18, v35, v34
	v_fmac_f32_e32 v35, v36, v19
	v_fma_f32 v18, -v18, v35, v34
	v_div_fmas_f32 v18, v18, v19, v35
	v_div_fixup_f32 v0, v18, v0, 1.0
	v_mul_f32_e32 v18, 0xbfb8aa3b, v20
	v_exp_f32_e32 v18, v18
	v_fma_f32 v0, v0, s80, 0.5
	v_cvt_u32_f32_e32 v0, v0
	v_add_f32_e32 v18, 1.0, v18
	v_div_scale_f32 v19, s[0:1], v18, v18, 1.0
	v_rcp_f32_e32 v20, v19
	v_lshl_or_b32 v142, v0, 8, v140
	v_mul_f32_e32 v0, 0xbfb8aa3b, v22
	v_exp_f32_e32 v0, v0
	v_fma_f32 v34, -v19, v20, 1.0
	v_fmac_f32_e32 v20, v34, v20
	v_div_scale_f32 v34, vcc, 1.0, v18, 1.0
	v_mul_f32_e32 v35, v34, v20
	v_fma_f32 v36, -v19, v35, v34
	v_fmac_f32_e32 v35, v36, v20
	v_fma_f32 v19, -v19, v35, v34
	v_div_fmas_f32 v19, v19, v20, v35
	v_div_fixup_f32 v18, v19, v18, 1.0
	v_mul_f32_e32 v19, 0xbfb8aa3b, v21
	v_exp_f32_e32 v19, v19
	v_fma_f32 v18, v18, s80, 0.5
	v_cvt_u32_f32_sdwa v18, v18 dst_sel:WORD_1 dst_unused:UNUSED_PAD src0_sel:DWORD
	v_add_f32_e32 v0, 1.0, v0
	v_add_f32_e32 v19, 1.0, v19
	v_div_scale_f32 v20, s[0:1], v19, v19, 1.0
	v_rcp_f32_e32 v21, v20
	s_nop 0
	v_fma_f32 v34, -v20, v21, 1.0
	v_fmac_f32_e32 v21, v34, v21
	v_div_scale_f32 v34, vcc, 1.0, v19, 1.0
	v_mul_f32_e32 v35, v34, v21
	v_fma_f32 v36, -v20, v35, v34
	v_fmac_f32_e32 v35, v36, v21
	v_fma_f32 v20, -v20, v35, v34
	v_div_fmas_f32 v20, v20, v21, v35
	v_div_fixup_f32 v19, v20, v19, 1.0
	v_fma_f32 v19, v19, s80, 0.5
	v_cvt_u32_f32_sdwa v19, v19 dst_sel:BYTE_3 dst_unused:UNUSED_PAD src0_sel:DWORD
	s_nop 0
	v_or3_b32 v141, v18, v19, v142
	v_div_scale_f32 v18, s[0:1], v0, v0, 1.0
	v_rcp_f32_e32 v19, v18
	s_nop 0
	v_fma_f32 v20, -v18, v19, 1.0
	v_fmac_f32_e32 v19, v20, v19
	v_div_scale_f32 v20, vcc, 1.0, v0, 1.0
	v_mul_f32_e32 v21, v20, v19
	v_fma_f32 v22, -v18, v21, v20
	v_fmac_f32_e32 v21, v22, v19
	v_fma_f32 v18, -v18, v21, v20
	v_div_fmas_f32 v18, v18, v19, v21
	v_div_fixup_f32 v0, v18, v0, 1.0
	v_fma_f32 v0, v0, s80, 0.5
	v_cvt_u32_f32_e32 v143, v0
	v_mul_f32_e32 v0, 0xbfb8aa3b, v23
	v_exp_f32_e32 v0, v0
	s_nop 0
	v_add_f32_e32 v0, 1.0, v0
	v_div_scale_f32 v18, s[0:1], v0, v0, 1.0
	v_rcp_f32_e32 v19, v18
	s_nop 0
	v_fma_f32 v20, -v18, v19, 1.0
	v_fmac_f32_e32 v19, v20, v19
	v_div_scale_f32 v20, vcc, 1.0, v0, 1.0
	v_mul_f32_e32 v21, v20, v19
	v_fma_f32 v22, -v18, v21, v20
	v_fmac_f32_e32 v21, v22, v19
	v_fma_f32 v18, -v18, v21, v20
	v_div_fmas_f32 v18, v18, v19, v21
	v_div_fixup_f32 v0, v18, v0, 1.0
	v_mul_f32_e32 v18, 0xbfb8aa3b, v24
	v_exp_f32_e32 v18, v18
	v_fma_f32 v0, v0, s80, 0.5
	v_cvt_u32_f32_e32 v0, v0
	v_add_f32_e32 v18, 1.0, v18
	v_div_scale_f32 v19, s[0:1], v18, v18, 1.0
	v_rcp_f32_e32 v20, v19
	v_lshl_or_b32 v145, v0, 8, v143
	v_mul_f32_e32 v0, 0xbfb8aa3b, v26
	v_exp_f32_e32 v0, v0
	v_fma_f32 v21, -v19, v20, 1.0
	v_fmac_f32_e32 v20, v21, v20
	v_div_scale_f32 v21, vcc, 1.0, v18, 1.0
	v_mul_f32_e32 v22, v21, v20
	v_fma_f32 v23, -v19, v22, v21
	v_fmac_f32_e32 v22, v23, v20
	v_fma_f32 v19, -v19, v22, v21
	v_div_fmas_f32 v19, v19, v20, v22
	v_div_fixup_f32 v18, v19, v18, 1.0
	v_mul_f32_e32 v19, 0xbfb8aa3b, v25
	v_exp_f32_e32 v19, v19
	v_fma_f32 v18, v18, s80, 0.5
	v_cvt_u32_f32_sdwa v18, v18 dst_sel:WORD_1 dst_unused:UNUSED_PAD src0_sel:DWORD
	v_add_f32_e32 v0, 1.0, v0
	v_add_f32_e32 v19, 1.0, v19
	v_div_scale_f32 v20, s[0:1], v19, v19, 1.0
	v_rcp_f32_e32 v21, v20
	s_nop 0
	v_fma_f32 v22, -v20, v21, 1.0
	v_fmac_f32_e32 v21, v22, v21
	v_div_scale_f32 v22, vcc, 1.0, v19, 1.0
	v_mul_f32_e32 v23, v22, v21
	v_fma_f32 v24, -v20, v23, v22
	v_fmac_f32_e32 v23, v24, v21
	v_fma_f32 v20, -v20, v23, v22
	v_div_fmas_f32 v20, v20, v21, v23
	v_div_fixup_f32 v19, v20, v19, 1.0
	v_fma_f32 v19, v19, s80, 0.5
	v_cvt_u32_f32_sdwa v19, v19 dst_sel:BYTE_3 dst_unused:UNUSED_PAD src0_sel:DWORD
	s_nop 0
	v_or3_b32 v144, v18, v19, v145
	v_div_scale_f32 v18, s[0:1], v0, v0, 1.0
	v_rcp_f32_e32 v19, v18
	s_nop 0
	v_fma_f32 v20, -v18, v19, 1.0
	v_fmac_f32_e32 v19, v20, v19
	v_div_scale_f32 v20, vcc, 1.0, v0, 1.0
	v_mul_f32_e32 v21, v20, v19
	v_fma_f32 v22, -v18, v21, v20
	v_fmac_f32_e32 v21, v22, v19
	v_fma_f32 v18, -v18, v21, v20
	v_div_fmas_f32 v18, v18, v19, v21
	v_div_fixup_f32 v0, v18, v0, 1.0
	v_fma_f32 v0, v0, s80, 0.5
	v_cvt_u32_f32_e32 v146, v0
	v_mul_f32_e32 v0, 0xbfb8aa3b, v27
	v_exp_f32_e32 v0, v0
	s_nop 0
	v_add_f32_e32 v0, 1.0, v0
	v_div_scale_f32 v18, s[0:1], v0, v0, 1.0
	v_rcp_f32_e32 v19, v18
	s_nop 0
	v_fma_f32 v20, -v18, v19, 1.0
	v_fmac_f32_e32 v19, v20, v19
	v_div_scale_f32 v20, vcc, 1.0, v0, 1.0
	v_mul_f32_e32 v21, v20, v19
	v_fma_f32 v22, -v18, v21, v20
	v_fmac_f32_e32 v21, v22, v19
	v_fma_f32 v18, -v18, v21, v20
	v_div_fmas_f32 v18, v18, v19, v21
	v_div_fixup_f32 v0, v18, v0, 1.0
	v_mul_f32_e32 v18, 0xbfb8aa3b, v28
	v_exp_f32_e32 v18, v18
	v_fma_f32 v0, v0, s80, 0.5
	v_cvt_u32_f32_e32 v0, v0
	v_add_f32_e32 v18, 1.0, v18
	v_div_scale_f32 v19, s[0:1], v18, v18, 1.0
	v_rcp_f32_e32 v20, v19
	v_lshl_or_b32 v148, v0, 8, v146
	v_mul_f32_e32 v0, 0xbfb8aa3b, v30
	v_exp_f32_e32 v0, v0
	v_fma_f32 v21, -v19, v20, 1.0
	v_fmac_f32_e32 v20, v21, v20
	v_div_scale_f32 v21, vcc, 1.0, v18, 1.0
	v_mul_f32_e32 v22, v21, v20
	v_fma_f32 v23, -v19, v22, v21
	v_fmac_f32_e32 v22, v23, v20
	v_fma_f32 v19, -v19, v22, v21
	v_div_fmas_f32 v19, v19, v20, v22
	v_div_fixup_f32 v18, v19, v18, 1.0
	v_mul_f32_e32 v19, 0xbfb8aa3b, v29
	v_exp_f32_e32 v19, v19
	v_fma_f32 v18, v18, s80, 0.5
	v_cvt_u32_f32_sdwa v18, v18 dst_sel:WORD_1 dst_unused:UNUSED_PAD src0_sel:DWORD
	v_add_f32_e32 v0, 1.0, v0
	v_add_f32_e32 v19, 1.0, v19
	v_div_scale_f32 v20, s[0:1], v19, v19, 1.0
	v_rcp_f32_e32 v21, v20
	s_nop 0
	v_fma_f32 v22, -v20, v21, 1.0
	v_fmac_f32_e32 v21, v22, v21
	v_div_scale_f32 v22, vcc, 1.0, v19, 1.0
	v_mul_f32_e32 v23, v22, v21
	v_fma_f32 v24, -v20, v23, v22
	v_fmac_f32_e32 v23, v24, v21
	v_fma_f32 v20, -v20, v23, v22
	v_div_fmas_f32 v20, v20, v21, v23
	v_div_fixup_f32 v19, v20, v19, 1.0
	v_fma_f32 v19, v19, s80, 0.5
	v_cvt_u32_f32_sdwa v19, v19 dst_sel:BYTE_3 dst_unused:UNUSED_PAD src0_sel:DWORD
	s_nop 0
	v_or3_b32 v147, v18, v19, v148
	v_div_scale_f32 v18, s[0:1], v0, v0, 1.0
	v_rcp_f32_e32 v19, v18
	s_nop 0
	v_fma_f32 v20, -v18, v19, 1.0
	v_fmac_f32_e32 v19, v20, v19
	v_div_scale_f32 v20, vcc, 1.0, v0, 1.0
	v_mul_f32_e32 v21, v20, v19
	v_fma_f32 v22, -v18, v21, v20
	v_fmac_f32_e32 v21, v22, v19
	v_fma_f32 v18, -v18, v21, v20
	v_div_fmas_f32 v18, v18, v19, v21
	v_div_fixup_f32 v0, v18, v0, 1.0
	v_fma_f32 v0, v0, s80, 0.5
	v_cvt_u32_f32_e32 v149, v0
	v_mul_f32_e32 v0, 0xbfb8aa3b, v31
	v_exp_f32_e32 v0, v0
	s_nop 0
	v_add_f32_e32 v0, 1.0, v0
	v_div_scale_f32 v18, s[0:1], v0, v0, 1.0
	v_rcp_f32_e32 v19, v18
	s_nop 0
	v_fma_f32 v20, -v18, v19, 1.0
	v_fmac_f32_e32 v19, v20, v19
	v_div_scale_f32 v20, vcc, 1.0, v0, 1.0
	v_mul_f32_e32 v21, v20, v19
	v_fma_f32 v22, -v18, v21, v20
	v_fmac_f32_e32 v21, v22, v19
	v_fma_f32 v18, -v18, v21, v20
	v_div_fmas_f32 v18, v18, v19, v21
	v_div_fixup_f32 v0, v18, v0, 1.0
	v_mul_f32_e32 v18, 0xbfb8aa3b, v32
	v_exp_f32_e32 v18, v18
	v_fma_f32 v0, v0, s80, 0.5
	v_cvt_u32_f32_e32 v0, v0
	v_add_f32_e32 v18, 1.0, v18
	v_div_scale_f32 v19, s[0:1], v18, v18, 1.0
	v_rcp_f32_e32 v20, v19
	v_lshl_or_b32 v151, v0, 8, v149
	v_mul_f32_e32 v0, 0xbfb8aa3b, v2
	v_exp_f32_e32 v0, v0
	v_fma_f32 v21, -v19, v20, 1.0
	v_fmac_f32_e32 v20, v21, v20
	v_div_scale_f32 v21, vcc, 1.0, v18, 1.0
	v_mul_f32_e32 v22, v21, v20
	v_fma_f32 v23, -v19, v22, v21
	v_fmac_f32_e32 v22, v23, v20
	v_fma_f32 v19, -v19, v22, v21
	v_div_fmas_f32 v19, v19, v20, v22
	v_div_fixup_f32 v18, v19, v18, 1.0
	v_mul_f32_e32 v19, 0xbfb8aa3b, v33
	v_exp_f32_e32 v19, v19
	v_fma_f32 v18, v18, s80, 0.5
	v_cvt_u32_f32_sdwa v18, v18 dst_sel:WORD_1 dst_unused:UNUSED_PAD src0_sel:DWORD
	v_add_f32_e32 v0, 1.0, v0
	v_add_f32_e32 v19, 1.0, v19
	v_div_scale_f32 v20, s[0:1], v19, v19, 1.0
	v_rcp_f32_e32 v21, v20
	v_div_scale_f32 v2, s[0:1], v0, v0, 1.0
	v_fma_f32 v22, -v20, v21, 1.0
	v_fmac_f32_e32 v21, v22, v21
	v_div_scale_f32 v22, vcc, 1.0, v19, 1.0
	v_mul_f32_e32 v23, v22, v21
	v_fma_f32 v24, -v20, v23, v22
	v_fmac_f32_e32 v23, v24, v21
	v_fma_f32 v20, -v20, v23, v22
	v_div_fmas_f32 v20, v20, v21, v23
	v_div_fixup_f32 v19, v20, v19, 1.0
	v_fma_f32 v19, v19, s80, 0.5
	v_cvt_u32_f32_sdwa v19, v19 dst_sel:BYTE_3 dst_unused:UNUSED_PAD src0_sel:DWORD
	s_nop 0
	v_or3_b32 v150, v18, v19, v151
	v_rcp_f32_e32 v18, v2
	s_nop 0
	v_fma_f32 v19, -v2, v18, 1.0
	v_fmac_f32_e32 v18, v19, v18
	v_div_scale_f32 v19, vcc, 1.0, v0, 1.0
	v_mul_f32_e32 v20, v19, v18
	v_fma_f32 v21, -v2, v20, v19
	v_fmac_f32_e32 v20, v21, v18
	v_fma_f32 v2, -v2, v20, v19
	v_div_fmas_f32 v2, v2, v18, v20
	v_div_fixup_f32 v0, v2, v0, 1.0
	v_fma_f32 v0, v0, s80, 0.5
	v_cvt_u32_f32_e32 v152, v0
	v_mul_f32_e32 v0, 0xbfb8aa3b, v3
	v_exp_f32_e32 v0, v0
	s_nop 0
	v_add_f32_e32 v0, 1.0, v0
	v_div_scale_f32 v2, s[0:1], v0, v0, 1.0
	v_rcp_f32_e32 v3, v2
	s_nop 0
	v_fma_f32 v18, -v2, v3, 1.0
	v_fmac_f32_e32 v3, v18, v3
	v_div_scale_f32 v18, vcc, 1.0, v0, 1.0
	v_mul_f32_e32 v19, v18, v3
	v_fma_f32 v20, -v2, v19, v18
	v_fmac_f32_e32 v19, v20, v3
	v_fma_f32 v2, -v2, v19, v18
	v_div_fmas_f32 v2, v2, v3, v19
	v_div_fixup_f32 v0, v2, v0, 1.0
	v_mul_f32_e32 v2, 0xbfb8aa3b, v4
	v_exp_f32_e32 v2, v2
	v_fma_f32 v0, v0, s80, 0.5
	v_cvt_u32_f32_e32 v0, v0
	v_add_f32_e32 v2, 1.0, v2
	v_div_scale_f32 v3, s[0:1], v2, v2, 1.0
	v_rcp_f32_e32 v4, v3
	v_lshl_or_b32 v154, v0, 8, v152
	v_mul_f32_e32 v0, 0xbfb8aa3b, v6
	v_exp_f32_e32 v0, v0
	v_fma_f32 v18, -v3, v4, 1.0
	v_fmac_f32_e32 v4, v18, v4
	v_div_scale_f32 v18, vcc, 1.0, v2, 1.0
	v_mul_f32_e32 v19, v18, v4
	v_fma_f32 v20, -v3, v19, v18
	v_fmac_f32_e32 v19, v20, v4
	v_fma_f32 v3, -v3, v19, v18
	v_div_fmas_f32 v3, v3, v4, v19
	v_div_fixup_f32 v2, v3, v2, 1.0
	v_mul_f32_e32 v3, 0xbfb8aa3b, v5
	v_exp_f32_e32 v3, v3
	v_fma_f32 v2, v2, s80, 0.5
	v_cvt_u32_f32_sdwa v2, v2 dst_sel:WORD_1 dst_unused:UNUSED_PAD src0_sel:DWORD
	v_add_f32_e32 v0, 1.0, v0
	v_add_f32_e32 v3, 1.0, v3
	v_div_scale_f32 v4, s[0:1], v3, v3, 1.0
	v_rcp_f32_e32 v5, v4
	s_nop 0
	v_fma_f32 v18, -v4, v5, 1.0
	v_fmac_f32_e32 v5, v18, v5
	v_div_scale_f32 v18, vcc, 1.0, v3, 1.0
	v_mul_f32_e32 v19, v18, v5
	v_fma_f32 v20, -v4, v19, v18
	v_fmac_f32_e32 v19, v20, v5
	v_fma_f32 v4, -v4, v19, v18
	v_div_fmas_f32 v4, v4, v5, v19
	v_div_fixup_f32 v3, v4, v3, 1.0
	v_fma_f32 v3, v3, s80, 0.5
	v_cvt_u32_f32_sdwa v3, v3 dst_sel:BYTE_3 dst_unused:UNUSED_PAD src0_sel:DWORD
	s_nop 0
	v_or3_b32 v153, v2, v3, v154
	v_div_scale_f32 v2, s[0:1], v0, v0, 1.0
	v_rcp_f32_e32 v3, v2
	s_nop 0
	v_fma_f32 v4, -v2, v3, 1.0
	v_fmac_f32_e32 v3, v4, v3
	v_div_scale_f32 v4, vcc, 1.0, v0, 1.0
	v_mul_f32_e32 v5, v4, v3
	v_fma_f32 v6, -v2, v5, v4
	v_fmac_f32_e32 v5, v6, v3
	v_fma_f32 v2, -v2, v5, v4
	v_div_fmas_f32 v2, v2, v3, v5
	v_div_fixup_f32 v0, v2, v0, 1.0
	v_fma_f32 v0, v0, s80, 0.5
	v_cvt_u32_f32_e32 v155, v0
	v_mul_f32_e32 v0, 0xbfb8aa3b, v7
	v_exp_f32_e32 v0, v0
	s_nop 0
	v_add_f32_e32 v0, 1.0, v0
	v_div_scale_f32 v2, s[0:1], v0, v0, 1.0
	v_rcp_f32_e32 v3, v2
	s_nop 0
	v_fma_f32 v4, -v2, v3, 1.0
	v_fmac_f32_e32 v3, v4, v3
	v_div_scale_f32 v4, vcc, 1.0, v0, 1.0
	v_mul_f32_e32 v5, v4, v3
	v_fma_f32 v6, -v2, v5, v4
	v_fmac_f32_e32 v5, v6, v3
	v_fma_f32 v2, -v2, v5, v4
	v_div_fmas_f32 v2, v2, v3, v5
	v_div_fixup_f32 v0, v2, v0, 1.0
	v_mul_f32_e32 v2, 0xbfb8aa3b, v8
	v_exp_f32_e32 v2, v2
	v_fma_f32 v0, v0, s80, 0.5
	v_cvt_u32_f32_e32 v0, v0
	v_add_f32_e32 v2, 1.0, v2
	v_div_scale_f32 v3, s[0:1], v2, v2, 1.0
	v_rcp_f32_e32 v4, v3
	v_lshl_or_b32 v157, v0, 8, v155
	v_mul_f32_e32 v0, 0xbfb8aa3b, v10
	v_exp_f32_e32 v0, v0
	v_fma_f32 v5, -v3, v4, 1.0
	v_fmac_f32_e32 v4, v5, v4
	v_div_scale_f32 v5, vcc, 1.0, v2, 1.0
	v_mul_f32_e32 v6, v5, v4
	v_fma_f32 v7, -v3, v6, v5
	v_fmac_f32_e32 v6, v7, v4
	v_fma_f32 v3, -v3, v6, v5
	v_div_fmas_f32 v3, v3, v4, v6
	v_div_fixup_f32 v2, v3, v2, 1.0
	v_mul_f32_e32 v3, 0xbfb8aa3b, v9
	v_exp_f32_e32 v3, v3
	v_fma_f32 v2, v2, s80, 0.5
	v_cvt_u32_f32_sdwa v2, v2 dst_sel:WORD_1 dst_unused:UNUSED_PAD src0_sel:DWORD
	v_add_f32_e32 v0, 1.0, v0
	v_add_f32_e32 v3, 1.0, v3
	v_div_scale_f32 v4, s[0:1], v3, v3, 1.0
	v_rcp_f32_e32 v5, v4
	s_nop 0
	v_fma_f32 v6, -v4, v5, 1.0
	v_fmac_f32_e32 v5, v6, v5
	v_div_scale_f32 v6, vcc, 1.0, v3, 1.0
	v_mul_f32_e32 v7, v6, v5
	v_fma_f32 v8, -v4, v7, v6
	v_fmac_f32_e32 v7, v8, v5
	v_fma_f32 v4, -v4, v7, v6
	v_div_fmas_f32 v4, v4, v5, v7
	v_div_fixup_f32 v3, v4, v3, 1.0
	v_fma_f32 v3, v3, s80, 0.5
	v_cvt_u32_f32_sdwa v3, v3 dst_sel:BYTE_3 dst_unused:UNUSED_PAD src0_sel:DWORD
	s_nop 0
	v_or3_b32 v156, v2, v3, v157
	v_div_scale_f32 v2, s[0:1], v0, v0, 1.0
	v_rcp_f32_e32 v3, v2
	s_nop 0
	v_fma_f32 v4, -v2, v3, 1.0
	v_fmac_f32_e32 v3, v4, v3
	v_div_scale_f32 v4, vcc, 1.0, v0, 1.0
	v_mul_f32_e32 v5, v4, v3
	v_fma_f32 v6, -v2, v5, v4
	v_fmac_f32_e32 v5, v6, v3
	v_fma_f32 v2, -v2, v5, v4
	v_div_fmas_f32 v2, v2, v3, v5
	v_div_fixup_f32 v0, v2, v0, 1.0
	v_fma_f32 v0, v0, s80, 0.5
	v_cvt_u32_f32_e32 v158, v0
	v_mul_f32_e32 v0, 0xbfb8aa3b, v11
	v_exp_f32_e32 v0, v0
	s_nop 0
	v_add_f32_e32 v0, 1.0, v0
	v_div_scale_f32 v2, s[0:1], v0, v0, 1.0
	v_rcp_f32_e32 v3, v2
	s_nop 0
	v_fma_f32 v4, -v2, v3, 1.0
	v_fmac_f32_e32 v3, v4, v3
	v_div_scale_f32 v4, vcc, 1.0, v0, 1.0
	v_mul_f32_e32 v5, v4, v3
	v_fma_f32 v6, -v2, v5, v4
	v_fmac_f32_e32 v5, v6, v3
	v_fma_f32 v2, -v2, v5, v4
	v_div_fmas_f32 v2, v2, v3, v5
	v_div_fixup_f32 v0, v2, v0, 1.0
	v_mul_f32_e32 v2, 0xbfb8aa3b, v12
	v_exp_f32_e32 v2, v2
	v_fma_f32 v0, v0, s80, 0.5
	v_cvt_u32_f32_e32 v0, v0
	v_add_f32_e32 v2, 1.0, v2
	v_div_scale_f32 v3, s[0:1], v2, v2, 1.0
	v_rcp_f32_e32 v4, v3
	v_lshl_or_b32 v160, v0, 8, v158
	v_mul_f32_e32 v0, 0xbfb8aa3b, v14
	v_exp_f32_e32 v0, v0
	v_fma_f32 v5, -v3, v4, 1.0
	v_fmac_f32_e32 v4, v5, v4
	v_div_scale_f32 v5, vcc, 1.0, v2, 1.0
	v_mul_f32_e32 v6, v5, v4
	v_fma_f32 v7, -v3, v6, v5
	v_fmac_f32_e32 v6, v7, v4
	v_fma_f32 v3, -v3, v6, v5
	v_div_fmas_f32 v3, v3, v4, v6
	v_div_fixup_f32 v2, v3, v2, 1.0
	v_mul_f32_e32 v3, 0xbfb8aa3b, v13
	v_exp_f32_e32 v3, v3
	v_fma_f32 v2, v2, s80, 0.5
	v_cvt_u32_f32_sdwa v2, v2 dst_sel:WORD_1 dst_unused:UNUSED_PAD src0_sel:DWORD
	v_add_f32_e32 v0, 1.0, v0
	v_add_f32_e32 v3, 1.0, v3
	v_div_scale_f32 v4, s[0:1], v3, v3, 1.0
	v_rcp_f32_e32 v5, v4
	s_nop 0
	v_fma_f32 v6, -v4, v5, 1.0
	v_fmac_f32_e32 v5, v6, v5
	v_div_scale_f32 v6, vcc, 1.0, v3, 1.0
	v_mul_f32_e32 v7, v6, v5
	v_fma_f32 v8, -v4, v7, v6
	v_fmac_f32_e32 v7, v8, v5
	v_fma_f32 v4, -v4, v7, v6
	v_div_fmas_f32 v4, v4, v5, v7
	v_div_fixup_f32 v3, v4, v3, 1.0
	v_fma_f32 v3, v3, s80, 0.5
	v_cvt_u32_f32_sdwa v3, v3 dst_sel:BYTE_3 dst_unused:UNUSED_PAD src0_sel:DWORD
	s_nop 0
	v_or3_b32 v159, v2, v3, v160
	v_div_scale_f32 v2, s[0:1], v0, v0, 1.0
	v_rcp_f32_e32 v3, v2
	s_nop 0
	v_fma_f32 v4, -v2, v3, 1.0
	v_fmac_f32_e32 v3, v4, v3
	v_div_scale_f32 v4, vcc, 1.0, v0, 1.0
	v_mul_f32_e32 v5, v4, v3
	v_fma_f32 v6, -v2, v5, v4
	v_fmac_f32_e32 v5, v6, v3
	v_fma_f32 v2, -v2, v5, v4
	v_div_fmas_f32 v2, v2, v3, v5
	v_div_fixup_f32 v0, v2, v0, 1.0
	v_fma_f32 v0, v0, s80, 0.5
	v_cvt_u32_f32_e32 v161, v0
	v_mul_f32_e32 v0, 0xbfb8aa3b, v15
	v_exp_f32_e32 v0, v0
	s_nop 0
	v_add_f32_e32 v0, 1.0, v0
	v_div_scale_f32 v2, s[0:1], v0, v0, 1.0
	v_rcp_f32_e32 v3, v2
	s_nop 0
	v_fma_f32 v4, -v2, v3, 1.0
	v_fmac_f32_e32 v3, v4, v3
	v_div_scale_f32 v4, vcc, 1.0, v0, 1.0
	v_mul_f32_e32 v5, v4, v3
	v_fma_f32 v6, -v2, v5, v4
	v_fmac_f32_e32 v5, v6, v3
	v_fma_f32 v2, -v2, v5, v4
	v_div_fmas_f32 v2, v2, v3, v5
	v_div_fixup_f32 v0, v2, v0, 1.0
	v_mul_f32_e32 v2, 0xbfb8aa3b, v16
	v_exp_f32_e32 v2, v2
	v_fma_f32 v0, v0, s80, 0.5
	v_cvt_u32_f32_e32 v0, v0
	v_add_f32_e32 v2, 1.0, v2
	v_div_scale_f32 v3, s[0:1], v2, v2, 1.0
	v_rcp_f32_e32 v4, v3
	v_lshl_or_b32 v163, v0, 8, v161
	v_fma_f32 v5, -v3, v4, 1.0
	v_fmac_f32_e32 v4, v5, v4
	v_div_scale_f32 v5, vcc, 1.0, v2, 1.0
	v_mul_f32_e32 v6, v5, v4
	v_fma_f32 v7, -v3, v6, v5
	v_fmac_f32_e32 v6, v7, v4
	v_fma_f32 v3, -v3, v6, v5
	v_div_fmas_f32 v3, v3, v4, v6
	v_div_fixup_f32 v2, v3, v2, 1.0
	v_mul_f32_e32 v3, 0xbfb8aa3b, v17
	v_exp_f32_e32 v3, v3
	v_fma_f32 v2, v2, s80, 0.5
	v_cvt_u32_f32_sdwa v2, v2 dst_sel:WORD_1 dst_unused:UNUSED_PAD src0_sel:DWORD
	v_add_f32_e32 v3, 1.0, v3
	v_div_scale_f32 v4, s[0:1], v3, v3, 1.0
	v_rcp_f32_e32 v5, v4
	s_movk_i32 s0, 0xaa0
	s_cselect_b32 s12, s0, 0x12a0
	s_mov_b32 s0, 0x12f0000
	v_fma_f32 v6, -v4, v5, 1.0
	v_fmac_f32_e32 v5, v6, v5
	v_div_scale_f32 v6, vcc, 1.0, v3, 1.0
	v_mul_f32_e32 v7, v6, v5
	v_fma_f32 v8, -v4, v7, v6
	v_fmac_f32_e32 v7, v8, v5
	v_fma_f32 v4, -v4, v7, v6
	v_div_fmas_f32 v4, v4, v5, v7
	s_cselect_b32 s13, s0, 0x13f0000
	s_cmp_eq_u32 s45, 0
	v_div_fixup_f32 v3, v4, v3, 1.0
	s_cselect_b64 vcc, -1, 0
	v_fma_f32 v3, v3, s80, 0.5
	s_and_b64 s[0:1], vcc, exec
	v_cvt_u32_f32_sdwa v3, v3 dst_sel:BYTE_3 dst_unused:UNUSED_PAD src0_sel:DWORD
	s_cselect_b32 s0, 0x2a0, s12
	s_cselect_b32 s13, 0x11f0000, s13
	s_lshl_b32 s0, s0, 1
	s_add_u32 s0, s43, s0
	v_mov_b32_e32 v6, v178
	s_addc_u32 s1, s44, 0
	v_or3_b32 v162, v2, v3, v163
	v_lshlrev_b32_e32 v0, 3, v6
	v_ashrrev_i32_e32 v2, 3, v6
	v_and_b32_e32 v36, 56, v0
	v_mov_b64_e32 v[4:5], s[0:1]
	s_add_u32 s12, s25, s13
	v_ashrrev_i32_e32 v3, 31, v2
	v_mad_i64_i32 v[4:5], s[0:1], v2, s77, v[4:5]
	v_lshlrev_b32_e32 v0, 1, v36
	s_addc_u32 s13, s42, 0
	v_lshl_add_u64 v[102:103], v[4:5], 0, v[0:1]
	v_lshlrev_b64 v[4:5], 10, v[2:3]
	v_lshl_add_u64 v[4:5], s[12:13], 0, v[4:5]
	v_and_b32_e32 v7, 31, v6
	v_lshl_add_u64 v[100:101], v[4:5], 0, v[0:1]
	v_lshrrev_b32_e32 v0, 1, v6
	v_and_or_b32 v3, v0, s35, v7
	v_and_b32_e32 v0, 16, v0
	v_mad_u64_u32 v[98:99], s[0:1], v3, s72, v[0:1]
	v_add_co_u32_e64 v104, s[0:1], s97, v102
	v_and_b32_e32 v3, 0x5f, v6
	s_nop 0
	v_addc_co_u32_e64 v105, s[0:1], 0, v103, s[0:1]
	v_add_co_u32_e64 v106, s[0:1], s31, v100
	global_load_dwordx4 v[4:7], v[102:103], off
	global_load_dwordx4 v[8:11], v[100:101], off
	v_addc_co_u32_e64 v107, s[0:1], 0, v101, s[0:1]
	v_add_co_u32_e64 v108, s[0:1], s26, v102
	global_load_dwordx4 v[12:15], v[104:105], off
	global_load_dwordx4 v[16:19], v[106:107], off
	v_addc_co_u32_e64 v109, s[0:1], 0, v103, s[0:1]
	v_add_co_u32_e64 v110, s[0:1], s73, v100
	global_load_dwordx4 v[20:23], v[108:109], off
	s_nop 0
	v_addc_co_u32_e64 v111, s[0:1], 0, v101, s[0:1]
	v_add_co_u32_e64 v112, s[0:1], s96, v102
	global_load_dwordx4 v[24:27], v[110:111], off
	s_nop 0
	v_addc_co_u32_e64 v113, s[0:1], 0, v103, s[0:1]
	s_mov_b32 s0, 0x18000
	s_nop 0
	v_add_co_u32_e64 v114, s[0:1], s0, v100
	global_load_dwordx4 v[28:31], v[112:113], off
	s_nop 0
	v_addc_co_u32_e64 v115, s[0:1], 0, v101, s[0:1]
	global_load_dwordx4 v[32:35], v[114:115], off
	v_mul_lo_u32 v2, v2, s82
	v_add_lshl_u32 v99, v2, v36, 1
	s_waitcnt vmcnt(7)
	ds_write_b128 v99, v[4:7]
	s_waitcnt vmcnt(6)
	ds_write_b128 v99, v[8:11] offset:36864
	s_waitcnt vmcnt(5)
	ds_write_b128 v99, v[12:15] offset:4608
	s_waitcnt vmcnt(4)
	ds_write_b128 v99, v[16:19] offset:41472
	s_waitcnt vmcnt(3)
	ds_write_b128 v99, v[20:23] offset:9216
	s_waitcnt vmcnt(2)
	ds_write_b128 v99, v[24:27] offset:46080
	s_waitcnt vmcnt(1)
	ds_write_b128 v99, v[28:31] offset:13824
	s_waitcnt vmcnt(0)
	ds_write_b128 v99, v[32:35] offset:50688
	s_waitcnt lgkmcnt(0)
	s_barrier
	global_load_dwordx4 v[94:97], v[102:103], off offset:128
	global_load_dwordx4 v[78:81], v[100:101], off offset:128
	global_load_dwordx4 v[82:85], v[104:105], off offset:128
	global_load_dwordx4 v[86:89], v[106:107], off offset:128
	global_load_dwordx4 v[90:93], v[108:109], off offset:128
	global_load_dwordx4 v[66:69], v[110:111], off offset:128
	global_load_dwordx4 v[70:73], v[112:113], off offset:128
	global_load_dwordx4 v[74:77], v[114:115], off offset:128
	v_mad_u32_u24 v0, v3, s72, v0
	ds_read_b128 v[18:21], v98 offset:4608
	ds_read_b128 v[22:25], v0 offset:41472
	ds_read_b128 v[26:29], v98
	ds_read_b128 v[222:225], v98 offset:32
	ds_read_b128 v[30:33], v0 offset:36864
	ds_read_b128 v[226:229], v0 offset:36896
	s_waitcnt lgkmcnt(1)
	v_mfma_f32_32x32x16_bf16 v[2:17], v[26:29], v[30:33], 0
	ds_read_b128 v[230:233], v98 offset:4640
	ds_read_b128 v[234:237], v0 offset:41504
	s_cmp_eq_u32 s45, 2
	s_mov_b64 s[0:1], -1
	v_mfma_f32_32x32x16_bf16 v[50:65], v[26:29], v[22:25], 0
	v_mfma_f32_32x32x16_bf16 v[34:49], v[18:21], v[30:33], 0
	v_mfma_f32_32x32x16_bf16 v[18:33], v[18:21], v[22:25], 0
	s_waitcnt lgkmcnt(2)
	v_mfma_f32_32x32x16_bf16 v[2:17], v[222:225], v[226:229], v[2:17]
	s_waitcnt lgkmcnt(0)
	v_mfma_f32_32x32x16_bf16 v[50:65], v[222:225], v[234:237], v[50:65]
	v_mfma_f32_32x32x16_bf16 v[34:49], v[230:233], v[226:229], v[34:49]
	v_mfma_f32_32x32x16_bf16 v[18:33], v[230:233], v[234:237], v[18:33]
	ds_read_b128 v[222:225], v98 offset:64
	ds_read_b128 v[226:229], v98 offset:4672
	ds_read_b128 v[230:233], v0 offset:36928
	ds_read_b128 v[234:237], v0 offset:41536
	s_waitcnt lgkmcnt(1)
	v_mfma_f32_32x32x16_bf16 v[2:17], v[222:225], v[230:233], v[2:17]
	s_waitcnt lgkmcnt(0)
	v_mfma_f32_32x32x16_bf16 v[50:65], v[222:225], v[234:237], v[50:65]
	v_mfma_f32_32x32x16_bf16 v[34:49], v[226:229], v[230:233], v[34:49]
	v_mfma_f32_32x32x16_bf16 v[18:33], v[226:229], v[234:237], v[18:33]
	ds_read_b128 v[222:225], v98 offset:96
	ds_read_b128 v[226:229], v98 offset:4704
	ds_read_b128 v[230:233], v0 offset:36960
	ds_read_b128 v[234:237], v0 offset:41568
	s_waitcnt vmcnt(7)
	ds_write_b128 v99, v[94:97] offset:18432
	s_waitcnt lgkmcnt(2)
	v_mfma_f32_32x32x16_bf16 v[2:17], v[222:225], v[230:233], v[2:17]
	s_waitcnt lgkmcnt(1)
	v_mfma_f32_32x32x16_bf16 v[50:65], v[222:225], v[234:237], v[50:65]
	v_add_u32_e32 v222, 0xd800, v99
	s_waitcnt vmcnt(6)
	ds_write_b128 v99, v[78:81] offset:55296
	s_waitcnt vmcnt(5)
	ds_write_b128 v99, v[82:85] offset:23040
	s_waitcnt vmcnt(4)
	ds_write_b128 v99, v[86:89] offset:59904
	s_waitcnt vmcnt(3)
	ds_write_b128 v99, v[90:93] offset:27648
	s_waitcnt vmcnt(2)
	ds_write_b128 v99, v[66:69] offset:64512
	s_waitcnt vmcnt(1)
	ds_write_b128 v99, v[70:73] offset:32256
	s_waitcnt vmcnt(0)
	ds_write_b128 v222, v[74:77] offset:13824
	s_waitcnt lgkmcnt(0)
	s_barrier
	global_load_dwordx4 v[94:97], v[102:103], off offset:256
	global_load_dwordx4 v[78:81], v[100:101], off offset:256
	global_load_dwordx4 v[82:85], v[104:105], off offset:256
	global_load_dwordx4 v[86:89], v[106:107], off offset:256
	global_load_dwordx4 v[90:93], v[108:109], off offset:256
	global_load_dwordx4 v[66:69], v[110:111], off offset:256
	global_load_dwordx4 v[70:73], v[112:113], off offset:256
	global_load_dwordx4 v[74:77], v[114:115], off offset:256
	v_mfma_f32_32x32x16_bf16 v[34:49], v[226:229], v[230:233], v[34:49]
	v_mfma_f32_32x32x16_bf16 v[18:33], v[226:229], v[234:237], v[18:33]
	ds_read_b128 v[224:227], v98 offset:23040
	ds_read_b128 v[228:231], v0 offset:59904
	ds_read_b128 v[232:235], v98 offset:18432
	ds_read_b128 v[236:239], v98 offset:18464
	ds_read_b128 v[240:243], v0 offset:55296
	ds_read_b128 v[244:247], v0 offset:55328
	s_waitcnt lgkmcnt(1)
	v_mfma_f32_32x32x16_bf16 v[2:17], v[232:235], v[240:243], v[2:17]
	v_mfma_f32_32x32x16_bf16 v[50:65], v[232:235], v[228:231], v[50:65]
	v_mfma_f32_32x32x16_bf16 v[34:49], v[224:227], v[240:243], v[34:49]
	v_mfma_f32_32x32x16_bf16 v[18:33], v[224:227], v[228:231], v[18:33]
	ds_read_b128 v[224:227], v98 offset:23072
	ds_read_b128 v[228:231], v0 offset:59936
	s_waitcnt lgkmcnt(2)
	v_mfma_f32_32x32x16_bf16 v[2:17], v[236:239], v[244:247], v[2:17]
	s_waitcnt lgkmcnt(0)
	v_mfma_f32_32x32x16_bf16 v[50:65], v[236:239], v[228:231], v[50:65]
	v_mfma_f32_32x32x16_bf16 v[34:49], v[224:227], v[244:247], v[34:49]
	v_mfma_f32_32x32x16_bf16 v[18:33], v[224:227], v[228:231], v[18:33]
	ds_read_b128 v[224:227], v98 offset:18496
	ds_read_b128 v[228:231], v98 offset:23104
	ds_read_b128 v[232:235], v0 offset:55360
	ds_read_b128 v[236:239], v0 offset:59968
	s_waitcnt lgkmcnt(1)
	v_mfma_f32_32x32x16_bf16 v[2:17], v[224:227], v[232:235], v[2:17]
	s_waitcnt lgkmcnt(0)
	v_mfma_f32_32x32x16_bf16 v[50:65], v[224:227], v[236:239], v[50:65]
	v_mfma_f32_32x32x16_bf16 v[34:49], v[228:231], v[232:235], v[34:49]
	v_mfma_f32_32x32x16_bf16 v[18:33], v[228:231], v[236:239], v[18:33]
	ds_read_b128 v[224:227], v98 offset:18528
	ds_read_b128 v[228:231], v98 offset:23136
	ds_read_b128 v[232:235], v0 offset:55392
	ds_read_b128 v[236:239], v0 offset:60000
	s_waitcnt vmcnt(7)
	ds_write_b128 v99, v[94:97]
	s_waitcnt vmcnt(6)
	ds_write_b128 v99, v[78:81] offset:36864
	s_waitcnt vmcnt(5)
	ds_write_b128 v99, v[82:85] offset:4608
	s_waitcnt vmcnt(4)
	ds_write_b128 v99, v[86:89] offset:41472
	s_waitcnt vmcnt(3)
	ds_write_b128 v99, v[90:93] offset:9216
	s_waitcnt vmcnt(2)
	ds_write_b128 v99, v[66:69] offset:46080
	s_waitcnt vmcnt(1)
	ds_write_b128 v99, v[70:73] offset:13824
	s_waitcnt vmcnt(0)
	ds_write_b128 v99, v[74:77] offset:50688
	s_waitcnt lgkmcnt(0)
	s_barrier
	global_load_dwordx4 v[78:81], v[102:103], off offset:384
	global_load_dwordx4 v[82:85], v[100:101], off offset:384
	global_load_dwordx4 v[86:89], v[104:105], off offset:384
	global_load_dwordx4 v[90:93], v[106:107], off offset:384
	global_load_dwordx4 v[94:97], v[108:109], off offset:384
	global_load_dwordx4 v[66:69], v[110:111], off offset:384
	global_load_dwordx4 v[70:73], v[112:113], off offset:384
	global_load_dwordx4 v[74:77], v[114:115], off offset:384
	v_mfma_f32_32x32x16_bf16 v[2:17], v[224:227], v[232:235], v[2:17]
	v_mfma_f32_32x32x16_bf16 v[50:65], v[224:227], v[236:239], v[50:65]
	v_mfma_f32_32x32x16_bf16 v[34:49], v[228:231], v[232:235], v[34:49]
	v_mfma_f32_32x32x16_bf16 v[18:33], v[228:231], v[236:239], v[18:33]
	ds_read_b128 v[224:227], v98 offset:4608
	ds_read_b128 v[228:231], v0 offset:41472
	ds_read_b128 v[232:235], v98
	ds_read_b128 v[236:239], v98 offset:32
	ds_read_b128 v[240:243], v0 offset:36864
	ds_read_b128 v[244:247], v0 offset:36896
	s_waitcnt lgkmcnt(1)
	v_mfma_f32_32x32x16_bf16 v[2:17], v[232:235], v[240:243], v[2:17]
	v_mfma_f32_32x32x16_bf16 v[50:65], v[232:235], v[228:231], v[50:65]
	v_mfma_f32_32x32x16_bf16 v[34:49], v[224:227], v[240:243], v[34:49]
	v_mfma_f32_32x32x16_bf16 v[18:33], v[224:227], v[228:231], v[18:33]
	ds_read_b128 v[224:227], v98 offset:4640
	ds_read_b128 v[228:231], v0 offset:41504
	s_waitcnt lgkmcnt(2)
	v_mfma_f32_32x32x16_bf16 v[2:17], v[236:239], v[244:247], v[2:17]
	s_waitcnt lgkmcnt(0)
	v_mfma_f32_32x32x16_bf16 v[50:65], v[236:239], v[228:231], v[50:65]
	v_mfma_f32_32x32x16_bf16 v[34:49], v[224:227], v[244:247], v[34:49]
	v_mfma_f32_32x32x16_bf16 v[18:33], v[224:227], v[228:231], v[18:33]
	ds_read_b128 v[224:227], v98 offset:64
	ds_read_b128 v[228:231], v98 offset:4672
	ds_read_b128 v[232:235], v0 offset:36928
	ds_read_b128 v[236:239], v0 offset:41536
	s_waitcnt lgkmcnt(1)
	v_mfma_f32_32x32x16_bf16 v[2:17], v[224:227], v[232:235], v[2:17]
	s_waitcnt lgkmcnt(0)
	v_mfma_f32_32x32x16_bf16 v[50:65], v[224:227], v[236:239], v[50:65]
	v_mfma_f32_32x32x16_bf16 v[34:49], v[228:231], v[232:235], v[34:49]
	v_mfma_f32_32x32x16_bf16 v[18:33], v[228:231], v[236:239], v[18:33]
	ds_read_b128 v[224:227], v98 offset:96
	ds_read_b128 v[228:231], v98 offset:4704
	ds_read_b128 v[232:235], v0 offset:36960
	ds_read_b128 v[236:239], v0 offset:41568
	s_waitcnt vmcnt(7)
	ds_write_b128 v99, v[78:81] offset:18432
	s_waitcnt vmcnt(6)
	ds_write_b128 v99, v[82:85] offset:55296
	s_waitcnt vmcnt(5)
	ds_write_b128 v99, v[86:89] offset:23040
	s_waitcnt vmcnt(4)
	ds_write_b128 v99, v[90:93] offset:59904
	s_waitcnt vmcnt(3)
	ds_write_b128 v99, v[94:97] offset:27648
	s_waitcnt vmcnt(2)
	ds_write_b128 v99, v[66:69] offset:64512
	s_waitcnt vmcnt(1)
	ds_write_b128 v99, v[70:73] offset:32256
	s_waitcnt vmcnt(0)
	ds_write_b128 v222, v[74:77] offset:13824
	s_waitcnt lgkmcnt(0)
	s_barrier
	global_load_dwordx4 v[78:81], v[102:103], off offset:512
	global_load_dwordx4 v[82:85], v[100:101], off offset:512
	global_load_dwordx4 v[86:89], v[104:105], off offset:512
	global_load_dwordx4 v[90:93], v[106:107], off offset:512
	global_load_dwordx4 v[94:97], v[108:109], off offset:512
	global_load_dwordx4 v[66:69], v[110:111], off offset:512
	global_load_dwordx4 v[70:73], v[112:113], off offset:512
	global_load_dwordx4 v[74:77], v[114:115], off offset:512
	v_mfma_f32_32x32x16_bf16 v[2:17], v[224:227], v[232:235], v[2:17]
	v_mfma_f32_32x32x16_bf16 v[50:65], v[224:227], v[236:239], v[50:65]
	v_mfma_f32_32x32x16_bf16 v[34:49], v[228:231], v[232:235], v[34:49]
	v_mfma_f32_32x32x16_bf16 v[18:33], v[228:231], v[236:239], v[18:33]
	ds_read_b128 v[224:227], v98 offset:23040
	ds_read_b128 v[228:231], v0 offset:59904
	ds_read_b128 v[232:235], v98 offset:18432
	ds_read_b128 v[236:239], v98 offset:18464
	ds_read_b128 v[240:243], v0 offset:55296
	ds_read_b128 v[244:247], v0 offset:55328
	s_waitcnt lgkmcnt(1)
	v_mfma_f32_32x32x16_bf16 v[2:17], v[232:235], v[240:243], v[2:17]
	v_mfma_f32_32x32x16_bf16 v[50:65], v[232:235], v[228:231], v[50:65]
	v_mfma_f32_32x32x16_bf16 v[34:49], v[224:227], v[240:243], v[34:49]
	v_mfma_f32_32x32x16_bf16 v[18:33], v[224:227], v[228:231], v[18:33]
	ds_read_b128 v[224:227], v98 offset:23072
	ds_read_b128 v[228:231], v0 offset:59936
	s_waitcnt lgkmcnt(2)
	v_mfma_f32_32x32x16_bf16 v[2:17], v[236:239], v[244:247], v[2:17]
	s_waitcnt lgkmcnt(0)
	v_mfma_f32_32x32x16_bf16 v[50:65], v[236:239], v[228:231], v[50:65]
	v_mfma_f32_32x32x16_bf16 v[34:49], v[224:227], v[244:247], v[34:49]
	v_mfma_f32_32x32x16_bf16 v[18:33], v[224:227], v[228:231], v[18:33]
	ds_read_b128 v[224:227], v98 offset:18496
	ds_read_b128 v[228:231], v98 offset:23104
	ds_read_b128 v[232:235], v0 offset:55360
	ds_read_b128 v[236:239], v0 offset:59968
	s_waitcnt lgkmcnt(1)
	v_mfma_f32_32x32x16_bf16 v[2:17], v[224:227], v[232:235], v[2:17]
	s_waitcnt lgkmcnt(0)
	v_mfma_f32_32x32x16_bf16 v[50:65], v[224:227], v[236:239], v[50:65]
	v_mfma_f32_32x32x16_bf16 v[34:49], v[228:231], v[232:235], v[34:49]
	v_mfma_f32_32x32x16_bf16 v[18:33], v[228:231], v[236:239], v[18:33]
	ds_read_b128 v[224:227], v98 offset:18528
	ds_read_b128 v[228:231], v98 offset:23136
	ds_read_b128 v[232:235], v0 offset:55392
	ds_read_b128 v[236:239], v0 offset:60000
	s_waitcnt vmcnt(7)
	ds_write_b128 v99, v[78:81]
	s_waitcnt vmcnt(6)
	ds_write_b128 v99, v[82:85] offset:36864
	s_waitcnt vmcnt(5)
	ds_write_b128 v99, v[86:89] offset:4608
	s_waitcnt vmcnt(4)
	ds_write_b128 v99, v[90:93] offset:41472
	s_waitcnt vmcnt(3)
	ds_write_b128 v99, v[94:97] offset:9216
	s_waitcnt vmcnt(2)
	ds_write_b128 v99, v[66:69] offset:46080
	s_waitcnt vmcnt(1)
	ds_write_b128 v99, v[70:73] offset:13824
	s_waitcnt vmcnt(0)
	ds_write_b128 v99, v[74:77] offset:50688
	s_waitcnt lgkmcnt(0)
	s_barrier
	global_load_dwordx4 v[78:81], v[102:103], off offset:640
	global_load_dwordx4 v[82:85], v[100:101], off offset:640
	global_load_dwordx4 v[86:89], v[104:105], off offset:640
	global_load_dwordx4 v[90:93], v[106:107], off offset:640
	global_load_dwordx4 v[94:97], v[108:109], off offset:640
	global_load_dwordx4 v[66:69], v[110:111], off offset:640
	global_load_dwordx4 v[70:73], v[112:113], off offset:640
	global_load_dwordx4 v[74:77], v[114:115], off offset:640
	v_mfma_f32_32x32x16_bf16 v[2:17], v[224:227], v[232:235], v[2:17]
	v_mfma_f32_32x32x16_bf16 v[50:65], v[224:227], v[236:239], v[50:65]
	v_mfma_f32_32x32x16_bf16 v[34:49], v[228:231], v[232:235], v[34:49]
	v_mfma_f32_32x32x16_bf16 v[18:33], v[228:231], v[236:239], v[18:33]
	ds_read_b128 v[224:227], v98 offset:4608
	ds_read_b128 v[228:231], v0 offset:41472
	ds_read_b128 v[232:235], v98
	ds_read_b128 v[236:239], v98 offset:32
	ds_read_b128 v[240:243], v0 offset:36864
	ds_read_b128 v[244:247], v0 offset:36896
	s_waitcnt lgkmcnt(1)
	v_mfma_f32_32x32x16_bf16 v[2:17], v[232:235], v[240:243], v[2:17]
	v_mfma_f32_32x32x16_bf16 v[50:65], v[232:235], v[228:231], v[50:65]
	v_mfma_f32_32x32x16_bf16 v[34:49], v[224:227], v[240:243], v[34:49]
	v_mfma_f32_32x32x16_bf16 v[18:33], v[224:227], v[228:231], v[18:33]
	ds_read_b128 v[224:227], v98 offset:4640
	ds_read_b128 v[228:231], v0 offset:41504
	s_waitcnt lgkmcnt(2)
	v_mfma_f32_32x32x16_bf16 v[2:17], v[236:239], v[244:247], v[2:17]
	s_waitcnt lgkmcnt(0)
	v_mfma_f32_32x32x16_bf16 v[50:65], v[236:239], v[228:231], v[50:65]
	v_mfma_f32_32x32x16_bf16 v[34:49], v[224:227], v[244:247], v[34:49]
	v_mfma_f32_32x32x16_bf16 v[18:33], v[224:227], v[228:231], v[18:33]
	ds_read_b128 v[224:227], v98 offset:64
	ds_read_b128 v[228:231], v98 offset:4672
	ds_read_b128 v[232:235], v0 offset:36928
	ds_read_b128 v[236:239], v0 offset:41536
	s_waitcnt lgkmcnt(1)
	v_mfma_f32_32x32x16_bf16 v[2:17], v[224:227], v[232:235], v[2:17]
	s_waitcnt lgkmcnt(0)
	v_mfma_f32_32x32x16_bf16 v[50:65], v[224:227], v[236:239], v[50:65]
	v_mfma_f32_32x32x16_bf16 v[34:49], v[228:231], v[232:235], v[34:49]
	v_mfma_f32_32x32x16_bf16 v[18:33], v[228:231], v[236:239], v[18:33]
	ds_read_b128 v[224:227], v98 offset:96
	ds_read_b128 v[228:231], v98 offset:4704
	ds_read_b128 v[232:235], v0 offset:36960
	ds_read_b128 v[236:239], v0 offset:41568
	s_waitcnt vmcnt(7)
	ds_write_b128 v99, v[78:81] offset:18432
	s_waitcnt vmcnt(6)
	ds_write_b128 v99, v[82:85] offset:55296
	s_waitcnt vmcnt(5)
	ds_write_b128 v99, v[86:89] offset:23040
	s_waitcnt vmcnt(4)
	ds_write_b128 v99, v[90:93] offset:59904
	s_waitcnt vmcnt(3)
	ds_write_b128 v99, v[94:97] offset:27648
	s_waitcnt vmcnt(2)
	ds_write_b128 v99, v[66:69] offset:64512
	s_waitcnt vmcnt(1)
	ds_write_b128 v99, v[70:73] offset:32256
	s_waitcnt vmcnt(0)
	ds_write_b128 v222, v[74:77] offset:13824
	s_waitcnt lgkmcnt(0)
	s_barrier
	global_load_dwordx4 v[94:97], v[102:103], off offset:768
	global_load_dwordx4 v[90:93], v[100:101], off offset:768
	global_load_dwordx4 v[70:73], v[104:105], off offset:768
	global_load_dwordx4 v[74:77], v[106:107], off offset:768
	global_load_dwordx4 v[78:81], v[108:109], off offset:768
	global_load_dwordx4 v[82:85], v[110:111], off offset:768
	global_load_dwordx4 v[86:89], v[112:113], off offset:768
	global_load_dwordx4 v[66:69], v[114:115], off offset:768
	v_mfma_f32_32x32x16_bf16 v[2:17], v[224:227], v[232:235], v[2:17]
	v_mfma_f32_32x32x16_bf16 v[50:65], v[224:227], v[236:239], v[50:65]
	v_mfma_f32_32x32x16_bf16 v[34:49], v[228:231], v[232:235], v[34:49]
	v_mfma_f32_32x32x16_bf16 v[18:33], v[228:231], v[236:239], v[18:33]
	ds_read_b128 v[224:227], v98 offset:23040
	ds_read_b128 v[228:231], v0 offset:59904
	ds_read_b128 v[232:235], v98 offset:18432
	ds_read_b128 v[236:239], v98 offset:18464
	ds_read_b128 v[240:243], v0 offset:55296
	ds_read_b128 v[244:247], v0 offset:55328
	s_waitcnt lgkmcnt(1)
	v_mfma_f32_32x32x16_bf16 v[2:17], v[232:235], v[240:243], v[2:17]
	v_mfma_f32_32x32x16_bf16 v[50:65], v[232:235], v[228:231], v[50:65]
	v_mfma_f32_32x32x16_bf16 v[34:49], v[224:227], v[240:243], v[34:49]
	v_mfma_f32_32x32x16_bf16 v[18:33], v[224:227], v[228:231], v[18:33]
	ds_read_b128 v[224:227], v98 offset:23072
	ds_read_b128 v[228:231], v0 offset:59936
	s_waitcnt lgkmcnt(2)
	v_mfma_f32_32x32x16_bf16 v[2:17], v[236:239], v[244:247], v[2:17]
	s_waitcnt lgkmcnt(0)
	v_mfma_f32_32x32x16_bf16 v[50:65], v[236:239], v[228:231], v[50:65]
	v_mfma_f32_32x32x16_bf16 v[34:49], v[224:227], v[244:247], v[34:49]
	v_mfma_f32_32x32x16_bf16 v[18:33], v[224:227], v[228:231], v[18:33]
	ds_read_b128 v[224:227], v98 offset:18496
	ds_read_b128 v[228:231], v98 offset:23104
	ds_read_b128 v[232:235], v0 offset:55360
	ds_read_b128 v[236:239], v0 offset:59968
	s_waitcnt lgkmcnt(1)
	v_mfma_f32_32x32x16_bf16 v[2:17], v[224:227], v[232:235], v[2:17]
	s_waitcnt lgkmcnt(0)
	v_mfma_f32_32x32x16_bf16 v[50:65], v[224:227], v[236:239], v[50:65]
	v_mfma_f32_32x32x16_bf16 v[34:49], v[228:231], v[232:235], v[34:49]
	v_mfma_f32_32x32x16_bf16 v[18:33], v[228:231], v[236:239], v[18:33]
	ds_read_b128 v[224:227], v98 offset:18528
	ds_read_b128 v[228:231], v98 offset:23136
	ds_read_b128 v[232:235], v0 offset:55392
	ds_read_b128 v[236:239], v0 offset:60000
	s_waitcnt vmcnt(7)
	ds_write_b128 v99, v[94:97]
	s_waitcnt vmcnt(6)
	ds_write_b128 v99, v[90:93] offset:36864
	s_waitcnt vmcnt(5)
	ds_write_b128 v99, v[70:73] offset:4608
	s_waitcnt vmcnt(4)
	ds_write_b128 v99, v[74:77] offset:41472
	s_waitcnt vmcnt(3)
	ds_write_b128 v99, v[78:81] offset:9216
	s_waitcnt vmcnt(2)
	ds_write_b128 v99, v[82:85] offset:46080
	s_waitcnt vmcnt(1)
	ds_write_b128 v99, v[86:89] offset:13824
	s_waitcnt vmcnt(0)
	ds_write_b128 v99, v[66:69] offset:50688
	s_waitcnt lgkmcnt(0)
	s_barrier
	global_load_dwordx4 v[94:97], v[102:103], off offset:896
	global_load_dwordx4 v[90:93], v[100:101], off offset:896
	global_load_dwordx4 v[78:81], v[104:105], off offset:896
	global_load_dwordx4 v[82:85], v[106:107], off offset:896
	global_load_dwordx4 v[86:89], v[108:109], off offset:896
	global_load_dwordx4 v[66:69], v[110:111], off offset:896
	global_load_dwordx4 v[70:73], v[112:113], off offset:896
	global_load_dwordx4 v[74:77], v[114:115], off offset:896
	v_mfma_f32_32x32x16_bf16 v[2:17], v[224:227], v[232:235], v[2:17]
	v_mfma_f32_32x32x16_bf16 v[50:65], v[224:227], v[236:239], v[50:65]
	v_mfma_f32_32x32x16_bf16 v[34:49], v[228:231], v[232:235], v[34:49]
	v_mfma_f32_32x32x16_bf16 v[18:33], v[228:231], v[236:239], v[18:33]
	ds_read_b128 v[100:103], v98 offset:4608
	ds_read_b128 v[104:107], v0 offset:41472
	ds_read_b128 v[108:111], v98
	ds_read_b128 v[112:115], v98 offset:32
	ds_read_b128 v[224:227], v0 offset:36864
	ds_read_b128 v[228:231], v0 offset:36896
	s_waitcnt lgkmcnt(1)
	v_mfma_f32_32x32x16_bf16 v[2:17], v[108:111], v[224:227], v[2:17]
	v_mfma_f32_32x32x16_bf16 v[50:65], v[108:111], v[104:107], v[50:65]
	v_mfma_f32_32x32x16_bf16 v[34:49], v[100:103], v[224:227], v[34:49]
	v_mfma_f32_32x32x16_bf16 v[18:33], v[100:103], v[104:107], v[18:33]
	ds_read_b128 v[100:103], v98 offset:4640
	ds_read_b128 v[104:107], v0 offset:41504
	s_waitcnt lgkmcnt(2)
	v_mfma_f32_32x32x16_bf16 v[2:17], v[112:115], v[228:231], v[2:17]
	s_waitcnt lgkmcnt(0)
	v_mfma_f32_32x32x16_bf16 v[50:65], v[112:115], v[104:107], v[50:65]
	v_mfma_f32_32x32x16_bf16 v[34:49], v[100:103], v[228:231], v[34:49]
	v_mfma_f32_32x32x16_bf16 v[18:33], v[100:103], v[104:107], v[18:33]
	ds_read_b128 v[100:103], v98 offset:64
	ds_read_b128 v[104:107], v98 offset:4672
	ds_read_b128 v[108:111], v0 offset:36928
	ds_read_b128 v[112:115], v0 offset:41536
	s_waitcnt lgkmcnt(1)
	v_mfma_f32_32x32x16_bf16 v[2:17], v[100:103], v[108:111], v[2:17]
	s_waitcnt lgkmcnt(0)
	v_mfma_f32_32x32x16_bf16 v[50:65], v[100:103], v[112:115], v[50:65]
	v_mfma_f32_32x32x16_bf16 v[34:49], v[104:107], v[108:111], v[34:49]
	v_mfma_f32_32x32x16_bf16 v[18:33], v[104:107], v[112:115], v[18:33]
	ds_read_b128 v[100:103], v98 offset:96
	ds_read_b128 v[104:107], v98 offset:4704
	ds_read_b128 v[108:111], v0 offset:36960
	ds_read_b128 v[112:115], v0 offset:41568
	s_waitcnt vmcnt(7)
	ds_write_b128 v99, v[94:97] offset:18432
	s_waitcnt vmcnt(6)
	ds_write_b128 v99, v[90:93] offset:55296
	s_waitcnt vmcnt(5)
	ds_write_b128 v99, v[78:81] offset:23040
	s_waitcnt vmcnt(4)
	ds_write_b128 v99, v[82:85] offset:59904
	s_waitcnt vmcnt(3)
	ds_write_b128 v99, v[86:89] offset:27648
	s_waitcnt vmcnt(2)
	ds_write_b128 v99, v[66:69] offset:64512
	s_waitcnt vmcnt(1)
	ds_write_b128 v99, v[70:73] offset:32256
	s_waitcnt vmcnt(0)
	ds_write_b128 v222, v[74:77] offset:13824
	s_waitcnt lgkmcnt(0)
	s_barrier
	ds_read_b128 v[66:69], v98 offset:23040
	ds_read_b128 v[70:73], v0 offset:59904
	ds_read_b128 v[74:77], v98 offset:18432
	ds_read_b128 v[78:81], v98 offset:18464
	ds_read_b128 v[82:85], v0 offset:55296
	ds_read_b128 v[86:89], v0 offset:55328
	v_and_b32_e32 v92, 0xffff0000, v169
	v_mfma_f32_32x32x16_bf16 v[2:17], v[100:103], v[108:111], v[2:17]
	v_lshlrev_b32_e32 v96, 16, v206
	v_and_b32_e32 v99, 0xffff0000, v206
	v_mfma_f32_32x32x16_bf16 v[50:65], v[100:103], v[112:115], v[50:65]
	v_lshlrev_b32_e32 v100, 16, v207
	v_mfma_f32_32x32x16_bf16 v[34:49], v[104:107], v[108:111], v[34:49]
	v_and_b32_e32 v108, 0xffff0000, v209
	v_lshlrev_b32_e32 v110, 16, v210
	v_and_b32_e32 v111, 0xffff0000, v210
	v_mfma_f32_32x32x16_bf16 v[18:33], v[104:107], v[112:115], v[18:33]
	v_and_b32_e32 v104, 0xffff0000, v207
	v_lshlrev_b32_e32 v105, 16, v208
	v_and_b32_e32 v106, 0xffff0000, v208
	v_lshlrev_b32_e32 v107, 16, v209
	v_lshlrev_b32_e32 v112, 16, v211
	v_and_b32_e32 v114, 0xffff0000, v211
	s_waitcnt lgkmcnt(1)
	v_mfma_f32_32x32x16_bf16 v[2:17], v[74:77], v[82:85], v[2:17]
	v_mfma_f32_32x32x16_bf16 v[50:65], v[74:77], v[70:73], v[50:65]
	v_mfma_f32_32x32x16_bf16 v[34:49], v[66:69], v[82:85], v[34:49]
	v_and_b32_e32 v82, 0xffff0000, v171
	v_lshlrev_b32_e32 v83, 16, v170
	v_mfma_f32_32x32x16_bf16 v[18:33], v[66:69], v[70:73], v[18:33]
	ds_read_b128 v[66:69], v98 offset:23072
	ds_read_b128 v[70:73], v0 offset:59936
	s_waitcnt lgkmcnt(2)
	v_mfma_f32_32x32x16_bf16 v[2:17], v[78:81], v[86:89], v[2:17]
	s_waitcnt lgkmcnt(0)
	v_mfma_f32_32x32x16_bf16 v[50:65], v[78:81], v[70:73], v[50:65]
	v_mfma_f32_32x32x16_bf16 v[34:49], v[66:69], v[86:89], v[34:49]
	v_and_b32_e32 v86, 0xffff0000, v170
	v_lshlrev_b32_e32 v89, 16, v169
	v_mfma_f32_32x32x16_bf16 v[18:33], v[66:69], v[70:73], v[18:33]
	ds_read_b128 v[66:69], v98 offset:18496
	ds_read_b128 v[70:73], v98 offset:23104
	ds_read_b128 v[74:77], v0 offset:55360
	ds_read_b128 v[78:81], v0 offset:59968
	s_waitcnt lgkmcnt(1)
	v_mfma_f32_32x32x16_bf16 v[2:17], v[66:69], v[74:77], v[2:17]
	s_waitcnt lgkmcnt(0)
	v_mfma_f32_32x32x16_bf16 v[50:65], v[66:69], v[78:81], v[50:65]
	v_mfma_f32_32x32x16_bf16 v[34:49], v[70:73], v[74:77], v[34:49]
	v_mfma_f32_32x32x16_bf16 v[18:33], v[70:73], v[78:81], v[18:33]
	ds_read_b128 v[66:69], v98 offset:18528
	ds_read_b128 v[70:73], v98 offset:23136
	ds_read_b128 v[74:77], v0 offset:55392
	ds_read_b128 v[78:81], v0 offset:60000
	v_cvt_f32_ubyte0_e32 v0, v116
	v_mul_f32_e32 v0, 0x3b808081, v0
	v_lshlrev_b32_e32 v116, 16, v212
	s_waitcnt lgkmcnt(0)
	s_barrier
	v_mfma_f32_32x32x16_bf16 v[2:17], v[66:69], v[74:77], v[2:17]
	v_mfma_f32_32x32x16_bf16 v[50:65], v[66:69], v[78:81], v[50:65]
	v_cvt_f32_ubyte2_e32 v67, v117
	v_mul_f32_e32 v67, 0x3b808081, v67
	s_nop 8
	v_mul_f32_e32 v4, v67, v4
	v_cvt_f32_ubyte3_e32 v67, v117
	v_mul_f32_e32 v67, 0x3b808081, v67
	v_mul_f32_e32 v5, v67, v5
	v_cvt_f32_ubyte0_e32 v67, v119
	v_mul_f32_e32 v67, 0x3b808081, v67
	v_mul_f32_e32 v6, v67, v6
	v_cvt_f32_ubyte1_e32 v67, v121
	v_mul_f32_e32 v67, 0x3b808081, v67
	v_mul_f32_e32 v7, v67, v7
	v_cvt_f32_ubyte2_e32 v67, v120
	v_mul_f32_e32 v67, 0x3b808081, v67
	v_mul_f32_e32 v8, v67, v8
	v_cvt_f32_ubyte3_e32 v67, v120
	v_mul_f32_e32 v67, 0x3b808081, v67
	v_mul_f32_e32 v9, v67, v9
	v_cvt_f32_ubyte0_e32 v67, v122
	v_mul_f32_e32 v67, 0x3b808081, v67
	v_mul_f32_e32 v10, v67, v10
	v_cvt_f32_ubyte1_e32 v67, v124
	v_mul_f32_e32 v67, 0x3b808081, v67
	v_mul_f32_e32 v11, v67, v11
	v_cvt_f32_ubyte2_e32 v67, v123
	v_mul_f32_e32 v67, 0x3b808081, v67
	v_mul_f32_e32 v12, v67, v12
	v_cvt_f32_ubyte3_e32 v67, v123
	v_mul_f32_e32 v67, 0x3b808081, v67
	v_mul_f32_e32 v13, v67, v13
	v_cvt_f32_ubyte0_e32 v67, v125
	v_mul_f32_e32 v67, 0x3b808081, v67
	v_mul_f32_e32 v14, v67, v14
	v_cvt_f32_ubyte1_e32 v67, v127
	v_mul_f32_e32 v67, 0x3b808081, v67
	v_mul_f32_e32 v15, v67, v15
	v_cvt_f32_ubyte2_e32 v67, v126
	v_mul_f32_e32 v67, 0x3b808081, v67
	v_mul_f32_e32 v67, v67, v16
	v_cvt_f32_ubyte3_e32 v16, v126
	v_mul_f32_e32 v16, 0x3b808081, v16
	v_mul_f32_e32 v68, v16, v17
	v_cvt_f32_ubyte0_e32 v16, v128
	v_mul_f32_e32 v16, 0x3b808081, v16
	v_mul_f32_e32 v50, v16, v50
	v_cvt_f32_ubyte1_e32 v16, v130
	v_mul_f32_e32 v16, 0x3b808081, v16
	v_mul_f32_e32 v51, v16, v51
	v_cvt_f32_ubyte2_e32 v16, v129
	v_mul_f32_e32 v16, 0x3b808081, v16
	v_mul_f32_e32 v52, v16, v52
	v_cvt_f32_ubyte3_e32 v16, v129
	v_mul_f32_e32 v16, 0x3b808081, v16
	v_mul_f32_e32 v53, v16, v53
	v_cvt_f32_ubyte0_e32 v16, v131
	v_mul_f32_e32 v16, 0x3b808081, v16
	v_mul_f32_e32 v54, v16, v54
	v_cvt_f32_ubyte1_e32 v16, v133
	v_mul_f32_e32 v16, 0x3b808081, v16
	v_mul_f32_e32 v55, v16, v55
	v_cvt_f32_ubyte2_e32 v16, v132
	v_mul_f32_e32 v16, 0x3b808081, v16
	v_mul_f32_e32 v56, v16, v56
	v_cvt_f32_ubyte3_e32 v16, v132
	v_mul_f32_e32 v16, 0x3b808081, v16
	v_mul_f32_e32 v57, v16, v57
	v_cvt_f32_ubyte0_e32 v16, v134
	v_mul_f32_e32 v16, 0x3b808081, v16
	v_mul_f32_e32 v58, v16, v58
	v_cvt_f32_ubyte1_e32 v16, v136
	v_mul_f32_e32 v16, 0x3b808081, v16
	v_mul_f32_e32 v59, v16, v59
	v_cvt_f32_ubyte2_e32 v16, v135
	v_mul_f32_e32 v16, 0x3b808081, v16
	v_mul_f32_e32 v60, v16, v60
	v_cvt_f32_ubyte3_e32 v16, v135
	v_mul_f32_e32 v16, 0x3b808081, v16
	v_mul_f32_e32 v61, v16, v61
	v_cvt_f32_ubyte0_e32 v16, v137
	v_mul_f32_e32 v16, 0x3b808081, v16
	v_mfma_f32_32x32x16_bf16 v[34:49], v[70:73], v[74:77], v[34:49]
	v_mul_f32_e32 v62, v16, v62
	v_cvt_f32_ubyte1_e32 v16, v139
	v_mul_f32_e32 v16, 0x3b808081, v16
	v_mul_f32_e32 v63, v16, v63
	v_cvt_f32_ubyte2_e32 v16, v138
	v_mul_f32_e32 v16, 0x3b808081, v16
	v_mul_f32_e32 v64, v16, v64
	v_cvt_f32_ubyte3_e32 v16, v138
	v_mul_f32_e32 v16, 0x3b808081, v16
	v_mul_f32_e32 v65, v16, v65
	v_cvt_f32_ubyte0_e32 v16, v140
	v_mul_f32_e32 v16, 0x3b808081, v16
	v_mul_f32_e32 v34, v16, v34
	v_cvt_f32_ubyte1_e32 v16, v142
	v_mul_f32_e32 v16, 0x3b808081, v16
	v_mul_f32_e32 v35, v16, v35
	v_cvt_f32_ubyte2_e32 v16, v141
	v_mul_f32_e32 v16, 0x3b808081, v16
	v_mul_f32_e32 v36, v16, v36
	v_cvt_f32_ubyte3_e32 v16, v141
	v_mul_f32_e32 v16, 0x3b808081, v16
	v_mul_f32_e32 v37, v16, v37
	v_cvt_f32_ubyte0_e32 v16, v143
	v_mul_f32_e32 v16, 0x3b808081, v16
	v_mul_f32_e32 v38, v16, v38
	v_cvt_f32_ubyte1_e32 v16, v145
	v_mul_f32_e32 v16, 0x3b808081, v16
	v_mul_f32_e32 v39, v16, v39
	v_cvt_f32_ubyte2_e32 v16, v144
	v_mul_f32_e32 v16, 0x3b808081, v16
	v_mul_f32_e32 v40, v16, v40
	v_cvt_f32_ubyte3_e32 v16, v144
	v_mul_f32_e32 v16, 0x3b808081, v16
	v_mul_f32_e32 v69, v16, v41
	v_cvt_f32_ubyte0_e32 v16, v146
	v_mul_f32_e32 v16, 0x3b808081, v16
	v_mfma_f32_32x32x16_bf16 v[18:33], v[70:73], v[78:81], v[18:33]
	v_mul_f32_e32 v70, v16, v42
	v_cvt_f32_ubyte1_e32 v16, v148
	v_mul_f32_e32 v16, 0x3b808081, v16
	v_mul_f32_e32 v76, v16, v43
	v_cvt_f32_ubyte2_e32 v16, v147
	v_mul_f32_e32 v16, 0x3b808081, v16
	v_mul_f32_e32 v78, v16, v44
	v_cvt_f32_ubyte3_e32 v16, v147
	v_mul_f32_e32 v16, 0x3b808081, v16
	v_mul_f32_e32 v81, v16, v45
	v_cvt_f32_ubyte0_e32 v16, v149
	v_mul_f32_e32 v16, 0x3b808081, v16
	v_mul_f32_e32 v93, v16, v46
	v_cvt_f32_ubyte1_e32 v16, v151
	v_mul_f32_e32 v16, 0x3b808081, v16
	v_mul_f32_e32 v101, v16, v47
	v_cvt_f32_ubyte2_e32 v16, v150
	v_mul_f32_e32 v16, 0x3b808081, v16
	v_mul_f32_e32 v109, v16, v48
	v_cvt_f32_ubyte3_e32 v16, v150
	v_mul_f32_e32 v16, 0x3b808081, v16
	v_mul_f32_e32 v113, v16, v49
	v_cvt_f32_ubyte0_e32 v16, v152
	v_mul_f32_e32 v16, 0x3b808081, v16
	v_mul_f32_e32 v115, v16, v18
	v_cvt_f32_ubyte1_e32 v16, v154
	v_mul_f32_e32 v16, 0x3b808081, v16
	v_mul_f32_e32 v117, v16, v19
	v_cvt_f32_ubyte2_e32 v16, v153
	v_mul_f32_e32 v16, 0x3b808081, v16
	v_cvt_f32_ubyte1_e32 v66, v118
	v_mul_f32_e32 v118, v16, v20
	v_cvt_f32_ubyte3_e32 v16, v153
	v_mul_f32_e32 v16, 0x3b808081, v16
	v_mul_f32_e32 v119, v16, v21
	v_cvt_f32_ubyte0_e32 v16, v155
	v_mul_f32_e32 v16, 0x3b808081, v16
	v_mul_f32_e32 v120, v16, v22
	v_cvt_f32_ubyte1_e32 v16, v157
	v_mul_f32_e32 v16, 0x3b808081, v16
	v_mul_f32_e32 v122, v16, v23
	v_cvt_f32_ubyte2_e32 v16, v156
	v_mul_f32_e32 v16, 0x3b808081, v16
	v_mul_f32_e32 v123, v16, v24
	v_cvt_f32_ubyte3_e32 v16, v156
	v_mul_f32_e32 v16, 0x3b808081, v16
	v_mul_f32_e32 v124, v16, v25
	v_cvt_f32_ubyte0_e32 v16, v158
	v_mul_f32_e32 v16, 0x3b808081, v16
	v_mul_f32_e32 v125, v16, v26
	v_cvt_f32_ubyte1_e32 v16, v160
	v_mul_f32_e32 v16, 0x3b808081, v16
	v_mul_f32_e32 v127, v16, v27
	v_cvt_f32_ubyte2_e32 v16, v159
	v_mul_f32_e32 v16, 0x3b808081, v16
	v_mul_f32_e32 v128, v16, v28
	v_cvt_f32_ubyte3_e32 v16, v159
	v_mul_f32_e32 v16, 0x3b808081, v16
	v_mul_f32_e32 v129, v16, v29
	v_cvt_f32_ubyte0_e32 v16, v161
	v_mul_f32_e32 v16, 0x3b808081, v16
	v_mul_f32_e32 v130, v16, v30
	v_cvt_f32_ubyte1_e32 v16, v163
	v_mul_f32_e32 v16, 0x3b808081, v16
	v_mul_f32_e32 v132, v16, v31
	v_cvt_f32_ubyte2_e32 v16, v162
	v_mul_f32_e32 v16, 0x3b808081, v16
	v_mul_f32_e32 v133, v16, v32
	v_cvt_f32_ubyte3_e32 v16, v162
	v_mul_f32_e32 v16, 0x3b808081, v16
	v_mul_f32_e32 v66, 0x3b808081, v66
	v_mul_f32_e32 v134, v16, v33
	v_lshlrev_b32_e32 v16, 16, v205
	v_and_b32_e32 v17, 0xffff0000, v205
	v_lshlrev_b32_e32 v18, 16, v204
	v_and_b32_e32 v19, 0xffff0000, v204
	v_lshlrev_b32_e32 v20, 16, v203
	v_and_b32_e32 v21, 0xffff0000, v203
	v_lshlrev_b32_e32 v22, 16, v202
	v_and_b32_e32 v23, 0xffff0000, v202
	v_lshlrev_b32_e32 v24, 16, v201
	v_and_b32_e32 v25, 0xffff0000, v201
	v_lshlrev_b32_e32 v28, 16, v200
	v_and_b32_e32 v31, 0xffff0000, v200
	v_lshlrev_b32_e32 v41, 16, v199
	v_and_b32_e32 v44, 0xffff0000, v199
	v_lshlrev_b32_e32 v45, 16, v177
	v_and_b32_e32 v46, 0xffff0000, v177
	v_lshlrev_b32_e32 v47, 16, v176
	v_and_b32_e32 v48, 0xffff0000, v176
	v_lshlrev_b32_e32 v49, 16, v175
	v_and_b32_e32 v71, 0xffff0000, v175
	v_lshlrev_b32_e32 v72, 16, v174
	v_and_b32_e32 v73, 0xffff0000, v174
	v_lshlrev_b32_e32 v74, 16, v173
	v_and_b32_e32 v75, 0xffff0000, v173
	v_lshlrev_b32_e32 v77, 16, v172
	v_and_b32_e32 v79, 0xffff0000, v172
	v_lshlrev_b32_e32 v80, 16, v171
	v_and_b32_e32 v121, 0xffff0000, v212
	v_lshlrev_b32_e32 v126, 16, v213
	v_and_b32_e32 v131, 0xffff0000, v213
	v_lshlrev_b32_e32 v135, 16, v214
	v_and_b32_e32 v136, 0xffff0000, v214
	v_lshlrev_b32_e32 v137, 16, v215
	v_and_b32_e32 v138, 0xffff0000, v215
	v_lshlrev_b32_e32 v139, 16, v216
	v_and_b32_e32 v140, 0xffff0000, v216
	v_lshlrev_b32_e32 v141, 16, v217
	v_and_b32_e32 v142, 0xffff0000, v217
	v_lshlrev_b32_e32 v143, 16, v218
	v_and_b32_e32 v144, 0xffff0000, v218
	v_lshlrev_b32_e32 v145, 16, v219
	v_and_b32_e32 v146, 0xffff0000, v219
	v_lshlrev_b32_e32 v147, 16, v220
	v_and_b32_e32 v148, 0xffff0000, v220
	v_lshlrev_b32_e32 v149, 16, v221
	v_and_b32_e32 v150, 0xffff0000, v221
	v_fmac_f32_e32 v16, v0, v2
	v_fmac_f32_e32 v17, v66, v3
	v_add_f32_e32 v42, v4, v18
	v_add_f32_e32 v43, v5, v19
	v_add_f32_e32 v32, v6, v20
	v_add_f32_e32 v33, v7, v21
	v_add_f32_e32 v29, v8, v22
	v_add_f32_e32 v30, v9, v23
	v_add_f32_e32 v26, v10, v24
	v_add_f32_e32 v27, v11, v25
	v_add_f32_e32 v23, v12, v28
	v_add_f32_e32 v24, v13, v31
	v_add_f32_e32 v21, v14, v41
	v_add_f32_e32 v20, v15, v44
	v_add_f32_e32 v19, v67, v45
	v_add_f32_e32 v18, v68, v46
	v_add_f32_e32 v102, v50, v47
	v_add_f32_e32 v103, v51, v48
	v_add_f32_e32 v97, v52, v49
	v_add_f32_e32 v98, v53, v71
	v_add_f32_e32 v94, v54, v72
	v_add_f32_e32 v95, v55, v73
	v_add_f32_e32 v90, v56, v74
	v_add_f32_e32 v91, v57, v75
	v_add_f32_e32 v87, v58, v77
	v_add_f32_e32 v88, v59, v79
	v_add_f32_e32 v84, v60, v80
	v_add_f32_e32 v85, v61, v82
	v_add_f32_e32 v82, v62, v83
	v_add_f32_e32 v80, v63, v86
	v_add_f32_e32 v79, v64, v89
	v_add_f32_e32 v77, v65, v92
	v_add_f32_e32 v75, v34, v96
	v_add_f32_e32 v73, v35, v99
	v_add_f32_e32 v74, v36, v100
	v_add_f32_e32 v72, v37, v104
	v_add_f32_e32 v71, v38, v105
	v_add_f32_e32 v48, v39, v106
	v_add_f32_e32 v49, v40, v107
	v_add_f32_e32 v47, v69, v108
	v_add_f32_e32 v46, v70, v110
	v_add_f32_e32 v44, v76, v111
	v_add_f32_e32 v45, v78, v112
	v_add_f32_e32 v41, v81, v114
	v_add_f32_e32 v31, v93, v116
	v_add_f32_e32 v28, v101, v121
	v_add_f32_e32 v25, v109, v126
	v_add_f32_e32 v22, v113, v131
	v_add_f32_e32 v114, v115, v135
	v_add_f32_e32 v111, v117, v136
	v_add_f32_e32 v112, v118, v137
	v_add_f32_e32 v110, v119, v138
	v_add_f32_e32 v108, v120, v139
	v_add_f32_e32 v106, v122, v140
	v_add_f32_e32 v107, v123, v141
	v_add_f32_e32 v105, v124, v142
	v_add_f32_e32 v104, v125, v143
	v_add_f32_e32 v99, v127, v144
	v_add_f32_e32 v100, v128, v145
	v_add_f32_e32 v96, v129, v146
	v_add_f32_e32 v92, v130, v147
	v_add_f32_e32 v89, v132, v148
	v_add_f32_e32 v86, v133, v149
	v_add_f32_e32 v83, v134, v150
	s_cbranch_scc1 .LBB0_857
	v_mul_f32_e32 v0, v0, v2
	v_mul_f32_e32 v2, v66, v3
	v_cndmask_b32_e32 v0, v16, v0, vcc
	v_cndmask_b32_e32 v2, v17, v2, vcc
	v_cvt_pk_bf16_f32 v116, v0, v2
	v_cndmask_b32_e32 v0, v42, v4, vcc
	v_cndmask_b32_e32 v2, v43, v5, vcc
	v_cvt_pk_bf16_f32 v121, v0, v2
	v_cndmask_b32_e32 v0, v32, v6, vcc
	v_cndmask_b32_e32 v2, v33, v7, vcc
	v_cvt_pk_bf16_f32 v126, v0, v2
	v_cndmask_b32_e32 v0, v29, v8, vcc
	v_cndmask_b32_e32 v2, v30, v9, vcc
	v_cvt_pk_bf16_f32 v131, v0, v2
	v_cndmask_b32_e32 v0, v26, v10, vcc
	v_cndmask_b32_e32 v2, v27, v11, vcc
	v_cvt_pk_bf16_f32 v135, v0, v2
	v_cndmask_b32_e32 v0, v23, v12, vcc
	v_cndmask_b32_e32 v2, v24, v13, vcc
	v_cvt_pk_bf16_f32 v136, v0, v2
	v_cndmask_b32_e32 v0, v21, v14, vcc
	v_cndmask_b32_e32 v2, v20, v15, vcc
	v_cvt_pk_bf16_f32 v137, v0, v2
	v_cndmask_b32_e32 v0, v19, v67, vcc
	v_cndmask_b32_e32 v2, v18, v68, vcc
	v_cvt_pk_bf16_f32 v138, v0, v2
	v_cndmask_b32_e32 v0, v102, v50, vcc
	v_cndmask_b32_e32 v2, v103, v51, vcc
	v_cvt_pk_bf16_f32 v155, v0, v2
	v_cndmask_b32_e32 v0, v97, v52, vcc
	v_cndmask_b32_e32 v2, v98, v53, vcc
	v_cvt_pk_bf16_f32 v156, v0, v2
	v_cndmask_b32_e32 v0, v94, v54, vcc
	v_cndmask_b32_e32 v2, v95, v55, vcc
	v_cvt_pk_bf16_f32 v157, v0, v2
	v_cndmask_b32_e32 v0, v90, v56, vcc
	v_cndmask_b32_e32 v2, v91, v57, vcc
	v_cvt_pk_bf16_f32 v158, v0, v2
	v_cndmask_b32_e32 v0, v87, v58, vcc
	v_cndmask_b32_e32 v2, v88, v59, vcc
	v_cvt_pk_bf16_f32 v159, v0, v2
	v_cndmask_b32_e32 v0, v84, v60, vcc
	v_cndmask_b32_e32 v2, v85, v61, vcc
	v_cvt_pk_bf16_f32 v160, v0, v2
	v_cndmask_b32_e32 v0, v82, v62, vcc
	v_cndmask_b32_e32 v2, v80, v63, vcc
	v_cvt_pk_bf16_f32 v161, v0, v2
	v_cndmask_b32_e32 v0, v79, v64, vcc
	v_cndmask_b32_e32 v2, v77, v65, vcc
	v_cvt_pk_bf16_f32 v162, v0, v2
	v_cndmask_b32_e32 v0, v75, v34, vcc
	v_cndmask_b32_e32 v2, v73, v35, vcc
	v_cvt_pk_bf16_f32 v154, v0, v2
	v_cndmask_b32_e32 v0, v74, v36, vcc
	v_cndmask_b32_e32 v2, v72, v37, vcc
	v_cvt_pk_bf16_f32 v153, v0, v2
	v_cndmask_b32_e32 v0, v71, v38, vcc
	v_cndmask_b32_e32 v2, v48, v39, vcc
	v_cvt_pk_bf16_f32 v152, v0, v2
	v_cndmask_b32_e32 v0, v49, v40, vcc
	v_cndmask_b32_e32 v2, v47, v69, vcc
	v_cvt_pk_bf16_f32 v151, v0, v2
	v_cndmask_b32_e32 v0, v46, v70, vcc
	v_cndmask_b32_e32 v2, v44, v76, vcc
	v_cvt_pk_bf16_f32 v150, v0, v2
	v_cndmask_b32_e32 v0, v45, v78, vcc
	v_cndmask_b32_e32 v2, v41, v81, vcc
	v_cvt_pk_bf16_f32 v149, v0, v2
	v_cndmask_b32_e32 v0, v31, v93, vcc
	v_cndmask_b32_e32 v2, v28, v101, vcc
	v_cvt_pk_bf16_f32 v148, v0, v2
	v_cndmask_b32_e32 v0, v25, v109, vcc
	v_cndmask_b32_e32 v2, v22, v113, vcc
	v_cvt_pk_bf16_f32 v147, v0, v2
	v_cndmask_b32_e32 v0, v114, v115, vcc
	v_cndmask_b32_e32 v2, v111, v117, vcc
	v_cvt_pk_bf16_f32 v146, v0, v2
	v_cndmask_b32_e32 v0, v112, v118, vcc
	v_cndmask_b32_e32 v2, v110, v119, vcc
	v_cvt_pk_bf16_f32 v145, v0, v2
	v_cndmask_b32_e32 v0, v108, v120, vcc
	v_cndmask_b32_e32 v2, v106, v122, vcc
	v_cvt_pk_bf16_f32 v144, v0, v2
	v_cndmask_b32_e32 v0, v107, v123, vcc
	v_cndmask_b32_e32 v2, v105, v124, vcc
	v_cvt_pk_bf16_f32 v143, v0, v2
	v_cndmask_b32_e32 v0, v104, v125, vcc
	v_cndmask_b32_e32 v2, v99, v127, vcc
	v_cvt_pk_bf16_f32 v142, v0, v2
	v_cndmask_b32_e32 v0, v100, v128, vcc
	v_cndmask_b32_e32 v2, v96, v129, vcc
	v_cvt_pk_bf16_f32 v141, v0, v2
	v_cndmask_b32_e32 v0, v92, v130, vcc
	v_cndmask_b32_e32 v2, v89, v132, vcc
	v_cvt_pk_bf16_f32 v140, v0, v2
	v_cndmask_b32_e32 v0, v86, v133, vcc
	v_cndmask_b32_e32 v2, v83, v134, vcc
	v_cvt_pk_bf16_f32 v139, v0, v2
	s_mov_b64 s[0:1], 0

.LBB0_909:
	s_lshl_b32 s0, s13, 3
	s_and_b32 s0, s0, 56
	s_bfe_u32 s1, s13, 0x30003
	s_or_b32 s20, s0, s1
	s_lshl_b32 s0, s13, 1
	s_and_b32 s0, s0, 0xffffff80
	s_lshl_b32 s1, s20, 18
	v_readlane_b32 s22, v251, 37
	s_waitcnt vmcnt(12)
	v_mov_b32_e32 v36, v178
	v_readlane_b32 s23, v251, 38
	s_add_u32 s22, s22, s1
	s_addc_u32 s23, s23, 0
	v_ashrrev_i32_e32 v34, 3, v36
	s_ashr_i32 s1, s0, 31
	v_lshlrev_b32_e32 v0, 3, v36
	v_ashrrev_i32_e32 v35, 31, v34
	s_lshl_b64 s[24:25], s[0:1], 11
	v_and_b32_e32 v37, 56, v0
	s_waitcnt vmcnt(5)
	v_lshlrev_b64 v[2:3], 11, v[34:35]
	s_add_u32 s24, s68, s24
	v_lshl_add_u64 v[4:5], s[22:23], 0, v[2:3]
	v_lshlrev_b32_e32 v0, 1, v37
	s_addc_u32 s25, s69, s25
	v_lshl_add_u64 v[68:69], v[4:5], 0, v[0:1]
	v_lshl_add_u64 v[2:3], s[24:25], 0, v[2:3]
	v_lshl_add_u64 v[70:71], v[2:3], 0, v[0:1]
	v_and_b32_e32 v0, 7, v36
	v_bfe_u32 v66, v36, 4, 3
	v_xor_b32_e32 v66, v66, v0
	v_sub_u32_e32 v66, v66, v0
	v_lshlrev_b32_e32 v66, 4, v66
	v_ashrrev_i32_e32 v67, 31, v66
	v_lshl_add_u64 v[68:69], v[68:69], 0, v[66:67]
	v_lshl_add_u64 v[70:71], v[70:71], 0, v[66:67]
	v_add_co_u32_e32 v72, vcc, s73, v68
	s_nop 1
	v_addc_co_u32_e32 v73, vcc, 0, v69, vcc
	v_add_co_u32_e32 v74, vcc, s73, v70
	s_nop 1
	v_addc_co_u32_e32 v75, vcc, 0, v71, vcc
	v_add_co_u32_e32 v76, vcc, s52, v68
	s_nop 1
	v_addc_co_u32_e32 v77, vcc, 0, v69, vcc
	v_add_co_u32_e32 v78, vcc, s52, v70
	s_nop 1
	v_addc_co_u32_e32 v79, vcc, 0, v71, vcc
	v_add_co_u32_e32 v80, vcc, s53, v68
	s_nop 1
	v_addc_co_u32_e32 v81, vcc, 0, v69, vcc
	v_add_co_u32_e32 v82, vcc, s53, v70
	s_nop 1
	v_addc_co_u32_e32 v83, vcc, 0, v71, vcc
	v_and_b32_e32 v0, 31, v36
	v_bfe_u32 v66, v36, 5, 1
	v_bfe_u32 v67, v36, 1, 3
	v_xor_b32_e32 v66, v66, v67
	v_lshlrev_b32_e32 v66, 4, v66
	v_lshl_add_u32 v66, v0, 7, v66
	v_bfe_u32 v67, v36, 7, 1
	v_lshl_add_u32 v86, v67, 13, v66
	v_bfe_u32 v67, v36, 6, 1
	v_lshl_add_u32 v90, v67, 13, v66
	v_add_u32_e32 v90, 0x4000, v90
	v_xor_b32_e32 v87, 32, v86
	v_xor_b32_e32 v91, 32, v90
	v_xor_b32_e32 v88, 64, v86
	v_xor_b32_e32 v92, 64, v90
	v_xor_b32_e32 v89, 96, v86
	v_xor_b32_e32 v93, 96, v90
	v_lshrrev_b32_e32 v66, 6, v36
	v_lshlrev_b32_e32 v66, 10, v66
	s_nop 1
	v_readfirstlane_b32 s14, v66
	s_mov_b32 s21, 0
	s_lshl_b32 s20, s20, 7
	s_add_u32 m0, s14, 0x800
	s_nop 0
	global_load_lds_dwordx4 v[68:69], off
	s_add_u32 m0, s14, 0x1800
	s_nop 0
	global_load_lds_dwordx4 v[72:73], off
	s_add_u32 m0, s14, 0x2800
	s_nop 0
	global_load_lds_dwordx4 v[76:77], off
	s_add_u32 m0, s14, 0x3800
	s_nop 0
	global_load_lds_dwordx4 v[80:81], off
	s_add_u32 m0, s14, 0x4800
	s_nop 0
	global_load_lds_dwordx4 v[70:71], off
	s_add_u32 m0, s14, 0x5800
	s_nop 0
	global_load_lds_dwordx4 v[74:75], off
	s_add_u32 m0, s14, 0x6800
	s_nop 0
	global_load_lds_dwordx4 v[78:79], off
	s_add_u32 m0, s14, 0x7800
	s_nop 0
	global_load_lds_dwordx4 v[82:83], off
	s_add_u32 m0, s14, 0x8780
	s_nop 0
	global_load_lds_dwordx4 v[68:69], off offset:128
	s_add_u32 m0, s14, 0x9780
	s_nop 0
	global_load_lds_dwordx4 v[72:73], off offset:128
	s_add_u32 m0, s14, 0xa780
	s_nop 0
	global_load_lds_dwordx4 v[76:77], off offset:128
	s_add_u32 m0, s14, 0xb780
	s_nop 0
	global_load_lds_dwordx4 v[80:81], off offset:128
	s_add_u32 m0, s14, 0xc780
	s_nop 0
	global_load_lds_dwordx4 v[70:71], off offset:128
	s_add_u32 m0, s14, 0xd780
	s_nop 0
	global_load_lds_dwordx4 v[74:75], off offset:128
	s_add_u32 m0, s14, 0xe780
	s_nop 0
	global_load_lds_dwordx4 v[78:79], off offset:128
	s_add_u32 m0, s14, 0xf780
	s_nop 0
	global_load_lds_dwordx4 v[82:83], off offset:128
	s_waitcnt vmcnt(8)
	s_barrier
	ds_read_b128 v[94:97], v86 offset:2048
	ds_read_b128 v[98:101], v86 offset:6144
	ds_read_b128 v[102:105], v90 offset:2048
	ds_read_b128 v[106:109], v90 offset:6144
	ds_read_b128 v[110:113], v87 offset:2048
	ds_read_b128 v[114:117], v87 offset:6144
	ds_read_b128 v[118:121], v91 offset:2048
	ds_read_b128 v[122:125], v91 offset:6144
	ds_read_b128 v[126:129], v88 offset:2048
	ds_read_b128 v[130:133], v88 offset:6144
	ds_read_b128 v[134:137], v92 offset:2048
	ds_read_b128 v[138:141], v92 offset:6144
	ds_read_b128 v[142:145], v89 offset:2048
	ds_read_b128 v[146:149], v89 offset:6144
	ds_read_b128 v[150:153], v93 offset:2048
	ds_read_b128 v[154:157], v93 offset:6144
	s_waitcnt lgkmcnt(0)
	s_barrier
	s_add_u32 m0, s14, 0x700
	s_nop 0
	global_load_lds_dwordx4 v[68:69], off offset:256
	s_add_u32 m0, s14, 0x1700
	s_nop 0
	global_load_lds_dwordx4 v[72:73], off offset:256
	s_add_u32 m0, s14, 0x2700
	s_nop 0
	global_load_lds_dwordx4 v[76:77], off offset:256
	s_add_u32 m0, s14, 0x3700
	s_nop 0
	global_load_lds_dwordx4 v[80:81], off offset:256
	s_add_u32 m0, s14, 0x4700
	s_nop 0
	global_load_lds_dwordx4 v[70:71], off offset:256
	s_add_u32 m0, s14, 0x5700
	s_nop 0
	global_load_lds_dwordx4 v[74:75], off offset:256
	s_add_u32 m0, s14, 0x6700
	s_nop 0
	global_load_lds_dwordx4 v[78:79], off offset:256
	s_add_u32 m0, s14, 0x7700
	s_nop 0
	global_load_lds_dwordx4 v[82:83], off offset:256
	v_mfma_f32_32x32x16_bf16 v[34:49], v[94:97], v[102:105], 0
	v_mfma_f32_32x32x16_bf16 v[50:65], v[94:97], v[106:109], 0
	v_mfma_f32_32x32x16_bf16 v[2:17], v[98:101], v[102:105], 0
	v_mfma_f32_32x32x16_bf16 v[18:33], v[98:101], v[106:109], 0
	s_waitcnt vmcnt(8)
	s_barrier
	ds_read_b128 v[94:97], v86 offset:34816
	ds_read_b128 v[98:101], v86 offset:38912
	ds_read_b128 v[102:105], v90 offset:34816
	ds_read_b128 v[106:109], v90 offset:38912
	v_mfma_f32_32x32x16_bf16 v[34:49], v[110:113], v[118:121], v[34:49]
	v_mfma_f32_32x32x16_bf16 v[50:65], v[110:113], v[122:125], v[50:65]
	v_mfma_f32_32x32x16_bf16 v[2:17], v[114:117], v[118:121], v[2:17]
	v_mfma_f32_32x32x16_bf16 v[18:33], v[114:117], v[122:125], v[18:33]
	ds_read_b128 v[110:113], v87 offset:34816
	ds_read_b128 v[114:117], v87 offset:38912
	ds_read_b128 v[118:121], v91 offset:34816
	ds_read_b128 v[122:125], v91 offset:38912
	v_mfma_f32_32x32x16_bf16 v[34:49], v[126:129], v[134:137], v[34:49]
	v_mfma_f32_32x32x16_bf16 v[50:65], v[126:129], v[138:141], v[50:65]
	v_mfma_f32_32x32x16_bf16 v[2:17], v[130:133], v[134:137], v[2:17]
	v_mfma_f32_32x32x16_bf16 v[18:33], v[130:133], v[138:141], v[18:33]
	ds_read_b128 v[126:129], v88 offset:34816
	ds_read_b128 v[130:133], v88 offset:38912
	ds_read_b128 v[134:137], v92 offset:34816
	ds_read_b128 v[138:141], v92 offset:38912
	v_mfma_f32_32x32x16_bf16 v[34:49], v[142:145], v[150:153], v[34:49]
	v_mfma_f32_32x32x16_bf16 v[50:65], v[142:145], v[154:157], v[50:65]
	v_mfma_f32_32x32x16_bf16 v[2:17], v[146:149], v[150:153], v[2:17]
	v_mfma_f32_32x32x16_bf16 v[18:33], v[146:149], v[154:157], v[18:33]
	ds_read_b128 v[142:145], v89 offset:34816
	ds_read_b128 v[146:149], v89 offset:38912
	ds_read_b128 v[150:153], v93 offset:34816
	ds_read_b128 v[154:157], v93 offset:38912
	s_waitcnt lgkmcnt(0)
	s_barrier
	s_add_u32 m0, s14, 0x8680
	s_nop 0
	global_load_lds_dwordx4 v[68:69], off offset:384
	s_add_u32 m0, s14, 0x9680
	s_nop 0
	global_load_lds_dwordx4 v[72:73], off offset:384
	s_add_u32 m0, s14, 0xa680
	s_nop 0
	global_load_lds_dwordx4 v[76:77], off offset:384
	s_add_u32 m0, s14, 0xb680
	s_nop 0
	global_load_lds_dwordx4 v[80:81], off offset:384
	s_add_u32 m0, s14, 0xc680
	s_nop 0
	global_load_lds_dwordx4 v[70:71], off offset:384
	s_add_u32 m0, s14, 0xd680
	s_nop 0
	global_load_lds_dwordx4 v[74:75], off offset:384
	s_add_u32 m0, s14, 0xe680
	s_nop 0
	global_load_lds_dwordx4 v[78:79], off offset:384
	s_add_u32 m0, s14, 0xf680
	s_nop 0
	global_load_lds_dwordx4 v[82:83], off offset:384
	v_mfma_f32_32x32x16_bf16 v[34:49], v[94:97], v[102:105], v[34:49]
	v_mfma_f32_32x32x16_bf16 v[50:65], v[94:97], v[106:109], v[50:65]
	v_mfma_f32_32x32x16_bf16 v[2:17], v[98:101], v[102:105], v[2:17]
	v_mfma_f32_32x32x16_bf16 v[18:33], v[98:101], v[106:109], v[18:33]
	s_waitcnt vmcnt(8)
	s_barrier
	ds_read_b128 v[94:97], v86 offset:2048
	ds_read_b128 v[98:101], v86 offset:6144
	ds_read_b128 v[102:105], v90 offset:2048
	ds_read_b128 v[106:109], v90 offset:6144
	v_mfma_f32_32x32x16_bf16 v[34:49], v[110:113], v[118:121], v[34:49]
	v_mfma_f32_32x32x16_bf16 v[50:65], v[110:113], v[122:125], v[50:65]
	v_mfma_f32_32x32x16_bf16 v[2:17], v[114:117], v[118:121], v[2:17]
	v_mfma_f32_32x32x16_bf16 v[18:33], v[114:117], v[122:125], v[18:33]
	ds_read_b128 v[110:113], v87 offset:2048
	ds_read_b128 v[114:117], v87 offset:6144
	ds_read_b128 v[118:121], v91 offset:2048
	ds_read_b128 v[122:125], v91 offset:6144
	v_mfma_f32_32x32x16_bf16 v[34:49], v[126:129], v[134:137], v[34:49]
	v_mfma_f32_32x32x16_bf16 v[50:65], v[126:129], v[138:141], v[50:65]
	v_mfma_f32_32x32x16_bf16 v[2:17], v[130:133], v[134:137], v[2:17]
	v_mfma_f32_32x32x16_bf16 v[18:33], v[130:133], v[138:141], v[18:33]
	ds_read_b128 v[126:129], v88 offset:2048
	ds_read_b128 v[130:133], v88 offset:6144
	ds_read_b128 v[134:137], v92 offset:2048
	ds_read_b128 v[138:141], v92 offset:6144
	v_mfma_f32_32x32x16_bf16 v[34:49], v[142:145], v[150:153], v[34:49]
	v_mfma_f32_32x32x16_bf16 v[50:65], v[142:145], v[154:157], v[50:65]
	v_mfma_f32_32x32x16_bf16 v[2:17], v[146:149], v[150:153], v[2:17]
	v_mfma_f32_32x32x16_bf16 v[18:33], v[146:149], v[154:157], v[18:33]
	ds_read_b128 v[142:145], v89 offset:2048
	ds_read_b128 v[146:149], v89 offset:6144
	ds_read_b128 v[150:153], v93 offset:2048
	ds_read_b128 v[154:157], v93 offset:6144
	s_waitcnt lgkmcnt(0)
	s_barrier
	s_add_u32 m0, s14, 0x600
	s_nop 0
	global_load_lds_dwordx4 v[68:69], off offset:512
	s_add_u32 m0, s14, 0x1600
	s_nop 0
	global_load_lds_dwordx4 v[72:73], off offset:512
	s_add_u32 m0, s14, 0x2600
	s_nop 0
	global_load_lds_dwordx4 v[76:77], off offset:512
	s_add_u32 m0, s14, 0x3600
	s_nop 0
	global_load_lds_dwordx4 v[80:81], off offset:512
	s_add_u32 m0, s14, 0x4600
	s_nop 0
	global_load_lds_dwordx4 v[70:71], off offset:512
	s_add_u32 m0, s14, 0x5600
	s_nop 0
	global_load_lds_dwordx4 v[74:75], off offset:512
	s_add_u32 m0, s14, 0x6600
	s_nop 0
	global_load_lds_dwordx4 v[78:79], off offset:512
	s_add_u32 m0, s14, 0x7600
	s_nop 0
	global_load_lds_dwordx4 v[82:83], off offset:512
	v_mfma_f32_32x32x16_bf16 v[34:49], v[94:97], v[102:105], v[34:49]
	v_mfma_f32_32x32x16_bf16 v[50:65], v[94:97], v[106:109], v[50:65]
	v_mfma_f32_32x32x16_bf16 v[2:17], v[98:101], v[102:105], v[2:17]
	v_mfma_f32_32x32x16_bf16 v[18:33], v[98:101], v[106:109], v[18:33]
	s_waitcnt vmcnt(8)
	s_barrier
	ds_read_b128 v[94:97], v86 offset:34816
	ds_read_b128 v[98:101], v86 offset:38912
	ds_read_b128 v[102:105], v90 offset:34816
	ds_read_b128 v[106:109], v90 offset:38912
	v_mfma_f32_32x32x16_bf16 v[34:49], v[110:113], v[118:121], v[34:49]
	v_mfma_f32_32x32x16_bf16 v[50:65], v[110:113], v[122:125], v[50:65]
	v_mfma_f32_32x32x16_bf16 v[2:17], v[114:117], v[118:121], v[2:17]
	v_mfma_f32_32x32x16_bf16 v[18:33], v[114:117], v[122:125], v[18:33]
	ds_read_b128 v[110:113], v87 offset:34816
	ds_read_b128 v[114:117], v87 offset:38912
	ds_read_b128 v[118:121], v91 offset:34816
	ds_read_b128 v[122:125], v91 offset:38912
	v_mfma_f32_32x32x16_bf16 v[34:49], v[126:129], v[134:137], v[34:49]
	v_mfma_f32_32x32x16_bf16 v[50:65], v[126:129], v[138:141], v[50:65]
	v_mfma_f32_32x32x16_bf16 v[2:17], v[130:133], v[134:137], v[2:17]
	v_mfma_f32_32x32x16_bf16 v[18:33], v[130:133], v[138:141], v[18:33]
	ds_read_b128 v[126:129], v88 offset:34816
	ds_read_b128 v[130:133], v88 offset:38912
	ds_read_b128 v[134:137], v92 offset:34816
	ds_read_b128 v[138:141], v92 offset:38912
	v_mfma_f32_32x32x16_bf16 v[34:49], v[142:145], v[150:153], v[34:49]
	v_mfma_f32_32x32x16_bf16 v[50:65], v[142:145], v[154:157], v[50:65]
	v_mfma_f32_32x32x16_bf16 v[2:17], v[146:149], v[150:153], v[2:17]
	v_mfma_f32_32x32x16_bf16 v[18:33], v[146:149], v[154:157], v[18:33]
	ds_read_b128 v[142:145], v89 offset:34816
	ds_read_b128 v[146:149], v89 offset:38912
	ds_read_b128 v[150:153], v93 offset:34816
	ds_read_b128 v[154:157], v93 offset:38912
	s_waitcnt lgkmcnt(0)
	s_barrier
	s_add_u32 m0, s14, 0x8580
	s_nop 0
	global_load_lds_dwordx4 v[68:69], off offset:640
	s_add_u32 m0, s14, 0x9580
	s_nop 0
	global_load_lds_dwordx4 v[72:73], off offset:640
	s_add_u32 m0, s14, 0xa580
	s_nop 0
	global_load_lds_dwordx4 v[76:77], off offset:640
	s_add_u32 m0, s14, 0xb580
	s_nop 0
	global_load_lds_dwordx4 v[80:81], off offset:640
	s_add_u32 m0, s14, 0xc580
	s_nop 0
	global_load_lds_dwordx4 v[70:71], off offset:640
	s_add_u32 m0, s14, 0xd580
	s_nop 0
	global_load_lds_dwordx4 v[74:75], off offset:640
	s_add_u32 m0, s14, 0xe580
	s_nop 0
	global_load_lds_dwordx4 v[78:79], off offset:640
	s_add_u32 m0, s14, 0xf580
	s_nop 0
	global_load_lds_dwordx4 v[82:83], off offset:640
	v_mfma_f32_32x32x16_bf16 v[34:49], v[94:97], v[102:105], v[34:49]
	v_mfma_f32_32x32x16_bf16 v[50:65], v[94:97], v[106:109], v[50:65]
	v_mfma_f32_32x32x16_bf16 v[2:17], v[98:101], v[102:105], v[2:17]
	v_mfma_f32_32x32x16_bf16 v[18:33], v[98:101], v[106:109], v[18:33]
	s_waitcnt vmcnt(8)
	s_barrier
	ds_read_b128 v[94:97], v86 offset:2048
	ds_read_b128 v[98:101], v86 offset:6144
	ds_read_b128 v[102:105], v90 offset:2048
	ds_read_b128 v[106:109], v90 offset:6144
	v_mfma_f32_32x32x16_bf16 v[34:49], v[110:113], v[118:121], v[34:49]
	v_mfma_f32_32x32x16_bf16 v[50:65], v[110:113], v[122:125], v[50:65]
	v_mfma_f32_32x32x16_bf16 v[2:17], v[114:117], v[118:121], v[2:17]
	v_mfma_f32_32x32x16_bf16 v[18:33], v[114:117], v[122:125], v[18:33]
	ds_read_b128 v[110:113], v87 offset:2048
	ds_read_b128 v[114:117], v87 offset:6144
	ds_read_b128 v[118:121], v91 offset:2048
	ds_read_b128 v[122:125], v91 offset:6144
	v_mfma_f32_32x32x16_bf16 v[34:49], v[126:129], v[134:137], v[34:49]
	v_mfma_f32_32x32x16_bf16 v[50:65], v[126:129], v[138:141], v[50:65]
	v_mfma_f32_32x32x16_bf16 v[2:17], v[130:133], v[134:137], v[2:17]
	v_mfma_f32_32x32x16_bf16 v[18:33], v[130:133], v[138:141], v[18:33]
	ds_read_b128 v[126:129], v88 offset:2048
	ds_read_b128 v[130:133], v88 offset:6144
	ds_read_b128 v[134:137], v92 offset:2048
	ds_read_b128 v[138:141], v92 offset:6144
	v_mfma_f32_32x32x16_bf16 v[34:49], v[142:145], v[150:153], v[34:49]
	v_mfma_f32_32x32x16_bf16 v[50:65], v[142:145], v[154:157], v[50:65]
	v_mfma_f32_32x32x16_bf16 v[2:17], v[146:149], v[150:153], v[2:17]
	v_mfma_f32_32x32x16_bf16 v[18:33], v[146:149], v[154:157], v[18:33]
	ds_read_b128 v[142:145], v89 offset:2048
	ds_read_b128 v[146:149], v89 offset:6144
	ds_read_b128 v[150:153], v93 offset:2048
	ds_read_b128 v[154:157], v93 offset:6144
	s_waitcnt lgkmcnt(0)
	s_barrier
	s_add_u32 m0, s14, 0x500
	s_nop 0
	global_load_lds_dwordx4 v[68:69], off offset:768
	s_add_u32 m0, s14, 0x1500
	s_nop 0
	global_load_lds_dwordx4 v[72:73], off offset:768
	s_add_u32 m0, s14, 0x2500
	s_nop 0
	global_load_lds_dwordx4 v[76:77], off offset:768
	s_add_u32 m0, s14, 0x3500
	s_nop 0
	global_load_lds_dwordx4 v[80:81], off offset:768
	s_add_u32 m0, s14, 0x4500
	s_nop 0
	global_load_lds_dwordx4 v[70:71], off offset:768
	s_add_u32 m0, s14, 0x5500
	s_nop 0
	global_load_lds_dwordx4 v[74:75], off offset:768
	s_add_u32 m0, s14, 0x6500
	s_nop 0
	global_load_lds_dwordx4 v[78:79], off offset:768
	s_add_u32 m0, s14, 0x7500
	s_nop 0
	global_load_lds_dwordx4 v[82:83], off offset:768
	v_mfma_f32_32x32x16_bf16 v[34:49], v[94:97], v[102:105], v[34:49]
	v_mfma_f32_32x32x16_bf16 v[50:65], v[94:97], v[106:109], v[50:65]
	v_mfma_f32_32x32x16_bf16 v[2:17], v[98:101], v[102:105], v[2:17]
	v_mfma_f32_32x32x16_bf16 v[18:33], v[98:101], v[106:109], v[18:33]
	s_waitcnt vmcnt(8)
	s_barrier
	ds_read_b128 v[94:97], v86 offset:34816
	ds_read_b128 v[98:101], v86 offset:38912
	ds_read_b128 v[102:105], v90 offset:34816
	ds_read_b128 v[106:109], v90 offset:38912
	v_mfma_f32_32x32x16_bf16 v[34:49], v[110:113], v[118:121], v[34:49]
	v_mfma_f32_32x32x16_bf16 v[50:65], v[110:113], v[122:125], v[50:65]
	v_mfma_f32_32x32x16_bf16 v[2:17], v[114:117], v[118:121], v[2:17]
	v_mfma_f32_32x32x16_bf16 v[18:33], v[114:117], v[122:125], v[18:33]
	ds_read_b128 v[110:113], v87 offset:34816
	ds_read_b128 v[114:117], v87 offset:38912
	ds_read_b128 v[118:121], v91 offset:34816
	ds_read_b128 v[122:125], v91 offset:38912
	v_mfma_f32_32x32x16_bf16 v[34:49], v[126:129], v[134:137], v[34:49]
	v_mfma_f32_32x32x16_bf16 v[50:65], v[126:129], v[138:141], v[50:65]
	v_mfma_f32_32x32x16_bf16 v[2:17], v[130:133], v[134:137], v[2:17]
	v_mfma_f32_32x32x16_bf16 v[18:33], v[130:133], v[138:141], v[18:33]
	ds_read_b128 v[126:129], v88 offset:34816
	ds_read_b128 v[130:133], v88 offset:38912
	ds_read_b128 v[134:137], v92 offset:34816
	ds_read_b128 v[138:141], v92 offset:38912
	v_mfma_f32_32x32x16_bf16 v[34:49], v[142:145], v[150:153], v[34:49]
	v_mfma_f32_32x32x16_bf16 v[50:65], v[142:145], v[154:157], v[50:65]
	v_mfma_f32_32x32x16_bf16 v[2:17], v[146:149], v[150:153], v[2:17]
	v_mfma_f32_32x32x16_bf16 v[18:33], v[146:149], v[154:157], v[18:33]
	ds_read_b128 v[142:145], v89 offset:34816
	ds_read_b128 v[146:149], v89 offset:38912
	ds_read_b128 v[150:153], v93 offset:34816
	ds_read_b128 v[154:157], v93 offset:38912
	s_waitcnt lgkmcnt(0)
	s_barrier
	s_add_u32 m0, s14, 0x8480
	s_nop 0
	global_load_lds_dwordx4 v[68:69], off offset:896
	s_add_u32 m0, s14, 0x9480
	s_nop 0
	global_load_lds_dwordx4 v[72:73], off offset:896
	s_add_u32 m0, s14, 0xa480
	s_nop 0
	global_load_lds_dwordx4 v[76:77], off offset:896
	s_add_u32 m0, s14, 0xb480
	s_nop 0
	global_load_lds_dwordx4 v[80:81], off offset:896
	s_add_u32 m0, s14, 0xc480
	s_nop 0
	global_load_lds_dwordx4 v[70:71], off offset:896
	s_add_u32 m0, s14, 0xd480
	s_nop 0
	global_load_lds_dwordx4 v[74:75], off offset:896
	s_add_u32 m0, s14, 0xe480
	s_nop 0
	global_load_lds_dwordx4 v[78:79], off offset:896
	s_add_u32 m0, s14, 0xf480
	s_nop 0
	global_load_lds_dwordx4 v[82:83], off offset:896
	v_mfma_f32_32x32x16_bf16 v[34:49], v[94:97], v[102:105], v[34:49]
	v_mfma_f32_32x32x16_bf16 v[50:65], v[94:97], v[106:109], v[50:65]
	v_mfma_f32_32x32x16_bf16 v[2:17], v[98:101], v[102:105], v[2:17]
	v_mfma_f32_32x32x16_bf16 v[18:33], v[98:101], v[106:109], v[18:33]
	s_waitcnt vmcnt(8)
	s_barrier
	ds_read_b128 v[94:97], v86 offset:2048
	ds_read_b128 v[98:101], v86 offset:6144
	ds_read_b128 v[102:105], v90 offset:2048
	ds_read_b128 v[106:109], v90 offset:6144
	v_mfma_f32_32x32x16_bf16 v[34:49], v[110:113], v[118:121], v[34:49]
	v_mfma_f32_32x32x16_bf16 v[50:65], v[110:113], v[122:125], v[50:65]
	v_mfma_f32_32x32x16_bf16 v[2:17], v[114:117], v[118:121], v[2:17]
	v_mfma_f32_32x32x16_bf16 v[18:33], v[114:117], v[122:125], v[18:33]
	ds_read_b128 v[110:113], v87 offset:2048
	ds_read_b128 v[114:117], v87 offset:6144
	ds_read_b128 v[118:121], v91 offset:2048
	ds_read_b128 v[122:125], v91 offset:6144
	v_mfma_f32_32x32x16_bf16 v[34:49], v[126:129], v[134:137], v[34:49]
	v_mfma_f32_32x32x16_bf16 v[50:65], v[126:129], v[138:141], v[50:65]
	v_mfma_f32_32x32x16_bf16 v[2:17], v[130:133], v[134:137], v[2:17]
	v_mfma_f32_32x32x16_bf16 v[18:33], v[130:133], v[138:141], v[18:33]
	ds_read_b128 v[126:129], v88 offset:2048
	ds_read_b128 v[130:133], v88 offset:6144
	ds_read_b128 v[134:137], v92 offset:2048
	ds_read_b128 v[138:141], v92 offset:6144
	v_mfma_f32_32x32x16_bf16 v[34:49], v[142:145], v[150:153], v[34:49]
	v_mfma_f32_32x32x16_bf16 v[50:65], v[142:145], v[154:157], v[50:65]
	v_mfma_f32_32x32x16_bf16 v[2:17], v[146:149], v[150:153], v[2:17]
	v_mfma_f32_32x32x16_bf16 v[18:33], v[146:149], v[154:157], v[18:33]
	ds_read_b128 v[142:145], v89 offset:2048
	ds_read_b128 v[146:149], v89 offset:6144
	ds_read_b128 v[150:153], v93 offset:2048
	ds_read_b128 v[154:157], v93 offset:6144
	s_waitcnt lgkmcnt(0)
	s_barrier
	s_add_u32 m0, s14, 0x400
	s_nop 0
	global_load_lds_dwordx4 v[68:69], off offset:1024
	s_add_u32 m0, s14, 0x1400
	s_nop 0
	global_load_lds_dwordx4 v[72:73], off offset:1024
	s_add_u32 m0, s14, 0x2400
	s_nop 0
	global_load_lds_dwordx4 v[76:77], off offset:1024
	s_add_u32 m0, s14, 0x3400
	s_nop 0
	global_load_lds_dwordx4 v[80:81], off offset:1024
	s_add_u32 m0, s14, 0x4400
	s_nop 0
	global_load_lds_dwordx4 v[70:71], off offset:1024
	s_add_u32 m0, s14, 0x5400
	s_nop 0
	global_load_lds_dwordx4 v[74:75], off offset:1024
	s_add_u32 m0, s14, 0x6400
	s_nop 0
	global_load_lds_dwordx4 v[78:79], off offset:1024
	s_add_u32 m0, s14, 0x7400
	s_nop 0
	global_load_lds_dwordx4 v[82:83], off offset:1024
	v_mfma_f32_32x32x16_bf16 v[34:49], v[94:97], v[102:105], v[34:49]
	v_mfma_f32_32x32x16_bf16 v[50:65], v[94:97], v[106:109], v[50:65]
	v_mfma_f32_32x32x16_bf16 v[2:17], v[98:101], v[102:105], v[2:17]
	v_mfma_f32_32x32x16_bf16 v[18:33], v[98:101], v[106:109], v[18:33]
	s_waitcnt vmcnt(8)
	s_barrier
	ds_read_b128 v[94:97], v86 offset:34816
	ds_read_b128 v[98:101], v86 offset:38912
	ds_read_b128 v[102:105], v90 offset:34816
	ds_read_b128 v[106:109], v90 offset:38912
	v_mfma_f32_32x32x16_bf16 v[34:49], v[110:113], v[118:121], v[34:49]
	v_mfma_f32_32x32x16_bf16 v[50:65], v[110:113], v[122:125], v[50:65]
	v_mfma_f32_32x32x16_bf16 v[2:17], v[114:117], v[118:121], v[2:17]
	v_mfma_f32_32x32x16_bf16 v[18:33], v[114:117], v[122:125], v[18:33]
	ds_read_b128 v[110:113], v87 offset:34816
	ds_read_b128 v[114:117], v87 offset:38912
	ds_read_b128 v[118:121], v91 offset:34816
	ds_read_b128 v[122:125], v91 offset:38912
	v_mfma_f32_32x32x16_bf16 v[34:49], v[126:129], v[134:137], v[34:49]
	v_mfma_f32_32x32x16_bf16 v[50:65], v[126:129], v[138:141], v[50:65]
	v_mfma_f32_32x32x16_bf16 v[2:17], v[130:133], v[134:137], v[2:17]
	v_mfma_f32_32x32x16_bf16 v[18:33], v[130:133], v[138:141], v[18:33]
	ds_read_b128 v[126:129], v88 offset:34816
	ds_read_b128 v[130:133], v88 offset:38912
	ds_read_b128 v[134:137], v92 offset:34816
	ds_read_b128 v[138:141], v92 offset:38912
	v_mfma_f32_32x32x16_bf16 v[34:49], v[142:145], v[150:153], v[34:49]
	v_mfma_f32_32x32x16_bf16 v[50:65], v[142:145], v[154:157], v[50:65]
	v_mfma_f32_32x32x16_bf16 v[2:17], v[146:149], v[150:153], v[2:17]
	v_mfma_f32_32x32x16_bf16 v[18:33], v[146:149], v[154:157], v[18:33]
	ds_read_b128 v[142:145], v89 offset:34816
	ds_read_b128 v[146:149], v89 offset:38912
	ds_read_b128 v[150:153], v93 offset:34816
	ds_read_b128 v[154:157], v93 offset:38912
	s_waitcnt lgkmcnt(0)
	s_barrier
	s_add_u32 m0, s14, 0x8380
	s_nop 0
	global_load_lds_dwordx4 v[68:69], off offset:1152
	s_add_u32 m0, s14, 0x9380
	s_nop 0
	global_load_lds_dwordx4 v[72:73], off offset:1152
	s_add_u32 m0, s14, 0xa380
	s_nop 0
	global_load_lds_dwordx4 v[76:77], off offset:1152
	s_add_u32 m0, s14, 0xb380
	s_nop 0
	global_load_lds_dwordx4 v[80:81], off offset:1152
	s_add_u32 m0, s14, 0xc380
	s_nop 0
	global_load_lds_dwordx4 v[70:71], off offset:1152
	s_add_u32 m0, s14, 0xd380
	s_nop 0
	global_load_lds_dwordx4 v[74:75], off offset:1152
	s_add_u32 m0, s14, 0xe380
	s_nop 0
	global_load_lds_dwordx4 v[78:79], off offset:1152
	s_add_u32 m0, s14, 0xf380
	s_nop 0
	global_load_lds_dwordx4 v[82:83], off offset:1152
	v_mfma_f32_32x32x16_bf16 v[34:49], v[94:97], v[102:105], v[34:49]
	v_mfma_f32_32x32x16_bf16 v[50:65], v[94:97], v[106:109], v[50:65]
	v_mfma_f32_32x32x16_bf16 v[2:17], v[98:101], v[102:105], v[2:17]
	v_mfma_f32_32x32x16_bf16 v[18:33], v[98:101], v[106:109], v[18:33]
	s_waitcnt vmcnt(8)
	s_barrier
	ds_read_b128 v[94:97], v86 offset:2048
	ds_read_b128 v[98:101], v86 offset:6144
	ds_read_b128 v[102:105], v90 offset:2048
	ds_read_b128 v[106:109], v90 offset:6144
	v_mfma_f32_32x32x16_bf16 v[34:49], v[110:113], v[118:121], v[34:49]
	v_mfma_f32_32x32x16_bf16 v[50:65], v[110:113], v[122:125], v[50:65]
	v_mfma_f32_32x32x16_bf16 v[2:17], v[114:117], v[118:121], v[2:17]
	v_mfma_f32_32x32x16_bf16 v[18:33], v[114:117], v[122:125], v[18:33]
	ds_read_b128 v[110:113], v87 offset:2048
	ds_read_b128 v[114:117], v87 offset:6144
	ds_read_b128 v[118:121], v91 offset:2048
	ds_read_b128 v[122:125], v91 offset:6144
	v_mfma_f32_32x32x16_bf16 v[34:49], v[126:129], v[134:137], v[34:49]
	v_mfma_f32_32x32x16_bf16 v[50:65], v[126:129], v[138:141], v[50:65]
	v_mfma_f32_32x32x16_bf16 v[2:17], v[130:133], v[134:137], v[2:17]
	v_mfma_f32_32x32x16_bf16 v[18:33], v[130:133], v[138:141], v[18:33]
	ds_read_b128 v[126:129], v88 offset:2048
	ds_read_b128 v[130:133], v88 offset:6144
	ds_read_b128 v[134:137], v92 offset:2048
	ds_read_b128 v[138:141], v92 offset:6144
	v_mfma_f32_32x32x16_bf16 v[34:49], v[142:145], v[150:153], v[34:49]
	v_mfma_f32_32x32x16_bf16 v[50:65], v[142:145], v[154:157], v[50:65]
	v_mfma_f32_32x32x16_bf16 v[2:17], v[146:149], v[150:153], v[2:17]
	v_mfma_f32_32x32x16_bf16 v[18:33], v[146:149], v[154:157], v[18:33]
	ds_read_b128 v[142:145], v89 offset:2048
	ds_read_b128 v[146:149], v89 offset:6144
	ds_read_b128 v[150:153], v93 offset:2048
	ds_read_b128 v[154:157], v93 offset:6144
	s_waitcnt lgkmcnt(0)
	s_barrier
	s_add_u32 m0, s14, 0x300
	s_nop 0
	global_load_lds_dwordx4 v[68:69], off offset:1280
	s_add_u32 m0, s14, 0x1300
	s_nop 0
	global_load_lds_dwordx4 v[72:73], off offset:1280
	s_add_u32 m0, s14, 0x2300
	s_nop 0
	global_load_lds_dwordx4 v[76:77], off offset:1280
	s_add_u32 m0, s14, 0x3300
	s_nop 0
	global_load_lds_dwordx4 v[80:81], off offset:1280
	s_add_u32 m0, s14, 0x4300
	s_nop 0
	global_load_lds_dwordx4 v[70:71], off offset:1280
	s_add_u32 m0, s14, 0x5300
	s_nop 0
	global_load_lds_dwordx4 v[74:75], off offset:1280
	s_add_u32 m0, s14, 0x6300
	s_nop 0
	global_load_lds_dwordx4 v[78:79], off offset:1280
	s_add_u32 m0, s14, 0x7300
	s_nop 0
	global_load_lds_dwordx4 v[82:83], off offset:1280
	v_mfma_f32_32x32x16_bf16 v[34:49], v[94:97], v[102:105], v[34:49]
	v_mfma_f32_32x32x16_bf16 v[50:65], v[94:97], v[106:109], v[50:65]
	v_mfma_f32_32x32x16_bf16 v[2:17], v[98:101], v[102:105], v[2:17]
	v_mfma_f32_32x32x16_bf16 v[18:33], v[98:101], v[106:109], v[18:33]
	s_waitcnt vmcnt(8)
	s_barrier
	ds_read_b128 v[94:97], v86 offset:34816
	ds_read_b128 v[98:101], v86 offset:38912
	ds_read_b128 v[102:105], v90 offset:34816
	ds_read_b128 v[106:109], v90 offset:38912
	v_mfma_f32_32x32x16_bf16 v[34:49], v[110:113], v[118:121], v[34:49]
	v_mfma_f32_32x32x16_bf16 v[50:65], v[110:113], v[122:125], v[50:65]
	v_mfma_f32_32x32x16_bf16 v[2:17], v[114:117], v[118:121], v[2:17]
	v_mfma_f32_32x32x16_bf16 v[18:33], v[114:117], v[122:125], v[18:33]
	ds_read_b128 v[110:113], v87 offset:34816
	ds_read_b128 v[114:117], v87 offset:38912
	ds_read_b128 v[118:121], v91 offset:34816
	ds_read_b128 v[122:125], v91 offset:38912
	v_mfma_f32_32x32x16_bf16 v[34:49], v[126:129], v[134:137], v[34:49]
	v_mfma_f32_32x32x16_bf16 v[50:65], v[126:129], v[138:141], v[50:65]
	v_mfma_f32_32x32x16_bf16 v[2:17], v[130:133], v[134:137], v[2:17]
	v_mfma_f32_32x32x16_bf16 v[18:33], v[130:133], v[138:141], v[18:33]
	ds_read_b128 v[126:129], v88 offset:34816
	ds_read_b128 v[130:133], v88 offset:38912
	ds_read_b128 v[134:137], v92 offset:34816
	ds_read_b128 v[138:141], v92 offset:38912
	v_mfma_f32_32x32x16_bf16 v[34:49], v[142:145], v[150:153], v[34:49]
	v_mfma_f32_32x32x16_bf16 v[50:65], v[142:145], v[154:157], v[50:65]
	v_mfma_f32_32x32x16_bf16 v[2:17], v[146:149], v[150:153], v[2:17]
	v_mfma_f32_32x32x16_bf16 v[18:33], v[146:149], v[154:157], v[18:33]
	ds_read_b128 v[142:145], v89 offset:34816
	ds_read_b128 v[146:149], v89 offset:38912
	ds_read_b128 v[150:153], v93 offset:34816
	ds_read_b128 v[154:157], v93 offset:38912
	s_waitcnt lgkmcnt(0)
	s_barrier
	s_add_u32 m0, s14, 0x8280
	s_nop 0
	global_load_lds_dwordx4 v[68:69], off offset:1408
	s_add_u32 m0, s14, 0x9280
	s_nop 0
	global_load_lds_dwordx4 v[72:73], off offset:1408
	s_add_u32 m0, s14, 0xa280
	s_nop 0
	global_load_lds_dwordx4 v[76:77], off offset:1408
	s_add_u32 m0, s14, 0xb280
	s_nop 0
	global_load_lds_dwordx4 v[80:81], off offset:1408
	s_add_u32 m0, s14, 0xc280
	s_nop 0
	global_load_lds_dwordx4 v[70:71], off offset:1408
	s_add_u32 m0, s14, 0xd280
	s_nop 0
	global_load_lds_dwordx4 v[74:75], off offset:1408
	s_add_u32 m0, s14, 0xe280
	s_nop 0
	global_load_lds_dwordx4 v[78:79], off offset:1408
	s_add_u32 m0, s14, 0xf280
	s_nop 0
	global_load_lds_dwordx4 v[82:83], off offset:1408
	v_mfma_f32_32x32x16_bf16 v[34:49], v[94:97], v[102:105], v[34:49]
	v_mfma_f32_32x32x16_bf16 v[50:65], v[94:97], v[106:109], v[50:65]
	v_mfma_f32_32x32x16_bf16 v[2:17], v[98:101], v[102:105], v[2:17]
	v_mfma_f32_32x32x16_bf16 v[18:33], v[98:101], v[106:109], v[18:33]
	s_waitcnt vmcnt(8)
	s_barrier
	ds_read_b128 v[94:97], v86 offset:2048
	ds_read_b128 v[98:101], v86 offset:6144
	ds_read_b128 v[102:105], v90 offset:2048
	ds_read_b128 v[106:109], v90 offset:6144
	v_mfma_f32_32x32x16_bf16 v[34:49], v[110:113], v[118:121], v[34:49]
	v_mfma_f32_32x32x16_bf16 v[50:65], v[110:113], v[122:125], v[50:65]
	v_mfma_f32_32x32x16_bf16 v[2:17], v[114:117], v[118:121], v[2:17]
	v_mfma_f32_32x32x16_bf16 v[18:33], v[114:117], v[122:125], v[18:33]
	ds_read_b128 v[110:113], v87 offset:2048
	ds_read_b128 v[114:117], v87 offset:6144
	ds_read_b128 v[118:121], v91 offset:2048
	ds_read_b128 v[122:125], v91 offset:6144
	v_mfma_f32_32x32x16_bf16 v[34:49], v[126:129], v[134:137], v[34:49]
	v_mfma_f32_32x32x16_bf16 v[50:65], v[126:129], v[138:141], v[50:65]
	v_mfma_f32_32x32x16_bf16 v[2:17], v[130:133], v[134:137], v[2:17]
	v_mfma_f32_32x32x16_bf16 v[18:33], v[130:133], v[138:141], v[18:33]
	ds_read_b128 v[126:129], v88 offset:2048
	ds_read_b128 v[130:133], v88 offset:6144
	ds_read_b128 v[134:137], v92 offset:2048
	ds_read_b128 v[138:141], v92 offset:6144
	v_mfma_f32_32x32x16_bf16 v[34:49], v[142:145], v[150:153], v[34:49]
	v_mfma_f32_32x32x16_bf16 v[50:65], v[142:145], v[154:157], v[50:65]
	v_mfma_f32_32x32x16_bf16 v[2:17], v[146:149], v[150:153], v[2:17]
	v_mfma_f32_32x32x16_bf16 v[18:33], v[146:149], v[154:157], v[18:33]
	ds_read_b128 v[142:145], v89 offset:2048
	ds_read_b128 v[146:149], v89 offset:6144
	ds_read_b128 v[150:153], v93 offset:2048
	ds_read_b128 v[154:157], v93 offset:6144
	s_waitcnt lgkmcnt(0)
	s_barrier
	s_add_u32 m0, s14, 0x200
	s_nop 0
	global_load_lds_dwordx4 v[68:69], off offset:1536
	s_add_u32 m0, s14, 0x1200
	s_nop 0
	global_load_lds_dwordx4 v[72:73], off offset:1536
	s_add_u32 m0, s14, 0x2200
	s_nop 0
	global_load_lds_dwordx4 v[76:77], off offset:1536
	s_add_u32 m0, s14, 0x3200
	s_nop 0
	global_load_lds_dwordx4 v[80:81], off offset:1536
	s_add_u32 m0, s14, 0x4200
	s_nop 0
	global_load_lds_dwordx4 v[70:71], off offset:1536
	s_add_u32 m0, s14, 0x5200
	s_nop 0
	global_load_lds_dwordx4 v[74:75], off offset:1536
	s_add_u32 m0, s14, 0x6200
	s_nop 0
	global_load_lds_dwordx4 v[78:79], off offset:1536
	s_add_u32 m0, s14, 0x7200
	s_nop 0
	global_load_lds_dwordx4 v[82:83], off offset:1536
	v_mfma_f32_32x32x16_bf16 v[34:49], v[94:97], v[102:105], v[34:49]
	v_mfma_f32_32x32x16_bf16 v[50:65], v[94:97], v[106:109], v[50:65]
	v_mfma_f32_32x32x16_bf16 v[2:17], v[98:101], v[102:105], v[2:17]
	v_mfma_f32_32x32x16_bf16 v[18:33], v[98:101], v[106:109], v[18:33]
	s_waitcnt vmcnt(8)
	s_barrier
	ds_read_b128 v[94:97], v86 offset:34816
	ds_read_b128 v[98:101], v86 offset:38912
	ds_read_b128 v[102:105], v90 offset:34816
	ds_read_b128 v[106:109], v90 offset:38912
	v_mfma_f32_32x32x16_bf16 v[34:49], v[110:113], v[118:121], v[34:49]
	v_mfma_f32_32x32x16_bf16 v[50:65], v[110:113], v[122:125], v[50:65]
	v_mfma_f32_32x32x16_bf16 v[2:17], v[114:117], v[118:121], v[2:17]
	v_mfma_f32_32x32x16_bf16 v[18:33], v[114:117], v[122:125], v[18:33]
	ds_read_b128 v[110:113], v87 offset:34816
	ds_read_b128 v[114:117], v87 offset:38912
	ds_read_b128 v[118:121], v91 offset:34816
	ds_read_b128 v[122:125], v91 offset:38912
	v_mfma_f32_32x32x16_bf16 v[34:49], v[126:129], v[134:137], v[34:49]
	v_mfma_f32_32x32x16_bf16 v[50:65], v[126:129], v[138:141], v[50:65]
	v_mfma_f32_32x32x16_bf16 v[2:17], v[130:133], v[134:137], v[2:17]
	v_mfma_f32_32x32x16_bf16 v[18:33], v[130:133], v[138:141], v[18:33]
	ds_read_b128 v[126:129], v88 offset:34816
	ds_read_b128 v[130:133], v88 offset:38912
	ds_read_b128 v[134:137], v92 offset:34816
	ds_read_b128 v[138:141], v92 offset:38912
	v_mfma_f32_32x32x16_bf16 v[34:49], v[142:145], v[150:153], v[34:49]
	v_mfma_f32_32x32x16_bf16 v[50:65], v[142:145], v[154:157], v[50:65]
	v_mfma_f32_32x32x16_bf16 v[2:17], v[146:149], v[150:153], v[2:17]
	v_mfma_f32_32x32x16_bf16 v[18:33], v[146:149], v[154:157], v[18:33]
	ds_read_b128 v[142:145], v89 offset:34816
	ds_read_b128 v[146:149], v89 offset:38912
	ds_read_b128 v[150:153], v93 offset:34816
	ds_read_b128 v[154:157], v93 offset:38912
	s_waitcnt lgkmcnt(0)
	s_barrier
	s_add_u32 m0, s14, 0x8180
	s_nop 0
	global_load_lds_dwordx4 v[68:69], off offset:1664
	s_add_u32 m0, s14, 0x9180
	s_nop 0
	global_load_lds_dwordx4 v[72:73], off offset:1664
	s_add_u32 m0, s14, 0xa180
	s_nop 0
	global_load_lds_dwordx4 v[76:77], off offset:1664
	s_add_u32 m0, s14, 0xb180
	s_nop 0
	global_load_lds_dwordx4 v[80:81], off offset:1664
	s_add_u32 m0, s14, 0xc180
	s_nop 0
	global_load_lds_dwordx4 v[70:71], off offset:1664
	s_add_u32 m0, s14, 0xd180
	s_nop 0
	global_load_lds_dwordx4 v[74:75], off offset:1664
	s_add_u32 m0, s14, 0xe180
	s_nop 0
	global_load_lds_dwordx4 v[78:79], off offset:1664
	s_add_u32 m0, s14, 0xf180
	s_nop 0
	global_load_lds_dwordx4 v[82:83], off offset:1664
	v_mfma_f32_32x32x16_bf16 v[34:49], v[94:97], v[102:105], v[34:49]
	v_mfma_f32_32x32x16_bf16 v[50:65], v[94:97], v[106:109], v[50:65]
	v_mfma_f32_32x32x16_bf16 v[2:17], v[98:101], v[102:105], v[2:17]
	v_mfma_f32_32x32x16_bf16 v[18:33], v[98:101], v[106:109], v[18:33]
	s_waitcnt vmcnt(8)
	s_barrier
	ds_read_b128 v[94:97], v86 offset:2048
	ds_read_b128 v[98:101], v86 offset:6144
	ds_read_b128 v[102:105], v90 offset:2048
	ds_read_b128 v[106:109], v90 offset:6144
	v_mfma_f32_32x32x16_bf16 v[34:49], v[110:113], v[118:121], v[34:49]
	v_mfma_f32_32x32x16_bf16 v[50:65], v[110:113], v[122:125], v[50:65]
	v_mfma_f32_32x32x16_bf16 v[2:17], v[114:117], v[118:121], v[2:17]
	v_mfma_f32_32x32x16_bf16 v[18:33], v[114:117], v[122:125], v[18:33]
	ds_read_b128 v[110:113], v87 offset:2048
	ds_read_b128 v[114:117], v87 offset:6144
	ds_read_b128 v[118:121], v91 offset:2048
	ds_read_b128 v[122:125], v91 offset:6144
	v_mfma_f32_32x32x16_bf16 v[34:49], v[126:129], v[134:137], v[34:49]
	v_mfma_f32_32x32x16_bf16 v[50:65], v[126:129], v[138:141], v[50:65]
	v_mfma_f32_32x32x16_bf16 v[2:17], v[130:133], v[134:137], v[2:17]
	v_mfma_f32_32x32x16_bf16 v[18:33], v[130:133], v[138:141], v[18:33]
	ds_read_b128 v[126:129], v88 offset:2048
	ds_read_b128 v[130:133], v88 offset:6144
	ds_read_b128 v[134:137], v92 offset:2048
	ds_read_b128 v[138:141], v92 offset:6144
	v_mfma_f32_32x32x16_bf16 v[34:49], v[142:145], v[150:153], v[34:49]
	v_mfma_f32_32x32x16_bf16 v[50:65], v[142:145], v[154:157], v[50:65]
	v_mfma_f32_32x32x16_bf16 v[2:17], v[146:149], v[150:153], v[2:17]
	v_mfma_f32_32x32x16_bf16 v[18:33], v[146:149], v[154:157], v[18:33]
	ds_read_b128 v[142:145], v89 offset:2048
	ds_read_b128 v[146:149], v89 offset:6144
	ds_read_b128 v[150:153], v93 offset:2048
	ds_read_b128 v[154:157], v93 offset:6144
	s_waitcnt lgkmcnt(0)
	s_barrier
	s_add_u32 m0, s14, 0x100
	s_nop 0
	global_load_lds_dwordx4 v[68:69], off offset:1792
	s_add_u32 m0, s14, 0x1100
	s_nop 0
	global_load_lds_dwordx4 v[72:73], off offset:1792
	s_add_u32 m0, s14, 0x2100
	s_nop 0
	global_load_lds_dwordx4 v[76:77], off offset:1792
	s_add_u32 m0, s14, 0x3100
	s_nop 0
	global_load_lds_dwordx4 v[80:81], off offset:1792
	s_add_u32 m0, s14, 0x4100
	s_nop 0
	global_load_lds_dwordx4 v[70:71], off offset:1792
	s_add_u32 m0, s14, 0x5100
	s_nop 0
	global_load_lds_dwordx4 v[74:75], off offset:1792
	s_add_u32 m0, s14, 0x6100
	s_nop 0
	global_load_lds_dwordx4 v[78:79], off offset:1792
	s_add_u32 m0, s14, 0x7100
	s_nop 0
	global_load_lds_dwordx4 v[82:83], off offset:1792
	v_mfma_f32_32x32x16_bf16 v[34:49], v[94:97], v[102:105], v[34:49]
	v_mfma_f32_32x32x16_bf16 v[50:65], v[94:97], v[106:109], v[50:65]
	v_mfma_f32_32x32x16_bf16 v[2:17], v[98:101], v[102:105], v[2:17]
	v_mfma_f32_32x32x16_bf16 v[18:33], v[98:101], v[106:109], v[18:33]
	s_waitcnt vmcnt(8)
	s_barrier
	ds_read_b128 v[94:97], v86 offset:34816
	ds_read_b128 v[98:101], v86 offset:38912
	ds_read_b128 v[102:105], v90 offset:34816
	ds_read_b128 v[106:109], v90 offset:38912
	v_mfma_f32_32x32x16_bf16 v[34:49], v[110:113], v[118:121], v[34:49]
	v_mfma_f32_32x32x16_bf16 v[50:65], v[110:113], v[122:125], v[50:65]
	v_mfma_f32_32x32x16_bf16 v[2:17], v[114:117], v[118:121], v[2:17]
	v_mfma_f32_32x32x16_bf16 v[18:33], v[114:117], v[122:125], v[18:33]
	ds_read_b128 v[110:113], v87 offset:34816
	ds_read_b128 v[114:117], v87 offset:38912
	ds_read_b128 v[118:121], v91 offset:34816
	ds_read_b128 v[122:125], v91 offset:38912
	v_mfma_f32_32x32x16_bf16 v[34:49], v[126:129], v[134:137], v[34:49]
	v_mfma_f32_32x32x16_bf16 v[50:65], v[126:129], v[138:141], v[50:65]
	v_mfma_f32_32x32x16_bf16 v[2:17], v[130:133], v[134:137], v[2:17]
	v_mfma_f32_32x32x16_bf16 v[18:33], v[130:133], v[138:141], v[18:33]
	ds_read_b128 v[126:129], v88 offset:34816
	ds_read_b128 v[130:133], v88 offset:38912
	ds_read_b128 v[134:137], v92 offset:34816
	ds_read_b128 v[138:141], v92 offset:38912
	v_mfma_f32_32x32x16_bf16 v[34:49], v[142:145], v[150:153], v[34:49]
	v_mfma_f32_32x32x16_bf16 v[50:65], v[142:145], v[154:157], v[50:65]
	v_mfma_f32_32x32x16_bf16 v[2:17], v[146:149], v[150:153], v[2:17]
	v_mfma_f32_32x32x16_bf16 v[18:33], v[146:149], v[154:157], v[18:33]
	ds_read_b128 v[142:145], v89 offset:34816
	ds_read_b128 v[146:149], v89 offset:38912
	ds_read_b128 v[150:153], v93 offset:34816
	ds_read_b128 v[154:157], v93 offset:38912
	s_waitcnt lgkmcnt(0)
	s_barrier
	s_add_u32 m0, s14, 0x8080
	s_nop 0
	global_load_lds_dwordx4 v[68:69], off offset:1920
	s_add_u32 m0, s14, 0x9080
	s_nop 0
	global_load_lds_dwordx4 v[72:73], off offset:1920
	s_add_u32 m0, s14, 0xa080
	s_nop 0
	global_load_lds_dwordx4 v[76:77], off offset:1920
	s_add_u32 m0, s14, 0xb080
	s_nop 0
	global_load_lds_dwordx4 v[80:81], off offset:1920
	s_add_u32 m0, s14, 0xc080
	s_nop 0
	global_load_lds_dwordx4 v[70:71], off offset:1920
	s_add_u32 m0, s14, 0xd080
	s_nop 0
	global_load_lds_dwordx4 v[74:75], off offset:1920
	s_add_u32 m0, s14, 0xe080
	s_nop 0
	global_load_lds_dwordx4 v[78:79], off offset:1920
	s_add_u32 m0, s14, 0xf080
	s_nop 0
	global_load_lds_dwordx4 v[82:83], off offset:1920
	v_mfma_f32_32x32x16_bf16 v[34:49], v[94:97], v[102:105], v[34:49]
	v_mfma_f32_32x32x16_bf16 v[50:65], v[94:97], v[106:109], v[50:65]
	v_mfma_f32_32x32x16_bf16 v[2:17], v[98:101], v[102:105], v[2:17]
	v_mfma_f32_32x32x16_bf16 v[18:33], v[98:101], v[106:109], v[18:33]
	s_waitcnt vmcnt(8)
	s_barrier
	ds_read_b128 v[94:97], v86 offset:2048
	ds_read_b128 v[98:101], v86 offset:6144
	ds_read_b128 v[102:105], v90 offset:2048
	ds_read_b128 v[106:109], v90 offset:6144
	v_mfma_f32_32x32x16_bf16 v[34:49], v[110:113], v[118:121], v[34:49]
	v_mfma_f32_32x32x16_bf16 v[50:65], v[110:113], v[122:125], v[50:65]
	v_mfma_f32_32x32x16_bf16 v[2:17], v[114:117], v[118:121], v[2:17]
	v_mfma_f32_32x32x16_bf16 v[18:33], v[114:117], v[122:125], v[18:33]
	ds_read_b128 v[110:113], v87 offset:2048
	ds_read_b128 v[114:117], v87 offset:6144
	ds_read_b128 v[118:121], v91 offset:2048
	ds_read_b128 v[122:125], v91 offset:6144
	v_mfma_f32_32x32x16_bf16 v[34:49], v[126:129], v[134:137], v[34:49]
	v_mfma_f32_32x32x16_bf16 v[50:65], v[126:129], v[138:141], v[50:65]
	v_mfma_f32_32x32x16_bf16 v[2:17], v[130:133], v[134:137], v[2:17]
	v_mfma_f32_32x32x16_bf16 v[18:33], v[130:133], v[138:141], v[18:33]
	ds_read_b128 v[126:129], v88 offset:2048
	ds_read_b128 v[130:133], v88 offset:6144
	ds_read_b128 v[134:137], v92 offset:2048
	ds_read_b128 v[138:141], v92 offset:6144
	v_mfma_f32_32x32x16_bf16 v[34:49], v[142:145], v[150:153], v[34:49]
	v_mfma_f32_32x32x16_bf16 v[50:65], v[142:145], v[154:157], v[50:65]
	v_mfma_f32_32x32x16_bf16 v[2:17], v[146:149], v[150:153], v[2:17]
	v_mfma_f32_32x32x16_bf16 v[18:33], v[146:149], v[154:157], v[18:33]
	ds_read_b128 v[142:145], v89 offset:2048
	ds_read_b128 v[146:149], v89 offset:6144
	ds_read_b128 v[150:153], v93 offset:2048
	ds_read_b128 v[154:157], v93 offset:6144
	s_waitcnt lgkmcnt(0)
	v_mfma_f32_32x32x16_bf16 v[34:49], v[94:97], v[102:105], v[34:49]
	v_mfma_f32_32x32x16_bf16 v[50:65], v[94:97], v[106:109], v[50:65]
	v_mfma_f32_32x32x16_bf16 v[2:17], v[98:101], v[102:105], v[2:17]
	v_mfma_f32_32x32x16_bf16 v[18:33], v[98:101], v[106:109], v[18:33]
	s_waitcnt vmcnt(0)
	s_barrier
	ds_read_b128 v[94:97], v86 offset:34816
	ds_read_b128 v[98:101], v86 offset:38912
	ds_read_b128 v[102:105], v90 offset:34816
	ds_read_b128 v[106:109], v90 offset:38912
	v_mfma_f32_32x32x16_bf16 v[34:49], v[110:113], v[118:121], v[34:49]
	v_mfma_f32_32x32x16_bf16 v[50:65], v[110:113], v[122:125], v[50:65]
	v_mfma_f32_32x32x16_bf16 v[2:17], v[114:117], v[118:121], v[2:17]
	v_mfma_f32_32x32x16_bf16 v[18:33], v[114:117], v[122:125], v[18:33]
	ds_read_b128 v[110:113], v87 offset:34816
	ds_read_b128 v[114:117], v87 offset:38912
	ds_read_b128 v[118:121], v91 offset:34816
	ds_read_b128 v[122:125], v91 offset:38912
	v_mfma_f32_32x32x16_bf16 v[34:49], v[126:129], v[134:137], v[34:49]
	v_mfma_f32_32x32x16_bf16 v[50:65], v[126:129], v[138:141], v[50:65]
	v_mfma_f32_32x32x16_bf16 v[2:17], v[130:133], v[134:137], v[2:17]
	v_mfma_f32_32x32x16_bf16 v[18:33], v[130:133], v[138:141], v[18:33]
	ds_read_b128 v[126:129], v88 offset:34816
	ds_read_b128 v[130:133], v88 offset:38912
	ds_read_b128 v[134:137], v92 offset:34816
	ds_read_b128 v[138:141], v92 offset:38912
	v_mfma_f32_32x32x16_bf16 v[34:49], v[142:145], v[150:153], v[34:49]
	v_mfma_f32_32x32x16_bf16 v[50:65], v[142:145], v[154:157], v[50:65]
	v_mfma_f32_32x32x16_bf16 v[2:17], v[146:149], v[150:153], v[2:17]
	v_mfma_f32_32x32x16_bf16 v[18:33], v[146:149], v[154:157], v[18:33]
	ds_read_b128 v[142:145], v89 offset:34816
	ds_read_b128 v[146:149], v89 offset:38912
	ds_read_b128 v[150:153], v93 offset:34816
	ds_read_b128 v[154:157], v93 offset:38912
	s_waitcnt lgkmcnt(0)
	v_mfma_f32_32x32x16_bf16 v[34:49], v[94:97], v[102:105], v[34:49]
	v_mfma_f32_32x32x16_bf16 v[50:65], v[94:97], v[106:109], v[50:65]
	v_mfma_f32_32x32x16_bf16 v[2:17], v[98:101], v[102:105], v[2:17]
	v_mfma_f32_32x32x16_bf16 v[18:33], v[98:101], v[106:109], v[18:33]
	v_mfma_f32_32x32x16_bf16 v[34:49], v[110:113], v[118:121], v[34:49]
	v_mfma_f32_32x32x16_bf16 v[50:65], v[110:113], v[122:125], v[50:65]
	v_mfma_f32_32x32x16_bf16 v[2:17], v[114:117], v[118:121], v[2:17]
	v_mfma_f32_32x32x16_bf16 v[18:33], v[114:117], v[122:125], v[18:33]
	v_mfma_f32_32x32x16_bf16 v[34:49], v[126:129], v[134:137], v[34:49]
	v_mfma_f32_32x32x16_bf16 v[50:65], v[126:129], v[138:141], v[50:65]
	v_mfma_f32_32x32x16_bf16 v[2:17], v[130:133], v[134:137], v[2:17]
	v_mfma_f32_32x32x16_bf16 v[18:33], v[130:133], v[138:141], v[18:33]
	v_mfma_f32_32x32x16_bf16 v[34:49], v[142:145], v[150:153], v[34:49]
	v_mfma_f32_32x32x16_bf16 v[50:65], v[142:145], v[154:157], v[50:65]
	v_mfma_f32_32x32x16_bf16 v[2:17], v[146:149], v[150:153], v[2:17]
	v_mfma_f32_32x32x16_bf16 v[18:33], v[146:149], v[154:157], v[18:33]
	v_mov_b32_e32 v66, v178
	s_waitcnt lgkmcnt(0)
	s_barrier
	s_nop 0
	v_lshrrev_b32_e32 v0, 1, v66
	v_and_b32_e32 v0, 0xfffffc0, v0
	v_lshrrev_b32_e32 v67, 3, v66
	v_and_or_b32 v0, v67, 4, v0
	v_and_b32_e32 v67, 0x5f, v66
	v_mul_lo_u32 v0, v0, s83
	v_lshl_add_u32 v0, v67, 2, v0
	s_nop 0
	s_nop 11
	ds_write2_b32 v0, v34, v50 offset1:32
	ds_write2_b32 v0, v35, v51 offset0:132 offset1:164
	s_nop 0
	v_add_u32_e32 v34, 0x400, v0
	ds_write2_b32 v34, v36, v52 offset0:8 offset1:40
	ds_write2_b32 v34, v37, v53 offset0:140 offset1:172
	v_add_u32_e32 v34, 0x1000, v0
	ds_write2_b32 v34, v38, v54 offset0:32 offset1:64
	ds_write2_b32 v34, v39, v55 offset0:164 offset1:196
	v_add_u32_e32 v34, 0x1400, v0
	ds_write2_b32 v34, v40, v56 offset0:40 offset1:72
	ds_write2_b32 v34, v41, v57 offset0:172 offset1:204
	v_add_u32_e32 v34, 0x2000, v0
	s_nop 0
	ds_write2_b32 v34, v42, v58 offset0:64 offset1:96
	ds_write2_b32 v34, v43, v59 offset0:196 offset1:228
	v_add_u32_e32 v34, 0x2400, v0
	ds_write2_b32 v34, v44, v60 offset0:72 offset1:104
	ds_write2_b32 v34, v45, v61 offset0:204 offset1:236
	v_add_u32_e32 v34, 0x3000, v0
	ds_write2_b32 v34, v46, v62 offset0:96 offset1:128
	v_add_u32_e32 v34, 0x3200, v0
	ds_write2_b32 v34, v47, v63 offset0:100 offset1:132
	s_nop 0
	v_add_u32_e32 v34, 0x3400, v0
	ds_write2_b32 v34, v48, v64 offset0:104 offset1:136
	v_add_u32_e32 v34, 0x3600, v0
	ds_write2_b32 v34, v49, v65 offset0:108 offset1:140
	v_add_u32_e32 v34, 0x4000, v0
	s_nop 0
	s_nop 11
	ds_write2_b32 v34, v2, v18 offset0:128 offset1:160
	v_add_u32_e32 v2, 0x4400, v0
	ds_write2_b32 v2, v3, v19 offset0:4 offset1:36
	ds_write2_b32 v2, v4, v20 offset0:136 offset1:168
	v_add_u32_e32 v2, 0x4800, v0
	ds_write2_b32 v2, v5, v21 offset0:12 offset1:44
	v_add_u32_e32 v2, 0x5000, v0
	ds_write2_b32 v2, v6, v22 offset0:160 offset1:192
	v_add_u32_e32 v2, 0x5400, v0
	ds_write2_b32 v2, v7, v23 offset0:36 offset1:68
	ds_write2_b32 v2, v8, v24 offset0:168 offset1:200
	v_add_u32_e32 v2, 0x5800, v0
	ds_write2_b32 v2, v9, v25 offset0:44 offset1:76
	v_add_u32_e32 v2, 0x6000, v0
	ds_write2_b32 v2, v10, v26 offset0:192 offset1:224
	v_add_u32_e32 v2, 0x6400, v0
	ds_write2_b32 v2, v11, v27 offset0:68 offset1:100
	ds_write2_b32 v2, v12, v28 offset0:200 offset1:232
	v_add_u32_e32 v2, 0x6800, v0
	ds_write2_b32 v2, v13, v29 offset0:76 offset1:108
	v_add_u32_e32 v2, 0x7200, v0
	ds_write2_b32 v2, v14, v30 offset0:96 offset1:128
	v_add_u32_e32 v2, 0x7400, v0
	ds_write2_b32 v2, v15, v31 offset0:100 offset1:132
	v_add_u32_e32 v2, 0x7600, v0
	v_add_u32_e32 v0, 0x7800, v0
	ds_write2_b32 v0, v17, v33 offset0:108 offset1:140
	v_lshlrev_b32_e32 v0, 3, v66
	v_and_b32_e32 v0, 0x78, v0
	v_or_b32_e32 v12, s0, v0
	v_ashrrev_i32_e32 v13, 31, v12
	v_readlane_b32 s0, v249, 13
	ds_write2_b32 v2, v16, v32 offset0:104 offset1:136
	v_lshlrev_b64 v[2:3], 2, v[12:13]
	v_readlane_b32 s1, v249, 14
	v_lshlrev_b32_e32 v10, 2, v0
	v_lshl_add_u64 v[16:17], s[90:91], 0, v[2:3]
	v_lshl_add_u64 v[14:15], s[0:1], 0, v[2:3]
	s_waitcnt lgkmcnt(0)
	s_barrier
	s_branch .LBB0_912
